# GLU epilogue loads batched; GLA norm gains hoisted out of the chunk loop; merge gate epilogue: log2e folded into rstd and bias, packed adds
# speedup vs baseline: 1.0135x; 1.0098x over previous
.LBB0_730:
	s_lshl_b32 s42, s88, 6
	s_add_i32 s44, s42, 0x8000
	s_lshl_b32 s45, s88, 11
	s_and_b64 s[42:43], s[84:85], exec
	s_cselect_b32 s42, 0, 0x2000000
	v_readlane_b32 s31, v249, 30
	s_cselect_b32 s48, s45, s44
	s_add_u32 s49, s31, s42
	v_readlane_b32 s31, v249, 31
	s_addc_u32 s50, s31, 0
	v_or_b32_e32 v16, v58, v60
	s_movk_i32 s31, 0x90
	v_lshl_add_u32 v17, v34, 1, 0
	v_mul_lo_u32 v16, v16, s31
	v_add_u32_e32 v57, v17, v16
	s_waitcnt vmcnt(3)
	v_cvt_pk_bf16_f32 v16, v9, s0
	ds_write_b16 v57, v16 offset:55440
	v_cvt_pk_bf16_f32 v16, v10, s0
	ds_write_b16 v57, v16 offset:55584
	v_cvt_pk_bf16_f32 v16, v11, s0
	ds_write_b16 v57, v16 offset:55728
	s_waitcnt vmcnt(2)
	v_cvt_pk_bf16_f32 v16, v0, s0
	ds_write_b16 v57, v16 offset:55328
	v_cvt_pk_bf16_f32 v16, v1, s0
	s_ashr_i32 s89, s88, 31
	s_lshl_b32 s42, s90, 7
	ds_write_b16 v57, v16 offset:55472
	v_cvt_pk_bf16_f32 v16, v2, s0
	s_lshl_b64 s[44:45], s[88:89], 9
	s_ashr_i32 s43, s42, 31
	ds_write_b16 v57, v16 offset:55616
	v_cvt_pk_bf16_f32 v16, v3, s0
	s_add_u32 s44, s44, s42
	ds_write_b16 v57, v16 offset:55760
	s_waitcnt vmcnt(1)
	v_cvt_pk_bf16_f32 v16, v4, s0
	s_addc_u32 s45, s45, s43
	ds_write_b16 v57, v16 offset:55360
	v_cvt_pk_bf16_f32 v16, v5, s0
	s_and_b64 s[46:47], s[84:85], exec
	ds_write_b16 v57, v16 offset:55504
	v_cvt_pk_bf16_f32 v16, v6, s0
	s_cselect_b32 s51, 11, 6
	ds_write_b16 v57, v16 offset:55648
	v_cvt_pk_bf16_f32 v16, v7, s0
	s_lshl_b64 s[44:45], s[44:45], s51
	ds_write_b16 v57, v16 offset:55792
	s_waitcnt vmcnt(0)
	v_cvt_pk_bf16_f32 v16, v12, s0
	s_lshl_b64 s[44:45], s[44:45], 1
	ds_write_b16 v57, v16 offset:55392
	v_cvt_pk_bf16_f32 v16, v13, s0
	v_ashrrev_i32_e32 v38, 3, v32
	s_add_u32 s44, s49, s44
	ds_write_b16 v57, v16 offset:55536
	v_cvt_pk_bf16_f32 v16, v14, s0
	v_add_u32_e32 v62, s48, v38
	s_addc_u32 s45, s50, s45
	ds_write_b16 v57, v16 offset:55680
	v_cvt_pk_bf16_f32 v16, v15, s0
	v_ashrrev_i32_e32 v63, 31, v62
	v_readlane_b32 s48, v249, 34
	v_readlane_b32 s52, v249, 28
	v_add_u32_e32 v28, 0x200, v32
	s_and_b64 s[46:47], s[84:85], exec
	v_cvt_pk_bf16_f32 v18, v8, s0
	ds_write_b16 v57, v16 offset:55824
	v_lshlrev_b64 v[16:17], 9, v[62:63]
	v_readlane_b32 s49, v249, 35
	v_readlane_b32 s53, v249, 29
	v_readlane_b32 s54, v249, 36
	v_lshlrev_b32_e32 v26, 4, v32
	v_ashrrev_i32_e32 v46, 3, v28
	s_cselect_b32 s95, 32, 1
	ds_write_b16 v57, v18 offset:55296
	v_and_b32_e32 v37, 7, v32
	v_lshl_add_u64 v[18:19], s[48:49], 0, v[16:17]
	s_lshl_b64 s[40:41], s[40:41], 1
	v_lshl_add_u64 v[16:17], s[52:53], 0, v[16:17]
	v_lshlrev_b64 v[24:25], 6, v[62:63]
	v_readlane_b32 s55, v249, 37
	v_and_b32_e32 v44, 0x70, v26
	v_mov_b32_e32 v45, v177
	v_ashrrev_i32_e32 v39, 31, v38
	v_ashrrev_i32_e32 v47, 31, v46
	v_lshlrev_b32_e32 v40, 3, v37
	v_lshl_add_u64 v[18:19], v[18:19], 0, s[40:41]
	v_mov_b32_e32 v41, v177
	v_lshlrev_b32_e32 v42, 4, v37
	v_mov_b32_e32 v43, v177
	v_lshl_add_u64 v[16:17], v[16:17], 0, s[40:41]
	v_lshl_add_u64 v[24:25], s[54:55], 0, v[24:25]
	v_lshl_add_u64 v[64:65], s[44:45], 0, v[44:45]
	v_lshlrev_b64 v[66:67], s51, v[38:39]
	v_lshlrev_b64 v[68:69], s51, v[46:47]
	v_lshl_add_u64 v[18:19], v[18:19], 0, v[42:43]
	v_lshl_add_u64 v[20:21], v[16:17], 0, v[42:43]
	v_lshl_add_u64 v[24:25], v[24:25], 0, v[40:41]
	v_lshl_add_u64 v[26:27], v[66:67], 1, v[64:65]
	v_lshl_add_u64 v[28:29], v[68:69], 1, v[64:65]
	global_load_dwordx4 v[16:19], v[18:19], off
	s_nop 0
	global_load_dwordx4 v[20:23], v[20:21], off
	s_nop 0
	global_load_dwordx2 v[70:71], v[24:25], off
	s_nop 0
	global_load_dwordx4 v[24:27], v[26:27], off
	s_add_u32 s44, s48, s40
	global_load_dwordx4 v[28:31], v[28:29], off
	s_addc_u32 s45, s49, s41
	s_add_u32 s40, s52, s40
	s_addc_u32 s41, s53, s41
	v_lshl_add_u64 v[74:75], s[40:41], 0, v[42:43]
	s_lshl_b64 s[40:41], s[42:43], 1
	v_readlane_b32 s42, v249, 22
	v_lshlrev_b32_e32 v39, 6, v38
	v_readlane_b32 s46, v250, 24
	v_readlane_b32 s43, v249, 23
	s_add_u32 s40, s42, s40
	v_add3_u32 v104, s46, v39, v40
	v_lshl_add_u64 v[76:77], s[54:55], 0, v[40:41]
	s_addc_u32 s41, s43, s41
	v_lshlrev_b32_e32 v40, 5, v37
	v_mul_lo_u32 v59, v38, s31
	v_readlane_b32 s59, v250, 22
	v_readlane_b32 s60, v250, 23
	v_lshl_add_u64 v[78:79], s[40:41], 0, v[40:41]
	v_bfe_u32 v41, v32, 6, 2
	v_add3_u32 v63, s59, v59, v42
	v_add3_u32 v103, s60, v59, v42
	v_lshl_add_u64 v[72:73], s[44:45], 0, v[42:43]
	v_lshl_or_b32 v42, v41, 4, v34
	v_mul_u32_u24_e32 v39, 0x90, v42
	v_lshlrev_b32_e32 v109, 3, v36
	v_add3_u32 v110, 0, v39, v109
	v_lshl_add_u32 v36, v36, 4, 0
	v_or_b32_e32 v39, v58, v34
	v_mad_u64_u32 v[80:81], s[42:43], v39, s31, v[36:37]
	v_and_b32_e32 v39, 0xffffffc0, v32
	s_add_i32 s42, 0, 0x12000
	v_and_b32_e32 v43, 48, v32
	s_movk_i32 s43, 0x210
	v_add_u32_e32 v105, 0, v44
	v_add3_u32 v44, s42, v39, v43
	v_mul_lo_u32 v39, v38, s43
	v_lshlrev_b32_e32 v38, 6, v37
	v_add3_u32 v81, s42, v39, v38
	v_and_b32_e32 v39, 64, v229
	v_xor_b32_e32 v37, 1, v229
	v_add_u32_e32 v39, 64, v39
	v_cmp_lt_i32_e32 vcc, v37, v39
	v_readlane_b32 s42, v249, 45
	v_readlane_b32 s43, v249, 46
	v_cndmask_b32_e32 v37, v229, v37, vcc
	v_lshlrev_b32_e32 v111, 2, v37
	v_xor_b32_e32 v37, 2, v229
	v_cmp_lt_i32_e32 vcc, v37, v39
	s_movk_i32 s58, 0x240
	v_mad_u32_u24 v40, v33, s31, 0
	v_cndmask_b32_e32 v37, v229, v37, vcc
	v_lshlrev_b32_e32 v112, 2, v37
	v_xor_b32_e32 v37, 4, v229
	v_cmp_lt_i32_e32 vcc, v37, v39
	v_mov_b32_e32 v39, v177
	v_lshl_add_u64 v[82:83], s[42:43], 0, v[38:39]
	global_load_dwordx4 v[160:163], v[82:83], off
	global_load_dwordx4 v[164:167], v[82:83], off offset:16
	global_load_dwordx4 v[168:171], v[82:83], off offset:32
	global_load_dwordx4 v[172:175], v[82:83], off offset:48
	v_mul_lo_u32 v38, v35, s58
	v_or_b32_e32 v33, v38, v33
	v_lshlrev_b32_e32 v33, 1, v33
	v_add_u32_e32 v38, 0x90, v33
	v_add_u32_e32 v118, s59, v38
	v_add_u32_e32 v119, s60, v38
	v_add_u32_e32 v38, 0x120, v33
	v_add_u32_e32 v120, s59, v38
	v_add_u32_e32 v121, s60, v38
	v_add_u32_e32 v38, 0x1b0, v33
	v_add_u32_e32 v122, s59, v38
	v_add_u32_e32 v123, s60, v38
	v_add_u32_e32 v38, 0x240, v33
	v_readlane_b32 s40, v250, 25
	v_add_u32_e32 v124, s59, v38
	v_add_u32_e32 v125, s60, v38
	v_add_u32_e32 v38, 0x2d0, v33
	v_lshl_add_u32 v107, v32, 2, s40
	v_add_u32_e32 v108, s40, v176
	v_cmp_gt_u32_e64 s[40:41], 64, v32
	v_add_u32_e32 v115, s59, v33
	v_add_u32_e32 v116, s60, v33
	v_add_u32_e32 v117, 0, v33
	v_add_u32_e32 v126, s59, v38
	v_add_u32_e32 v127, s60, v38
	v_add_u32_e32 v38, 0x360, v33
	v_add_u32_e32 v33, 0x3f0, v33
	v_ashrrev_i32_e32 v32, 8, v32
	v_add_u32_e32 v130, s59, v33
	v_add_u32_e32 v131, s60, v33
	v_lshlrev_b32_e32 v33, 4, v32
	v_add_u32_e32 v128, s59, v38
	v_add_u32_e32 v129, s60, v38
	v_or_b32_e32 v38, v33, v34
	v_or_b32_e32 v33, v60, v33
	v_cmp_gt_i32_e64 s[60:61], v33, v42
	v_cmp_lt_i32_e64 s[62:63], v33, v42
	v_or_b32_e32 v39, 2, v33
	v_or_b32_e32 v33, 3, v33
	v_cmp_gt_i32_e64 s[66:67], v33, v42
	v_add_u32_e32 v33, 8, v35
	v_ashrrev_i32_e32 v33, 2, v33
	v_lshl_add_u32 v106, v35, 9, s46
	v_cmp_lt_i32_e64 s[42:43], 0, v35
	v_cmp_lt_i32_e64 s[44:45], 1, v35
	v_cmp_lt_i32_e64 s[46:47], 2, v35
	v_cmp_lt_i32_e64 s[48:49], 3, v35
	v_cmp_lt_i32_e64 s[50:51], 4, v35
	v_cmp_lt_i32_e64 s[52:53], 5, v35
	v_cmp_lt_i32_e64 s[54:55], 6, v35
	v_cmp_lt_i32_e64 s[56:57], 7, v35
	v_lshlrev_b32_e32 v35, 4, v33
	v_cmp_gt_i32_e64 s[64:65], v39, v42
	v_or_b32_e32 v39, v35, v34
	v_or_b32_e32 v35, v60, v35
	v_cmp_le_i32_e64 s[58:59], v32, v41
	v_cmp_le_i32_e64 s[68:69], v33, v41
	v_cmp_gt_i32_e64 s[70:71], v35, v42
	v_cmp_lt_i32_e64 s[72:73], v35, v42
	v_or_b32_e32 v41, 2, v35
	v_or_b32_e32 v35, 3, v35
	v_cndmask_b32_e32 v37, v229, v37, vcc
	v_readlane_b32 s80, v250, 26
	v_cmp_gt_i32_e64 s[76:77], v35, v42
	v_mul_u32_u24_e32 v35, 0x48, v34
	v_add_u32_e32 v43, 0, v43
	v_lshlrev_b32_e32 v113, 2, v37
	v_mul_lo_u32 v37, v46, s31
	v_mul_lo_u32 v38, v38, s31
	v_lshlrev_b32_e32 v32, 5, v32
	v_mul_lo_u32 v39, v39, s31
	v_lshlrev_b32_e32 v33, 5, v33
	v_lshl_add_u32 v132, v35, 1, v36
	v_mul_u32_u24_e32 v35, 0x210, v34
	v_lshl_add_u32 v133, v34, 2, s80
	v_mul_u32_u24_e32 v34, 0x90, v34
	s_mov_b32 s91, 0
	s_mov_b32 s86, 64
	v_add_u32_e32 v114, s80, v176
	v_cmp_gt_i32_e64 s[74:75], v41, v42
	v_add_u32_e32 v134, 64, v133
	v_add_u32_e32 v135, 0x80, v133
	v_add_u32_e32 v136, 0xc0, v133
	v_add_u32_e32 v137, v105, v37
	v_add_u32_e32 v138, v40, v58
	v_add_u32_e32 v139, v36, v38
	v_add_u32_e32 v140, v110, v32
	v_add_u32_e32 v141, v36, v39
	v_add_u32_e32 v142, v110, v33
	v_add_u32_e32 v143, v44, v35
	v_add_u32_e32 v144, v43, v34
	s_branch .LBB0_732
.LBB0_731:
	s_or_b64 exec, exec, s[80:81]
	v_cvt_pk_bf16_f32 v40, v46, v41
	v_cvt_pk_bf16_f32 v41, v42, v43
	ds_write_b64 v142, v[40:41] offset:46080
	s_waitcnt lgkmcnt(0)
	s_barrier
	ds_read_b128 v[44:47], v80 offset:27648
	ds_read_b128 v[48:51], v80 offset:55296
	ds_read_b128 v[40:43], v80 offset:27712
	ds_read_b128 v[52:55], v80 offset:55360
	ds_read_b128 v[146:149], v132 offset:46080
	ds_read_b128 v[150:153], v132
	s_waitcnt lgkmcnt(1)
	v_mfma_f32_16x16x32_bf16 v[146:149], v[44:47], v[146:149], 0
	s_add_i32 s86, s86, 64
	s_cmp_lg_u32 s95, s91
	s_waitcnt lgkmcnt(0)
	v_mfma_f32_16x16x32_bf16 v[146:149], v[48:51], v[150:153], v[146:149]
	ds_read_b128 v[150:153], v132 offset:46144
	ds_read_b128 v[154:157], v132 offset:64
	s_waitcnt lgkmcnt(1)
	v_mfma_f32_16x16x32_bf16 v[146:149], v[40:43], v[150:153], v[146:149]
	s_waitcnt lgkmcnt(0)
	v_mfma_f32_16x16x32_bf16 v[146:149], v[52:55], v[154:157], v[146:149]
	s_nop 7
	ds_write_b128 v143, v[146:149]
	ds_read_b128 v[146:149], v132 offset:48384
	ds_read_b128 v[150:153], v132 offset:2304
	s_waitcnt lgkmcnt(1)
	v_mfma_f32_16x16x32_bf16 v[146:149], v[44:47], v[146:149], 0
	s_waitcnt lgkmcnt(0)
	v_mfma_f32_16x16x32_bf16 v[146:149], v[48:51], v[150:153], v[146:149]
	ds_read_b128 v[150:153], v132 offset:48448
	ds_read_b128 v[154:157], v132 offset:2368
	s_waitcnt lgkmcnt(1)
	v_mfma_f32_16x16x32_bf16 v[146:149], v[40:43], v[150:153], v[146:149]
	s_waitcnt lgkmcnt(0)
	v_mfma_f32_16x16x32_bf16 v[146:149], v[52:55], v[154:157], v[146:149]
	s_nop 7
	ds_write_b128 v143, v[146:149] offset:8448
	ds_read_b128 v[146:149], v132 offset:50688
	ds_read_b128 v[150:153], v132 offset:4608
	s_waitcnt lgkmcnt(1)
	v_mfma_f32_16x16x32_bf16 v[146:149], v[44:47], v[146:149], 0
	s_waitcnt lgkmcnt(0)
	v_mfma_f32_16x16x32_bf16 v[146:149], v[48:51], v[150:153], v[146:149]
	ds_read_b128 v[150:153], v132 offset:50752
	ds_read_b128 v[154:157], v132 offset:4672
	s_waitcnt lgkmcnt(1)
	v_mfma_f32_16x16x32_bf16 v[146:149], v[40:43], v[150:153], v[146:149]
	s_waitcnt lgkmcnt(0)
	v_mfma_f32_16x16x32_bf16 v[146:149], v[52:55], v[154:157], v[146:149]
	s_nop 7
	ds_write_b128 v143, v[146:149] offset:16896
	ds_read_b128 v[146:149], v132 offset:52992
	ds_read_b128 v[150:153], v132 offset:6912
	s_waitcnt lgkmcnt(1)
	v_mfma_f32_16x16x32_bf16 v[146:149], v[44:47], v[146:149], 0
	s_waitcnt lgkmcnt(0)
	v_mfma_f32_16x16x32_bf16 v[48:51], v[48:51], v[150:153], v[146:149]
	s_nop 5
	ds_read_b128 v[146:149], v132 offset:53056
	ds_read_b128 v[150:153], v132 offset:6976
	s_waitcnt lgkmcnt(1)
	v_mfma_f32_16x16x32_bf16 v[48:51], v[40:43], v[146:149], v[48:51]
	s_waitcnt lgkmcnt(0)
	v_mfma_f32_16x16x32_bf16 v[48:51], v[52:55], v[150:153], v[48:51]
	s_nop 7
	ds_write_b128 v143, v[48:51] offset:25344
	ds_read_b32 v48, v133
	s_waitcnt lgkmcnt(0)
	v_pk_mul_f32 v[10:11], v[10:11], v[48:49] op_sel_hi:[1,0]
	v_pk_mul_f32 v[8:9], v[8:9], v[48:49] op_sel_hi:[1,0]
	ds_read_b128 v[48:51], v144 offset:18432
	s_waitcnt lgkmcnt(0)
	v_mfma_f32_16x16x32_bf16 v[8:11], v[44:47], v[48:51], v[8:11]
	ds_read_b128 v[48:51], v144 offset:18496
	s_waitcnt lgkmcnt(0)
	v_mfma_f32_16x16x32_bf16 v[8:11], v[40:43], v[48:51], v[8:11]
	s_nop 7
	v_cvt_pk_bf16_f32 v48, v8, s0
	ds_write_b16 v57, v48 offset:55296
	v_cvt_pk_bf16_f32 v48, v9, s0
	ds_write_b16 v57, v48 offset:55440
	v_cvt_pk_bf16_f32 v48, v10, s0
	ds_write_b16 v57, v48 offset:55584
	v_cvt_pk_bf16_f32 v48, v11, s0
	ds_write_b16 v57, v48 offset:55728
	ds_read_b32 v48, v134
	s_waitcnt lgkmcnt(0)
	v_pk_mul_f32 v[2:3], v[2:3], v[48:49] op_sel_hi:[1,0]
	v_pk_mul_f32 v[0:1], v[0:1], v[48:49] op_sel_hi:[1,0]
	ds_read_b128 v[48:51], v144 offset:20736
	s_waitcnt lgkmcnt(0)
	v_mfma_f32_16x16x32_bf16 v[0:3], v[44:47], v[48:51], v[0:3]
	ds_read_b128 v[48:51], v144 offset:20800
	s_waitcnt lgkmcnt(0)
	v_mfma_f32_16x16x32_bf16 v[0:3], v[40:43], v[48:51], v[0:3]
	s_nop 7
	v_cvt_pk_bf16_f32 v48, v0, s0
	ds_write_b16 v57, v48 offset:55328
	v_cvt_pk_bf16_f32 v48, v1, s0
	ds_write_b16 v57, v48 offset:55472
	v_cvt_pk_bf16_f32 v48, v2, s0
	ds_write_b16 v57, v48 offset:55616
	v_cvt_pk_bf16_f32 v48, v3, s0
	ds_write_b16 v57, v48 offset:55760
	ds_read_b32 v48, v135
	s_waitcnt lgkmcnt(0)
	v_pk_mul_f32 v[6:7], v[6:7], v[48:49] op_sel_hi:[1,0]
	v_pk_mul_f32 v[4:5], v[4:5], v[48:49] op_sel_hi:[1,0]
	ds_read_b128 v[48:51], v144 offset:23040
	s_waitcnt lgkmcnt(0)
	v_mfma_f32_16x16x32_bf16 v[4:7], v[44:47], v[48:51], v[4:7]
	ds_read_b128 v[48:51], v144 offset:23104
	s_waitcnt lgkmcnt(0)
	v_mfma_f32_16x16x32_bf16 v[4:7], v[40:43], v[48:51], v[4:7]
	s_nop 7
	v_cvt_pk_bf16_f32 v48, v4, s0
	ds_write_b16 v57, v48 offset:55360
	v_cvt_pk_bf16_f32 v48, v5, s0
	ds_write_b16 v57, v48 offset:55504
	v_cvt_pk_bf16_f32 v48, v6, s0
	ds_write_b16 v57, v48 offset:55648
	v_cvt_pk_bf16_f32 v48, v7, s0
	ds_write_b16 v57, v48 offset:55792
	ds_read_b32 v48, v136
	s_waitcnt lgkmcnt(0)
	v_pk_mul_f32 v[14:15], v[14:15], v[48:49] op_sel_hi:[1,0]
	v_pk_mul_f32 v[12:13], v[12:13], v[48:49] op_sel_hi:[1,0]
	ds_read_b128 v[48:51], v144 offset:25344
	s_waitcnt lgkmcnt(0)
	v_mfma_f32_16x16x32_bf16 v[12:15], v[44:47], v[48:51], v[12:15]
	ds_read_b128 v[44:47], v144 offset:25408
	s_waitcnt lgkmcnt(0)
	v_mfma_f32_16x16x32_bf16 v[12:15], v[40:43], v[44:47], v[12:15]
	s_nop 7
	v_cvt_pk_bf16_f32 v40, v12, s0
	ds_write_b16 v57, v40 offset:55392
	v_cvt_pk_bf16_f32 v40, v13, s0
	ds_write_b16 v57, v40 offset:55536
	v_cvt_pk_bf16_f32 v40, v14, s0
	ds_write_b16 v57, v40 offset:55680
	v_cvt_pk_bf16_f32 v40, v15, s0
	ds_write_b16 v57, v40 offset:55824
	s_waitcnt lgkmcnt(0)
	s_barrier
	ds_read_b128 v[52:55], v81
	ds_read_b128 v[48:51], v81 offset:16
	ds_read_b128 v[44:47], v81 offset:32
	ds_read_b128 v[40:43], v81 offset:48
	s_waitcnt lgkmcnt(3)
	v_mov_b32_e32 v148, v53
	s_waitcnt lgkmcnt(2)
	v_mov_b32_e32 v149, v49
	v_mov_b32_e32 v146, v52
	v_mov_b32_e32 v147, v48
	v_pk_mul_f32 v[148:149], v[148:149], v[148:149]
	s_waitcnt lgkmcnt(1)
	v_mov_b32_e32 v150, v45
	v_pk_fma_f32 v[146:147], v[146:147], v[146:147], v[148:149]
	v_mov_b32_e32 v148, v54
	v_mov_b32_e32 v149, v50
	v_pk_fma_f32 v[146:147], v[148:149], v[148:149], v[146:147]
	v_mov_b32_e32 v148, v55
	v_mov_b32_e32 v149, v51
	s_waitcnt lgkmcnt(0)
	v_mov_b32_e32 v151, v41
	v_pk_fma_f32 v[146:147], v[148:149], v[148:149], v[146:147]
	v_mov_b32_e32 v148, v44
	v_mov_b32_e32 v149, v40
	v_pk_mul_f32 v[150:151], v[150:151], v[150:151]
	v_add_f32_e32 v86, v146, v147
	v_pk_fma_f32 v[148:149], v[148:149], v[148:149], v[150:151]
	v_mov_b32_e32 v150, v46
	v_mov_b32_e32 v151, v42
	v_pk_fma_f32 v[148:149], v[150:151], v[150:151], v[148:149]
	v_mov_b32_e32 v150, v47
	v_mov_b32_e32 v151, v43
	v_pk_fma_f32 v[148:149], v[150:151], v[150:151], v[148:149]
	s_waitcnt vmcnt(0)
	v_lshlrev_b32_e32 v150, 16, v36
	v_add_f32_e32 v86, v86, v148
	v_add_f32_e32 v86, v86, v149
	ds_bpermute_b32 v145, v111, v86
	v_and_b32_e32 v151, 0xffff0000, v36
	v_lshlrev_b32_e32 v36, 16, v37
	v_and_b32_e32 v37, 0xffff0000, v37
	s_waitcnt lgkmcnt(0)
	v_add_f32_e32 v86, v86, v145
	ds_bpermute_b32 v145, v112, v86
	s_waitcnt lgkmcnt(0)
	v_add_f32_e32 v86, v86, v145
	ds_bpermute_b32 v145, v113, v86
	s_waitcnt lgkmcnt(0)
	v_add_f32_e32 v86, v86, v145
	v_fmamk_f32 v86, v86, 0x3c000000, v228
	v_rsq_f32_e32 v86, v86
	s_nop 0
	v_pk_mul_f32 v[54:55], v[54:55], v[86:87] op_sel_hi:[1,0]
	v_pk_mul_f32 v[52:53], v[52:53], v[86:87] op_sel_hi:[1,0]
	v_pk_mul_f32 v[50:51], v[50:51], v[86:87] op_sel_hi:[1,0]
	v_pk_mul_f32 v[48:49], v[48:49], v[86:87] op_sel_hi:[1,0]
	v_pk_mul_f32 v[46:47], v[46:47], v[86:87] op_sel_hi:[1,0]
	v_pk_mul_f32 v[44:45], v[44:45], v[86:87] op_sel_hi:[1,0]
	v_pk_mul_f32 v[42:43], v[42:43], v[86:87] op_sel_hi:[1,0]
	v_pk_mul_f32 v[40:41], v[40:41], v[86:87] op_sel_hi:[1,0]
	v_pk_mul_f32 v[52:53], v[160:161], v[52:53]
	v_pk_mul_f32 v[54:55], v[162:163], v[54:55]
	v_pk_mul_f32 v[52:53], v[52:53], v[150:151]
	v_pk_mul_f32 v[36:37], v[54:55], v[36:37]
	v_cvt_pk_bf16_f32 v52, v52, v53
	v_cvt_pk_bf16_f32 v53, v36, v37
	global_store_dwordx2 v[84:85], v[52:53], off
	v_lshlrev_b32_e32 v36, 16, v38
	v_and_b32_e32 v37, 0xffff0000, v38
	v_lshlrev_b32_e32 v38, 16, v39
	v_and_b32_e32 v39, 0xffff0000, v39
	v_pk_mul_f32 v[48:49], v[164:165], v[48:49]
	v_pk_mul_f32 v[50:51], v[166:167], v[50:51]
	v_pk_mul_f32 v[36:37], v[48:49], v[36:37]
	v_pk_mul_f32 v[38:39], v[50:51], v[38:39]
	v_cvt_pk_bf16_f32 v36, v36, v37
	v_cvt_pk_bf16_f32 v37, v38, v39
	global_store_dwordx2 v[84:85], v[36:37], off offset:8
	v_lshlrev_b32_e32 v48, 16, v32
	v_and_b32_e32 v49, 0xffff0000, v32
	v_lshlrev_b32_e32 v32, 16, v33
	v_and_b32_e32 v33, 0xffff0000, v33
	v_pk_mul_f32 v[36:37], v[168:169], v[44:45]
	v_pk_mul_f32 v[38:39], v[170:171], v[46:47]
	v_pk_mul_f32 v[36:37], v[36:37], v[48:49]
	v_pk_mul_f32 v[32:33], v[38:39], v[32:33]
	v_cvt_pk_bf16_f32 v36, v36, v37
	v_cvt_pk_bf16_f32 v37, v32, v33
	global_store_dwordx2 v[84:85], v[36:37], off offset:16
	v_lshlrev_b32_e32 v32, 16, v34
	v_and_b32_e32 v33, 0xffff0000, v34
	v_lshlrev_b32_e32 v34, 16, v35
	v_and_b32_e32 v35, 0xffff0000, v35
	v_pk_mul_f32 v[36:37], v[172:173], v[40:41]
	v_pk_mul_f32 v[38:39], v[174:175], v[42:43]
	v_pk_mul_f32 v[32:33], v[36:37], v[32:33]
	v_pk_mul_f32 v[34:35], v[38:39], v[34:35]
	v_cvt_pk_bf16_f32 v32, v32, v33
	v_cvt_pk_bf16_f32 v33, v34, v35
	global_store_dwordx2 v[84:85], v[32:33], off offset:24
	s_cbranch_scc0 .LBB0_742

.LBB0_932:
	s_add_u32 s16, s14, 0xfffe0080
	s_addc_u32 s17, s15, -1
	s_add_i32 s50, 0, 0x10000
	v_add_u32_e32 v150, s50, v144
	ds_read_b128 v[134:137], v150
	ds_read_b128 v[138:141], v150 offset:1024
	ds_read_b128 v[146:149], v150 offset:2048
	ds_read_b128 v[150:153], v150 offset:3072
	s_cmp_eq_u32 s49, 4
	s_cselect_b32 s19, s11, s17
	s_cselect_b32 s18, s10, s16
	s_cselect_b32 s17, s13, s9
	s_cselect_b32 s16, s12, s7
	v_lshl_add_u64 v[174:175], s[14:15], 0, v[130:131]
	s_add_i32 m0, s3, 0xc000
	ds_read_b128 v[154:157], v145
	ds_read_b128 v[158:161], v145 offset:1024
	ds_read_b128 v[162:165], v145 offset:2048
	ds_read_b128 v[166:169], v145 offset:3072
	ds_read_b128 v[170:173], v145 offset:4096
	ds_read_b128 v[190:193], v145 offset:5120
	ds_read_b128 v[194:197], v145 offset:6144
	ds_read_b128 v[198:201], v145 offset:7168
	global_load_lds_dwordx4 v[174:175], off
	v_lshl_add_u64 v[174:175], s[14:15], 0, v[132:133]
	s_add_i32 m0, s3, 0xe000
	s_nop 0
	global_load_lds_dwordx4 v[174:175], off
	s_waitcnt lgkmcnt(8)
	s_barrier
	s_waitcnt lgkmcnt(0)
	s_setprio 1
	s_waitcnt lgkmcnt(0)
	v_mfma_f32_16x16x32_bf16 v[124:127], v[134:137], v[154:157], v[124:127]
	v_mfma_f32_16x16x32_bf16 v[120:123], v[146:149], v[154:157], v[120:123]
	v_mfma_f32_16x16x32_bf16 v[108:111], v[134:137], v[162:165], v[108:111]
	v_mfma_f32_16x16x32_bf16 v[104:107], v[146:149], v[162:165], v[104:107]
	v_mfma_f32_16x16x32_bf16 v[92:95], v[134:137], v[170:173], v[92:95]
	v_mfma_f32_16x16x32_bf16 v[88:91], v[146:149], v[170:173], v[88:91]
	v_mfma_f32_16x16x32_bf16 v[76:79], v[134:137], v[194:197], v[76:79]
	v_mfma_f32_16x16x32_bf16 v[72:75], v[146:149], v[194:197], v[72:75]
	v_mfma_f32_16x16x32_bf16 v[124:127], v[138:141], v[158:161], v[124:127]
	v_mfma_f32_16x16x32_bf16 v[120:123], v[150:153], v[158:161], v[120:123]
	v_mfma_f32_16x16x32_bf16 v[108:111], v[138:141], v[166:169], v[108:111]
	v_mfma_f32_16x16x32_bf16 v[104:107], v[150:153], v[166:169], v[104:107]
	v_mfma_f32_16x16x32_bf16 v[92:95], v[138:141], v[190:193], v[92:95]
	v_mfma_f32_16x16x32_bf16 v[88:91], v[150:153], v[190:193], v[88:91]
	v_mfma_f32_16x16x32_bf16 v[76:79], v[138:141], v[198:201], v[76:79]
	v_mfma_f32_16x16x32_bf16 v[72:75], v[150:153], v[198:201], v[72:75]
	s_setprio 0
	s_barrier
	s_add_i32 s52, 0, 0x14000
	v_add_u32_e32 v174, s52, v144
	s_add_i32 s50, s50, s38
	ds_read_b128 v[202:205], v174
	ds_read_b128 v[206:209], v174 offset:1024
	ds_read_b128 v[210:213], v174 offset:2048
	ds_read_b128 v[214:217], v174 offset:3072
	v_lshl_add_u64 v[174:175], s[16:17], 0, v[176:177]
	s_mov_b32 m0, s50
	v_lshl_add_u64 v[218:219], s[16:17], 0, v[128:129]
	global_load_lds_dwordx4 v[174:175], off
	s_add_i32 m0, s50, 0x2000
	s_nop 0
	global_load_lds_dwordx4 v[218:219], off
	s_barrier
	s_waitcnt lgkmcnt(0)
	s_setprio 1
	s_waitcnt lgkmcnt(0)
	v_mfma_f32_16x16x32_bf16 v[116:119], v[202:205], v[154:157], v[116:119]
	v_mfma_f32_16x16x32_bf16 v[112:115], v[210:213], v[154:157], v[112:115]
	v_mfma_f32_16x16x32_bf16 v[100:103], v[202:205], v[162:165], v[100:103]
	v_mfma_f32_16x16x32_bf16 v[96:99], v[210:213], v[162:165], v[96:99]
	v_mfma_f32_16x16x32_bf16 v[84:87], v[202:205], v[170:173], v[84:87]
	v_mfma_f32_16x16x32_bf16 v[80:83], v[210:213], v[170:173], v[80:83]
	v_mfma_f32_16x16x32_bf16 v[68:71], v[202:205], v[194:197], v[68:71]
	v_mfma_f32_16x16x32_bf16 v[64:67], v[210:213], v[194:197], v[64:67]
	v_mfma_f32_16x16x32_bf16 v[116:119], v[206:209], v[158:161], v[116:119]
	v_mfma_f32_16x16x32_bf16 v[112:115], v[214:217], v[158:161], v[112:115]
	v_mfma_f32_16x16x32_bf16 v[100:103], v[206:209], v[166:169], v[100:103]
	v_mfma_f32_16x16x32_bf16 v[96:99], v[214:217], v[166:169], v[96:99]
	v_mfma_f32_16x16x32_bf16 v[84:87], v[206:209], v[190:193], v[84:87]
	v_mfma_f32_16x16x32_bf16 v[80:83], v[214:217], v[190:193], v[80:83]
	v_mfma_f32_16x16x32_bf16 v[68:71], v[206:209], v[198:201], v[68:71]
	v_mfma_f32_16x16x32_bf16 v[64:67], v[214:217], v[198:201], v[64:67]
	s_setprio 0
	s_mov_b32 m0, s3
	v_lshl_add_u64 v[220:221], s[18:19], 0, v[176:177]
	s_barrier
	ds_read_b128 v[154:157], v145 offset:16384
	ds_read_b128 v[158:161], v145 offset:17408
	ds_read_b128 v[162:165], v145 offset:18432
	ds_read_b128 v[166:169], v145 offset:19456
	ds_read_b128 v[170:173], v145 offset:20480
	ds_read_b128 v[190:193], v145 offset:21504
	ds_read_b128 v[194:197], v145 offset:22528
	ds_read_b128 v[198:201], v145 offset:23552
	global_load_lds_dwordx4 v[220:221], off
	v_lshl_add_u64 v[222:223], s[18:19], 0, v[128:129]
	s_mov_b32 m0, s39
	s_nop 0
	global_load_lds_dwordx4 v[222:223], off
	s_barrier
	s_waitcnt lgkmcnt(0)
	s_setprio 1
	s_waitcnt lgkmcnt(0)
	v_mfma_f32_16x16x32_bf16 v[60:63], v[134:137], v[154:157], v[60:63]
	v_mfma_f32_16x16x32_bf16 v[56:59], v[146:149], v[154:157], v[56:59]
	v_mfma_f32_16x16x32_bf16 v[44:47], v[134:137], v[162:165], v[44:47]
	v_mfma_f32_16x16x32_bf16 v[40:43], v[146:149], v[162:165], v[40:43]
	v_mfma_f32_16x16x32_bf16 v[28:31], v[134:137], v[170:173], v[28:31]
	v_mfma_f32_16x16x32_bf16 v[24:27], v[146:149], v[170:173], v[24:27]
	v_mfma_f32_16x16x32_bf16 v[12:15], v[134:137], v[194:197], v[12:15]
	v_mfma_f32_16x16x32_bf16 v[8:11], v[146:149], v[194:197], v[8:11]
	v_mfma_f32_16x16x32_bf16 v[60:63], v[138:141], v[158:161], v[60:63]
	v_mfma_f32_16x16x32_bf16 v[56:59], v[150:153], v[158:161], v[56:59]
	v_mfma_f32_16x16x32_bf16 v[44:47], v[138:141], v[166:169], v[44:47]
	v_mfma_f32_16x16x32_bf16 v[40:43], v[150:153], v[166:169], v[40:43]
	v_mfma_f32_16x16x32_bf16 v[28:31], v[138:141], v[190:193], v[28:31]
	v_mfma_f32_16x16x32_bf16 v[24:27], v[150:153], v[190:193], v[24:27]
	v_mfma_f32_16x16x32_bf16 v[12:15], v[138:141], v[198:201], v[12:15]
	v_mfma_f32_16x16x32_bf16 v[8:11], v[150:153], v[198:201], v[8:11]
	s_setprio 0
	s_barrier
	s_add_u32 s50, s16, 0x20000
	s_addc_u32 s51, s17, 0
	s_add_i32 s52, s52, s38
	v_lshl_add_u64 v[134:135], s[50:51], 0, v[176:177]
	s_mov_b32 m0, s52
	s_nop 0
	global_load_lds_dwordx4 v[134:135], off
	v_lshl_add_u64 v[134:135], s[50:51], 0, v[128:129]
	s_add_i32 m0, s52, 0x2000
	s_nop 0
	global_load_lds_dwordx4 v[134:135], off
	s_waitcnt vmcnt(6)
	s_barrier
	s_setprio 1
	v_mfma_f32_16x16x32_bf16 v[52:55], v[202:205], v[154:157], v[52:55]
	v_mfma_f32_16x16x32_bf16 v[48:51], v[210:213], v[154:157], v[48:51]
	v_mfma_f32_16x16x32_bf16 v[36:39], v[202:205], v[162:165], v[36:39]
	v_mfma_f32_16x16x32_bf16 v[32:35], v[210:213], v[162:165], v[32:35]
	v_mfma_f32_16x16x32_bf16 v[20:23], v[202:205], v[170:173], v[20:23]
	v_mfma_f32_16x16x32_bf16 v[16:19], v[210:213], v[170:173], v[16:19]
	v_mfma_f32_16x16x32_bf16 v[4:7], v[202:205], v[194:197], v[4:7]
	v_mfma_f32_16x16x32_bf16 v[0:3], v[210:213], v[194:197], v[0:3]
	v_mfma_f32_16x16x32_bf16 v[52:55], v[206:209], v[158:161], v[52:55]
	v_mfma_f32_16x16x32_bf16 v[48:51], v[214:217], v[158:161], v[48:51]
	v_mfma_f32_16x16x32_bf16 v[36:39], v[206:209], v[166:169], v[36:39]
	v_mfma_f32_16x16x32_bf16 v[32:35], v[214:217], v[166:169], v[32:35]
	v_mfma_f32_16x16x32_bf16 v[20:23], v[206:209], v[190:193], v[20:23]
	v_mfma_f32_16x16x32_bf16 v[16:19], v[214:217], v[190:193], v[16:19]
	v_mfma_f32_16x16x32_bf16 v[4:7], v[206:209], v[198:201], v[4:7]
	v_mfma_f32_16x16x32_bf16 v[0:3], v[214:217], v[198:201], v[0:3]
	s_setprio 0
	s_add_i32 s50, 0, 0x18000
	v_add_u32_e32 v150, s50, v144
	s_barrier
	ds_read_b128 v[134:137], v150
	ds_read_b128 v[138:141], v150 offset:1024
	ds_read_b128 v[146:149], v150 offset:2048
	ds_read_b128 v[150:153], v150 offset:3072
	s_add_u32 s18, s18, 0x20000
	s_addc_u32 s19, s19, 0
	s_mov_b32 m0, s42
	v_lshl_add_u64 v[202:203], s[18:19], 0, v[176:177]
	ds_read_b128 v[154:157], v145 offset:32768
	ds_read_b128 v[158:161], v145 offset:33792
	ds_read_b128 v[162:165], v145 offset:34816
	ds_read_b128 v[166:169], v145 offset:35840
	ds_read_b128 v[170:173], v145 offset:36864
	ds_read_b128 v[190:193], v145 offset:37888
	ds_read_b128 v[194:197], v145 offset:38912
	ds_read_b128 v[198:201], v145 offset:39936
	global_load_lds_dwordx4 v[202:203], off
	v_lshl_add_u64 v[202:203], s[18:19], 0, v[128:129]
	s_mov_b32 m0, s43
	s_nop 0
	global_load_lds_dwordx4 v[202:203], off
	s_waitcnt lgkmcnt(8)
	s_barrier
	s_waitcnt lgkmcnt(0)
	s_setprio 1
	s_waitcnt lgkmcnt(0)
	v_mfma_f32_16x16x32_bf16 v[124:127], v[134:137], v[154:157], v[124:127]
	v_mfma_f32_16x16x32_bf16 v[120:123], v[146:149], v[154:157], v[120:123]
	v_mfma_f32_16x16x32_bf16 v[108:111], v[134:137], v[162:165], v[108:111]
	v_mfma_f32_16x16x32_bf16 v[104:107], v[146:149], v[162:165], v[104:107]
	v_mfma_f32_16x16x32_bf16 v[92:95], v[134:137], v[170:173], v[92:95]
	v_mfma_f32_16x16x32_bf16 v[88:91], v[146:149], v[170:173], v[88:91]
	v_mfma_f32_16x16x32_bf16 v[76:79], v[134:137], v[194:197], v[76:79]
	v_mfma_f32_16x16x32_bf16 v[72:75], v[146:149], v[194:197], v[72:75]
	v_mfma_f32_16x16x32_bf16 v[124:127], v[138:141], v[158:161], v[124:127]
	v_mfma_f32_16x16x32_bf16 v[120:123], v[150:153], v[158:161], v[120:123]
	v_mfma_f32_16x16x32_bf16 v[108:111], v[138:141], v[166:169], v[108:111]
	v_mfma_f32_16x16x32_bf16 v[104:107], v[150:153], v[166:169], v[104:107]
	v_mfma_f32_16x16x32_bf16 v[92:95], v[138:141], v[190:193], v[92:95]
	v_mfma_f32_16x16x32_bf16 v[88:91], v[150:153], v[190:193], v[88:91]
	v_mfma_f32_16x16x32_bf16 v[76:79], v[138:141], v[198:201], v[76:79]
	v_mfma_f32_16x16x32_bf16 v[72:75], v[150:153], v[198:201], v[72:75]
	s_setprio 0
	s_barrier
	s_add_i32 s18, 0, 0x1c000
	s_add_i32 s19, s50, s38
	v_add_u32_e32 v214, s18, v144
	v_lshl_add_u64 v[174:175], v[174:175], 0, s[24:25]
	s_mov_b32 m0, s19
	ds_read_b128 v[202:205], v214
	ds_read_b128 v[206:209], v214 offset:1024
	ds_read_b128 v[210:213], v214 offset:2048
	ds_read_b128 v[214:217], v214 offset:3072
	global_load_lds_dwordx4 v[174:175], off
	v_lshl_add_u64 v[174:175], v[218:219], 0, s[24:25]
	s_add_i32 m0, s19, 0x2000
	s_nop 0
	global_load_lds_dwordx4 v[174:175], off
	s_barrier
	s_waitcnt lgkmcnt(0)
	s_setprio 1
	s_waitcnt lgkmcnt(0)
	v_mfma_f32_16x16x32_bf16 v[116:119], v[202:205], v[154:157], v[116:119]
	v_mfma_f32_16x16x32_bf16 v[112:115], v[210:213], v[154:157], v[112:115]
	v_mfma_f32_16x16x32_bf16 v[100:103], v[202:205], v[162:165], v[100:103]
	v_mfma_f32_16x16x32_bf16 v[96:99], v[210:213], v[162:165], v[96:99]
	v_mfma_f32_16x16x32_bf16 v[84:87], v[202:205], v[170:173], v[84:87]
	v_mfma_f32_16x16x32_bf16 v[80:83], v[210:213], v[170:173], v[80:83]
	v_mfma_f32_16x16x32_bf16 v[68:71], v[202:205], v[194:197], v[68:71]
	v_mfma_f32_16x16x32_bf16 v[64:67], v[210:213], v[194:197], v[64:67]
	v_mfma_f32_16x16x32_bf16 v[116:119], v[206:209], v[158:161], v[116:119]
	v_mfma_f32_16x16x32_bf16 v[112:115], v[214:217], v[158:161], v[112:115]
	v_mfma_f32_16x16x32_bf16 v[100:103], v[206:209], v[166:169], v[100:103]
	v_mfma_f32_16x16x32_bf16 v[96:99], v[214:217], v[166:169], v[96:99]
	v_mfma_f32_16x16x32_bf16 v[84:87], v[206:209], v[190:193], v[84:87]
	v_mfma_f32_16x16x32_bf16 v[80:83], v[214:217], v[190:193], v[80:83]
	v_mfma_f32_16x16x32_bf16 v[68:71], v[206:209], v[198:201], v[68:71]
	v_mfma_f32_16x16x32_bf16 v[64:67], v[214:217], v[198:201], v[64:67]
	s_setprio 0
	s_mov_b32 m0, s45
	v_lshl_add_u64 v[174:175], v[220:221], 0, s[24:25]
	s_barrier
	ds_read_b128 v[154:157], v145 offset:49152
	ds_read_b128 v[158:161], v145 offset:50176
	ds_read_b128 v[162:165], v145 offset:51200
	ds_read_b128 v[166:169], v145 offset:52224
	ds_read_b128 v[170:173], v145 offset:53248
	ds_read_b128 v[190:193], v145 offset:54272
	ds_read_b128 v[194:197], v145 offset:55296
	ds_read_b128 v[198:201], v145 offset:56320
	global_load_lds_dwordx4 v[174:175], off
	v_lshl_add_u64 v[174:175], v[222:223], 0, s[24:25]
	s_mov_b32 m0, s46
	s_nop 0
	global_load_lds_dwordx4 v[174:175], off
	s_barrier
	s_waitcnt lgkmcnt(0)
	s_setprio 1
	s_waitcnt lgkmcnt(0)
	v_mfma_f32_16x16x32_bf16 v[60:63], v[134:137], v[154:157], v[60:63]
	v_mfma_f32_16x16x32_bf16 v[56:59], v[146:149], v[154:157], v[56:59]
	v_mfma_f32_16x16x32_bf16 v[44:47], v[134:137], v[162:165], v[44:47]
	v_mfma_f32_16x16x32_bf16 v[40:43], v[146:149], v[162:165], v[40:43]
	v_mfma_f32_16x16x32_bf16 v[28:31], v[134:137], v[170:173], v[28:31]
	v_mfma_f32_16x16x32_bf16 v[24:27], v[146:149], v[170:173], v[24:27]
	v_mfma_f32_16x16x32_bf16 v[12:15], v[134:137], v[194:197], v[12:15]
	v_mfma_f32_16x16x32_bf16 v[8:11], v[146:149], v[194:197], v[8:11]
	v_mfma_f32_16x16x32_bf16 v[60:63], v[138:141], v[158:161], v[60:63]
	v_mfma_f32_16x16x32_bf16 v[56:59], v[150:153], v[158:161], v[56:59]
	v_mfma_f32_16x16x32_bf16 v[44:47], v[138:141], v[166:169], v[44:47]
	v_mfma_f32_16x16x32_bf16 v[40:43], v[150:153], v[166:169], v[40:43]
	v_mfma_f32_16x16x32_bf16 v[28:31], v[138:141], v[190:193], v[28:31]
	v_mfma_f32_16x16x32_bf16 v[24:27], v[150:153], v[190:193], v[24:27]
	v_mfma_f32_16x16x32_bf16 v[12:15], v[138:141], v[198:201], v[12:15]
	v_mfma_f32_16x16x32_bf16 v[8:11], v[150:153], v[198:201], v[8:11]
	s_setprio 0
	s_barrier
	s_add_u32 s16, s16, 0x20080
	s_addc_u32 s17, s17, 0
	s_add_i32 s18, s18, s38
	v_lshl_add_u64 v[134:135], s[16:17], 0, v[176:177]
	s_mov_b32 m0, s18
	s_nop 0
	global_load_lds_dwordx4 v[134:135], off
	v_lshl_add_u64 v[134:135], s[16:17], 0, v[128:129]
	s_add_i32 m0, s18, 0x2000
	s_nop 0
	global_load_lds_dwordx4 v[134:135], off
	s_waitcnt vmcnt(6)
	s_barrier
	s_setprio 1
	v_mfma_f32_16x16x32_bf16 v[52:55], v[202:205], v[154:157], v[52:55]
	v_mfma_f32_16x16x32_bf16 v[48:51], v[210:213], v[154:157], v[48:51]
	v_mfma_f32_16x16x32_bf16 v[36:39], v[202:205], v[162:165], v[36:39]
	v_mfma_f32_16x16x32_bf16 v[32:35], v[210:213], v[162:165], v[32:35]
	v_mfma_f32_16x16x32_bf16 v[20:23], v[202:205], v[170:173], v[20:23]
	v_mfma_f32_16x16x32_bf16 v[16:19], v[210:213], v[170:173], v[16:19]
	v_mfma_f32_16x16x32_bf16 v[4:7], v[202:205], v[194:197], v[4:7]
	v_mfma_f32_16x16x32_bf16 v[0:3], v[210:213], v[194:197], v[0:3]
	v_mfma_f32_16x16x32_bf16 v[52:55], v[206:209], v[158:161], v[52:55]
	v_mfma_f32_16x16x32_bf16 v[48:51], v[214:217], v[158:161], v[48:51]
	v_mfma_f32_16x16x32_bf16 v[36:39], v[206:209], v[166:169], v[36:39]
	v_mfma_f32_16x16x32_bf16 v[32:35], v[214:217], v[166:169], v[32:35]
	v_mfma_f32_16x16x32_bf16 v[20:23], v[206:209], v[190:193], v[20:23]
	v_mfma_f32_16x16x32_bf16 v[16:19], v[214:217], v[190:193], v[16:19]
	v_mfma_f32_16x16x32_bf16 v[4:7], v[206:209], v[198:201], v[4:7]
	v_mfma_f32_16x16x32_bf16 v[0:3], v[214:217], v[198:201], v[0:3]
	s_setprio 0
	s_add_i32 s49, s49, 2
	s_add_u32 s14, s14, 0x100
	s_addc_u32 s15, s15, 0
	s_add_u32 s7, s7, 0x100
	s_addc_u32 s9, s9, 0
	s_cmp_gt_u32 s49, 5
	s_barrier
	s_cbranch_scc0 .LBB0_932
	s_lshl_b32 s7, s29, 6
	s_lshl_b32 s9, s2, 8
	s_add_i32 s7, s7, s9
	v_add_u32_e32 v140, s7, v142
	s_lshl_b32 s7, s44, 5
	s_lshl_b32 s9, s48, 8
	s_add_i32 s7, s7, s9
	v_lshl_add_u32 v141, v143, 2, s7
	s_mov_b32 s48, s6
	s_mov_b64 s[16:17], s[12:13]
	s_mov_b32 s2, s8
	s_mov_b64 s[14:15], s[10:11]
	v_lshlrev_b32_e32 v134, 2, v141
	global_load_dwordx4 v[240:243], v134, s[4:5]
	global_load_dwordx4 v[244:247], v134, s[4:5] offset:64
	global_load_dwordx4 v[252:255], v134, s[4:5] offset:512
	global_load_dwordx4 v[136:139], v134, s[4:5] offset:576
	v_lshlrev_b32_e32 v238, 10, v140
	v_lshl_add_u32 v238, v141, 1, v238
	v_lshlrev_b32_e32 v239, 11, v140
	v_lshl_add_u32 v239, v141, 1, v239
	v_add_u32_e32 v239, 0x4100400, v239
	global_load_dwordx2 v[190:191], v238, s[78:79]
	global_load_dwordx2 v[192:193], v238, s[78:79] offset:32
	global_load_dwordx2 v[194:195], v238, s[78:79] offset:256
	global_load_dwordx2 v[196:197], v238, s[78:79] offset:288
	v_add_u32_e32 v238, 0x4000, v238
	global_load_dwordx2 v[198:199], v238, s[78:79]
	global_load_dwordx2 v[200:201], v238, s[78:79] offset:32
	global_load_dwordx2 v[202:203], v238, s[78:79] offset:256
	global_load_dwordx2 v[204:205], v238, s[78:79] offset:288
	v_add_u32_e32 v238, 0x4000, v238
	global_load_dwordx2 v[206:207], v238, s[78:79]
	global_load_dwordx2 v[208:209], v238, s[78:79] offset:32
	global_load_dwordx2 v[210:211], v238, s[78:79] offset:256
	global_load_dwordx2 v[212:213], v238, s[78:79] offset:288
	v_add_u32_e32 v238, 0x4000, v238
	global_load_dwordx2 v[214:215], v238, s[78:79]
	global_load_dwordx2 v[216:217], v238, s[78:79] offset:32
	global_load_dwordx2 v[218:219], v238, s[78:79] offset:256
	global_load_dwordx2 v[220:221], v238, s[78:79] offset:288
	v_add_u32_e32 v238, 0x14000, v238
	global_load_dwordx2 v[222:223], v238, s[78:79]
	global_load_dwordx2 v[146:147], v238, s[78:79] offset:32
	global_load_dwordx2 v[148:149], v238, s[78:79] offset:256
	global_load_dwordx2 v[150:151], v238, s[78:79] offset:288
	v_add_u32_e32 v238, 0x4000, v238
	global_load_dwordx2 v[152:153], v238, s[78:79]
	global_load_dwordx2 v[154:155], v238, s[78:79] offset:32
	global_load_dwordx2 v[156:157], v238, s[78:79] offset:256
	global_load_dwordx2 v[158:159], v238, s[78:79] offset:288
	v_add_u32_e32 v238, 0x4000, v238
	global_load_dwordx2 v[160:161], v238, s[78:79]
	global_load_dwordx2 v[162:163], v238, s[78:79] offset:32
	global_load_dwordx2 v[164:165], v238, s[78:79] offset:256
	global_load_dwordx2 v[166:167], v238, s[78:79] offset:288
	v_add_u32_e32 v238, 0x4000, v238
	global_load_dwordx2 v[168:169], v238, s[78:79]
	global_load_dwordx2 v[170:171], v238, s[78:79] offset:32
	global_load_dwordx2 v[172:173], v238, s[78:79] offset:256
	global_load_dwordx2 v[174:175], v238, s[78:79] offset:288
	s_waitcnt vmcnt(31)
	v_pk_add_f32 v[124:125], v[124:125], v[240:241]
	v_pk_add_f32 v[126:127], v[126:127], v[242:243]
	v_mul_f32_e32 v124, 0xbfb8aa3b, v124
	v_mul_f32_e32 v125, 0xbfb8aa3b, v125
	v_mul_f32_e32 v126, 0xbfb8aa3b, v126
	v_mul_f32_e32 v127, 0xbfb8aa3b, v127
	v_exp_f32_e32 v124, v124
	v_exp_f32_e32 v125, v125
	v_exp_f32_e32 v126, v126
	v_exp_f32_e32 v127, v127
	v_lshlrev_b32_e32 v134, 16, v190
	v_and_b32_e32 v135, 0xffff0000, v190
	v_lshlrev_b32_e32 v140, 16, v191
	v_and_b32_e32 v141, 0xffff0000, v191
	v_add_f32_e32 v124, 1.0, v124
	v_add_f32_e32 v125, 1.0, v125
	v_add_f32_e32 v126, 1.0, v126
	v_add_f32_e32 v127, 1.0, v127
	v_rcp_f32_e32 v124, v124
	v_rcp_f32_e32 v125, v125
	v_rcp_f32_e32 v126, v126
	v_rcp_f32_e32 v127, v127
	s_nop 0
	v_pk_mul_f32 v[124:125], v[124:125], v[134:135]
	v_pk_mul_f32 v[126:127], v[126:127], v[140:141]
	v_cvt_pk_bf16_f32 v134, v124, v125
	v_cvt_pk_bf16_f32 v135, v126, v127
	global_store_dwordx2 v239, v[134:135], s[96:97]
	s_waitcnt vmcnt(31)
	v_pk_add_f32 v[120:121], v[120:121], v[244:245]
	v_pk_add_f32 v[122:123], v[122:123], v[246:247]
	v_mul_f32_e32 v120, 0xbfb8aa3b, v120
	v_mul_f32_e32 v121, 0xbfb8aa3b, v121
	v_mul_f32_e32 v122, 0xbfb8aa3b, v122
	v_mul_f32_e32 v123, 0xbfb8aa3b, v123
	v_exp_f32_e32 v120, v120
	v_exp_f32_e32 v121, v121
	v_exp_f32_e32 v122, v122
	v_exp_f32_e32 v123, v123
	v_lshlrev_b32_e32 v134, 16, v192
	v_and_b32_e32 v135, 0xffff0000, v192
	v_lshlrev_b32_e32 v140, 16, v193
	v_and_b32_e32 v141, 0xffff0000, v193
	v_add_f32_e32 v120, 1.0, v120
	v_add_f32_e32 v121, 1.0, v121
	v_add_f32_e32 v122, 1.0, v122
	v_add_f32_e32 v123, 1.0, v123
	v_rcp_f32_e32 v120, v120
	v_rcp_f32_e32 v121, v121
	v_rcp_f32_e32 v122, v122
	v_rcp_f32_e32 v123, v123
	s_nop 0
	v_pk_mul_f32 v[120:121], v[120:121], v[134:135]
	v_pk_mul_f32 v[122:123], v[122:123], v[140:141]
	v_cvt_pk_bf16_f32 v134, v120, v121
	v_cvt_pk_bf16_f32 v135, v122, v123
	global_store_dwordx2 v239, v[134:135], s[96:97] offset:32
	s_waitcnt vmcnt(31)
	v_pk_add_f32 v[116:117], v[116:117], v[252:253]
	v_pk_add_f32 v[118:119], v[118:119], v[254:255]
	v_mul_f32_e32 v116, 0xbfb8aa3b, v116
	v_mul_f32_e32 v117, 0xbfb8aa3b, v117
	v_mul_f32_e32 v118, 0xbfb8aa3b, v118
	v_mul_f32_e32 v119, 0xbfb8aa3b, v119
	v_exp_f32_e32 v116, v116
	v_exp_f32_e32 v117, v117
	v_exp_f32_e32 v118, v118
	v_exp_f32_e32 v119, v119
	v_lshlrev_b32_e32 v134, 16, v194
	v_and_b32_e32 v135, 0xffff0000, v194
	v_lshlrev_b32_e32 v140, 16, v195
	v_and_b32_e32 v141, 0xffff0000, v195
	v_add_f32_e32 v116, 1.0, v116
	v_add_f32_e32 v117, 1.0, v117
	v_add_f32_e32 v118, 1.0, v118
	v_add_f32_e32 v119, 1.0, v119
	v_rcp_f32_e32 v116, v116
	v_rcp_f32_e32 v117, v117
	v_rcp_f32_e32 v118, v118
	v_rcp_f32_e32 v119, v119
	s_nop 0
	v_pk_mul_f32 v[116:117], v[116:117], v[134:135]
	v_pk_mul_f32 v[118:119], v[118:119], v[140:141]
	v_cvt_pk_bf16_f32 v134, v116, v117
	v_cvt_pk_bf16_f32 v135, v118, v119
	global_store_dwordx2 v239, v[134:135], s[96:97] offset:256
	s_waitcnt vmcnt(31)
	v_pk_add_f32 v[112:113], v[112:113], v[136:137]
	v_pk_add_f32 v[114:115], v[114:115], v[138:139]
	v_mul_f32_e32 v112, 0xbfb8aa3b, v112
	v_mul_f32_e32 v113, 0xbfb8aa3b, v113
	v_mul_f32_e32 v114, 0xbfb8aa3b, v114
	v_mul_f32_e32 v115, 0xbfb8aa3b, v115
	v_exp_f32_e32 v112, v112
	v_exp_f32_e32 v113, v113
	v_exp_f32_e32 v114, v114
	v_exp_f32_e32 v115, v115
	v_lshlrev_b32_e32 v134, 16, v196
	v_and_b32_e32 v135, 0xffff0000, v196
	v_lshlrev_b32_e32 v140, 16, v197
	v_and_b32_e32 v141, 0xffff0000, v197
	v_add_f32_e32 v112, 1.0, v112
	v_add_f32_e32 v113, 1.0, v113
	v_add_f32_e32 v114, 1.0, v114
	v_add_f32_e32 v115, 1.0, v115
	v_rcp_f32_e32 v112, v112
	v_rcp_f32_e32 v113, v113
	v_rcp_f32_e32 v114, v114
	v_rcp_f32_e32 v115, v115
	s_nop 0
	v_pk_mul_f32 v[112:113], v[112:113], v[134:135]
	v_pk_mul_f32 v[114:115], v[114:115], v[140:141]
	v_cvt_pk_bf16_f32 v134, v112, v113
	v_cvt_pk_bf16_f32 v135, v114, v115
	global_store_dwordx2 v239, v[134:135], s[96:97] offset:288
	v_add_u32_e32 v239, 0x8000, v239
	s_waitcnt vmcnt(31)
	v_pk_add_f32 v[108:109], v[108:109], v[240:241]
	v_pk_add_f32 v[110:111], v[110:111], v[242:243]
	v_mul_f32_e32 v108, 0xbfb8aa3b, v108
	v_mul_f32_e32 v109, 0xbfb8aa3b, v109
	v_mul_f32_e32 v110, 0xbfb8aa3b, v110
	v_mul_f32_e32 v111, 0xbfb8aa3b, v111
	v_exp_f32_e32 v108, v108
	v_exp_f32_e32 v109, v109
	v_exp_f32_e32 v110, v110
	v_exp_f32_e32 v111, v111
	v_lshlrev_b32_e32 v134, 16, v198
	v_and_b32_e32 v135, 0xffff0000, v198
	v_lshlrev_b32_e32 v140, 16, v199
	v_and_b32_e32 v141, 0xffff0000, v199
	v_add_f32_e32 v108, 1.0, v108
	v_add_f32_e32 v109, 1.0, v109
	v_add_f32_e32 v110, 1.0, v110
	v_add_f32_e32 v111, 1.0, v111
	v_rcp_f32_e32 v108, v108
	v_rcp_f32_e32 v109, v109
	v_rcp_f32_e32 v110, v110
	v_rcp_f32_e32 v111, v111
	s_nop 0
	v_pk_mul_f32 v[108:109], v[108:109], v[134:135]
	v_pk_mul_f32 v[110:111], v[110:111], v[140:141]
	v_cvt_pk_bf16_f32 v134, v108, v109
	v_cvt_pk_bf16_f32 v135, v110, v111
	global_store_dwordx2 v239, v[134:135], s[96:97]
	s_waitcnt vmcnt(31)
	v_pk_add_f32 v[104:105], v[104:105], v[244:245]
	v_pk_add_f32 v[106:107], v[106:107], v[246:247]
	v_mul_f32_e32 v104, 0xbfb8aa3b, v104
	v_mul_f32_e32 v105, 0xbfb8aa3b, v105
	v_mul_f32_e32 v106, 0xbfb8aa3b, v106
	v_mul_f32_e32 v107, 0xbfb8aa3b, v107
	v_exp_f32_e32 v104, v104
	v_exp_f32_e32 v105, v105
	v_exp_f32_e32 v106, v106
	v_exp_f32_e32 v107, v107
	v_lshlrev_b32_e32 v134, 16, v200
	v_and_b32_e32 v135, 0xffff0000, v200
	v_lshlrev_b32_e32 v140, 16, v201
	v_and_b32_e32 v141, 0xffff0000, v201
	v_add_f32_e32 v104, 1.0, v104
	v_add_f32_e32 v105, 1.0, v105
	v_add_f32_e32 v106, 1.0, v106
	v_add_f32_e32 v107, 1.0, v107
	v_rcp_f32_e32 v104, v104
	v_rcp_f32_e32 v105, v105
	v_rcp_f32_e32 v106, v106
	v_rcp_f32_e32 v107, v107
	s_nop 0
	v_pk_mul_f32 v[104:105], v[104:105], v[134:135]
	v_pk_mul_f32 v[106:107], v[106:107], v[140:141]
	v_cvt_pk_bf16_f32 v134, v104, v105
	v_cvt_pk_bf16_f32 v135, v106, v107
	global_store_dwordx2 v239, v[134:135], s[96:97] offset:32
	s_waitcnt vmcnt(31)
	v_pk_add_f32 v[100:101], v[100:101], v[252:253]
	v_pk_add_f32 v[102:103], v[102:103], v[254:255]
	v_mul_f32_e32 v100, 0xbfb8aa3b, v100
	v_mul_f32_e32 v101, 0xbfb8aa3b, v101
	v_mul_f32_e32 v102, 0xbfb8aa3b, v102
	v_mul_f32_e32 v103, 0xbfb8aa3b, v103
	v_exp_f32_e32 v100, v100
	v_exp_f32_e32 v101, v101
	v_exp_f32_e32 v102, v102
	v_exp_f32_e32 v103, v103
	v_lshlrev_b32_e32 v134, 16, v202
	v_and_b32_e32 v135, 0xffff0000, v202
	v_lshlrev_b32_e32 v140, 16, v203
	v_and_b32_e32 v141, 0xffff0000, v203
	v_add_f32_e32 v100, 1.0, v100
	v_add_f32_e32 v101, 1.0, v101
	v_add_f32_e32 v102, 1.0, v102
	v_add_f32_e32 v103, 1.0, v103
	v_rcp_f32_e32 v100, v100
	v_rcp_f32_e32 v101, v101
	v_rcp_f32_e32 v102, v102
	v_rcp_f32_e32 v103, v103
	s_nop 0
	v_pk_mul_f32 v[100:101], v[100:101], v[134:135]
	v_pk_mul_f32 v[102:103], v[102:103], v[140:141]
	v_cvt_pk_bf16_f32 v134, v100, v101
	v_cvt_pk_bf16_f32 v135, v102, v103
	global_store_dwordx2 v239, v[134:135], s[96:97] offset:256
	s_waitcnt vmcnt(31)
	v_pk_add_f32 v[96:97], v[96:97], v[136:137]
	v_pk_add_f32 v[98:99], v[98:99], v[138:139]
	v_mul_f32_e32 v96, 0xbfb8aa3b, v96
	v_mul_f32_e32 v97, 0xbfb8aa3b, v97
	v_mul_f32_e32 v98, 0xbfb8aa3b, v98
	v_mul_f32_e32 v99, 0xbfb8aa3b, v99
	v_exp_f32_e32 v96, v96
	v_exp_f32_e32 v97, v97
	v_exp_f32_e32 v98, v98
	v_exp_f32_e32 v99, v99
	v_lshlrev_b32_e32 v134, 16, v204
	v_and_b32_e32 v135, 0xffff0000, v204
	v_lshlrev_b32_e32 v140, 16, v205
	v_and_b32_e32 v141, 0xffff0000, v205
	v_add_f32_e32 v96, 1.0, v96
	v_add_f32_e32 v97, 1.0, v97
	v_add_f32_e32 v98, 1.0, v98
	v_add_f32_e32 v99, 1.0, v99
	v_rcp_f32_e32 v96, v96
	v_rcp_f32_e32 v97, v97
	v_rcp_f32_e32 v98, v98
	v_rcp_f32_e32 v99, v99
	s_nop 0
	v_pk_mul_f32 v[96:97], v[96:97], v[134:135]
	v_pk_mul_f32 v[98:99], v[98:99], v[140:141]
	v_cvt_pk_bf16_f32 v134, v96, v97
	v_cvt_pk_bf16_f32 v135, v98, v99
	global_store_dwordx2 v239, v[134:135], s[96:97] offset:288
	v_add_u32_e32 v239, 0x8000, v239
	s_waitcnt vmcnt(31)
	v_pk_add_f32 v[92:93], v[92:93], v[240:241]
	v_pk_add_f32 v[94:95], v[94:95], v[242:243]
	v_mul_f32_e32 v92, 0xbfb8aa3b, v92
	v_mul_f32_e32 v93, 0xbfb8aa3b, v93
	v_mul_f32_e32 v94, 0xbfb8aa3b, v94
	v_mul_f32_e32 v95, 0xbfb8aa3b, v95
	v_exp_f32_e32 v92, v92
	v_exp_f32_e32 v93, v93
	v_exp_f32_e32 v94, v94
	v_exp_f32_e32 v95, v95
	v_lshlrev_b32_e32 v134, 16, v206
	v_and_b32_e32 v135, 0xffff0000, v206
	v_lshlrev_b32_e32 v140, 16, v207
	v_and_b32_e32 v141, 0xffff0000, v207
	v_add_f32_e32 v92, 1.0, v92
	v_add_f32_e32 v93, 1.0, v93
	v_add_f32_e32 v94, 1.0, v94
	v_add_f32_e32 v95, 1.0, v95
	v_rcp_f32_e32 v92, v92
	v_rcp_f32_e32 v93, v93
	v_rcp_f32_e32 v94, v94
	v_rcp_f32_e32 v95, v95
	s_nop 0
	v_pk_mul_f32 v[92:93], v[92:93], v[134:135]
	v_pk_mul_f32 v[94:95], v[94:95], v[140:141]
	v_cvt_pk_bf16_f32 v134, v92, v93
	v_cvt_pk_bf16_f32 v135, v94, v95
	global_store_dwordx2 v239, v[134:135], s[96:97]
	s_waitcnt vmcnt(31)
	v_pk_add_f32 v[88:89], v[88:89], v[244:245]
	v_pk_add_f32 v[90:91], v[90:91], v[246:247]
	v_mul_f32_e32 v88, 0xbfb8aa3b, v88
	v_mul_f32_e32 v89, 0xbfb8aa3b, v89
	v_mul_f32_e32 v90, 0xbfb8aa3b, v90
	v_mul_f32_e32 v91, 0xbfb8aa3b, v91
	v_exp_f32_e32 v88, v88
	v_exp_f32_e32 v89, v89
	v_exp_f32_e32 v90, v90
	v_exp_f32_e32 v91, v91
	v_lshlrev_b32_e32 v134, 16, v208
	v_and_b32_e32 v135, 0xffff0000, v208
	v_lshlrev_b32_e32 v140, 16, v209
	v_and_b32_e32 v141, 0xffff0000, v209
	v_add_f32_e32 v88, 1.0, v88
	v_add_f32_e32 v89, 1.0, v89
	v_add_f32_e32 v90, 1.0, v90
	v_add_f32_e32 v91, 1.0, v91
	v_rcp_f32_e32 v88, v88
	v_rcp_f32_e32 v89, v89
	v_rcp_f32_e32 v90, v90
	v_rcp_f32_e32 v91, v91
	s_nop 0
	v_pk_mul_f32 v[88:89], v[88:89], v[134:135]
	v_pk_mul_f32 v[90:91], v[90:91], v[140:141]
	v_cvt_pk_bf16_f32 v134, v88, v89
	v_cvt_pk_bf16_f32 v135, v90, v91
	global_store_dwordx2 v239, v[134:135], s[96:97] offset:32
	s_waitcnt vmcnt(31)
	v_pk_add_f32 v[84:85], v[84:85], v[252:253]
	v_pk_add_f32 v[86:87], v[86:87], v[254:255]
	v_mul_f32_e32 v84, 0xbfb8aa3b, v84
	v_mul_f32_e32 v85, 0xbfb8aa3b, v85
	v_mul_f32_e32 v86, 0xbfb8aa3b, v86
	v_mul_f32_e32 v87, 0xbfb8aa3b, v87
	v_exp_f32_e32 v84, v84
	v_exp_f32_e32 v85, v85
	v_exp_f32_e32 v86, v86
	v_exp_f32_e32 v87, v87
	v_lshlrev_b32_e32 v134, 16, v210
	v_and_b32_e32 v135, 0xffff0000, v210
	v_lshlrev_b32_e32 v140, 16, v211
	v_and_b32_e32 v141, 0xffff0000, v211
	v_add_f32_e32 v84, 1.0, v84
	v_add_f32_e32 v85, 1.0, v85
	v_add_f32_e32 v86, 1.0, v86
	v_add_f32_e32 v87, 1.0, v87
	v_rcp_f32_e32 v84, v84
	v_rcp_f32_e32 v85, v85
	v_rcp_f32_e32 v86, v86
	v_rcp_f32_e32 v87, v87
	s_nop 0
	v_pk_mul_f32 v[84:85], v[84:85], v[134:135]
	v_pk_mul_f32 v[86:87], v[86:87], v[140:141]
	v_cvt_pk_bf16_f32 v134, v84, v85
	v_cvt_pk_bf16_f32 v135, v86, v87
	global_store_dwordx2 v239, v[134:135], s[96:97] offset:256
	s_waitcnt vmcnt(31)
	v_pk_add_f32 v[80:81], v[80:81], v[136:137]
	v_pk_add_f32 v[82:83], v[82:83], v[138:139]
	v_mul_f32_e32 v80, 0xbfb8aa3b, v80
	v_mul_f32_e32 v81, 0xbfb8aa3b, v81
	v_mul_f32_e32 v82, 0xbfb8aa3b, v82
	v_mul_f32_e32 v83, 0xbfb8aa3b, v83
	v_exp_f32_e32 v80, v80
	v_exp_f32_e32 v81, v81
	v_exp_f32_e32 v82, v82
	v_exp_f32_e32 v83, v83
	v_lshlrev_b32_e32 v134, 16, v212
	v_and_b32_e32 v135, 0xffff0000, v212
	v_lshlrev_b32_e32 v140, 16, v213
	v_and_b32_e32 v141, 0xffff0000, v213
	v_add_f32_e32 v80, 1.0, v80
	v_add_f32_e32 v81, 1.0, v81
	v_add_f32_e32 v82, 1.0, v82
	v_add_f32_e32 v83, 1.0, v83
	v_rcp_f32_e32 v80, v80
	v_rcp_f32_e32 v81, v81
	v_rcp_f32_e32 v82, v82
	v_rcp_f32_e32 v83, v83
	s_nop 0
	v_pk_mul_f32 v[80:81], v[80:81], v[134:135]
	v_pk_mul_f32 v[82:83], v[82:83], v[140:141]
	v_cvt_pk_bf16_f32 v134, v80, v81
	v_cvt_pk_bf16_f32 v135, v82, v83
	global_store_dwordx2 v239, v[134:135], s[96:97] offset:288
	v_add_u32_e32 v239, 0x8000, v239
	s_waitcnt vmcnt(31)
	v_pk_add_f32 v[76:77], v[76:77], v[240:241]
	v_pk_add_f32 v[78:79], v[78:79], v[242:243]
	v_mul_f32_e32 v76, 0xbfb8aa3b, v76
	v_mul_f32_e32 v77, 0xbfb8aa3b, v77
	v_mul_f32_e32 v78, 0xbfb8aa3b, v78
	v_mul_f32_e32 v79, 0xbfb8aa3b, v79
	v_exp_f32_e32 v76, v76
	v_exp_f32_e32 v77, v77
	v_exp_f32_e32 v78, v78
	v_exp_f32_e32 v79, v79
	v_lshlrev_b32_e32 v134, 16, v214
	v_and_b32_e32 v135, 0xffff0000, v214
	v_lshlrev_b32_e32 v140, 16, v215
	v_and_b32_e32 v141, 0xffff0000, v215
	v_add_f32_e32 v76, 1.0, v76
	v_add_f32_e32 v77, 1.0, v77
	v_add_f32_e32 v78, 1.0, v78
	v_add_f32_e32 v79, 1.0, v79
	v_rcp_f32_e32 v76, v76
	v_rcp_f32_e32 v77, v77
	v_rcp_f32_e32 v78, v78
	v_rcp_f32_e32 v79, v79
	s_nop 0
	v_pk_mul_f32 v[76:77], v[76:77], v[134:135]
	v_pk_mul_f32 v[78:79], v[78:79], v[140:141]
	v_cvt_pk_bf16_f32 v134, v76, v77
	v_cvt_pk_bf16_f32 v135, v78, v79
	global_store_dwordx2 v239, v[134:135], s[96:97]
	s_waitcnt vmcnt(31)
	v_pk_add_f32 v[72:73], v[72:73], v[244:245]
	v_pk_add_f32 v[74:75], v[74:75], v[246:247]
	v_mul_f32_e32 v72, 0xbfb8aa3b, v72
	v_mul_f32_e32 v73, 0xbfb8aa3b, v73
	v_mul_f32_e32 v74, 0xbfb8aa3b, v74
	v_mul_f32_e32 v75, 0xbfb8aa3b, v75
	v_exp_f32_e32 v72, v72
	v_exp_f32_e32 v73, v73
	v_exp_f32_e32 v74, v74
	v_exp_f32_e32 v75, v75
	v_lshlrev_b32_e32 v134, 16, v216
	v_and_b32_e32 v135, 0xffff0000, v216
	v_lshlrev_b32_e32 v140, 16, v217
	v_and_b32_e32 v141, 0xffff0000, v217
	v_add_f32_e32 v72, 1.0, v72
	v_add_f32_e32 v73, 1.0, v73
	v_add_f32_e32 v74, 1.0, v74
	v_add_f32_e32 v75, 1.0, v75
	v_rcp_f32_e32 v72, v72
	v_rcp_f32_e32 v73, v73
	v_rcp_f32_e32 v74, v74
	v_rcp_f32_e32 v75, v75
	s_nop 0
	v_pk_mul_f32 v[72:73], v[72:73], v[134:135]
	v_pk_mul_f32 v[74:75], v[74:75], v[140:141]
	v_cvt_pk_bf16_f32 v134, v72, v73
	v_cvt_pk_bf16_f32 v135, v74, v75
	global_store_dwordx2 v239, v[134:135], s[96:97] offset:32
	s_waitcnt vmcnt(31)
	v_pk_add_f32 v[68:69], v[68:69], v[252:253]
	v_pk_add_f32 v[70:71], v[70:71], v[254:255]
	v_mul_f32_e32 v68, 0xbfb8aa3b, v68
	v_mul_f32_e32 v69, 0xbfb8aa3b, v69
	v_mul_f32_e32 v70, 0xbfb8aa3b, v70
	v_mul_f32_e32 v71, 0xbfb8aa3b, v71
	v_exp_f32_e32 v68, v68
	v_exp_f32_e32 v69, v69
	v_exp_f32_e32 v70, v70
	v_exp_f32_e32 v71, v71
	v_lshlrev_b32_e32 v134, 16, v218
	v_and_b32_e32 v135, 0xffff0000, v218
	v_lshlrev_b32_e32 v140, 16, v219
	v_and_b32_e32 v141, 0xffff0000, v219
	v_add_f32_e32 v68, 1.0, v68
	v_add_f32_e32 v69, 1.0, v69
	v_add_f32_e32 v70, 1.0, v70
	v_add_f32_e32 v71, 1.0, v71
	v_rcp_f32_e32 v68, v68
	v_rcp_f32_e32 v69, v69
	v_rcp_f32_e32 v70, v70
	v_rcp_f32_e32 v71, v71
	s_nop 0
	v_pk_mul_f32 v[68:69], v[68:69], v[134:135]
	v_pk_mul_f32 v[70:71], v[70:71], v[140:141]
	v_cvt_pk_bf16_f32 v134, v68, v69
	v_cvt_pk_bf16_f32 v135, v70, v71
	global_store_dwordx2 v239, v[134:135], s[96:97] offset:256
	s_waitcnt vmcnt(31)
	v_pk_add_f32 v[64:65], v[64:65], v[136:137]
	v_pk_add_f32 v[66:67], v[66:67], v[138:139]
	v_mul_f32_e32 v64, 0xbfb8aa3b, v64
	v_mul_f32_e32 v65, 0xbfb8aa3b, v65
	v_mul_f32_e32 v66, 0xbfb8aa3b, v66
	v_mul_f32_e32 v67, 0xbfb8aa3b, v67
	v_exp_f32_e32 v64, v64
	v_exp_f32_e32 v65, v65
	v_exp_f32_e32 v66, v66
	v_exp_f32_e32 v67, v67
	v_lshlrev_b32_e32 v134, 16, v220
	v_and_b32_e32 v135, 0xffff0000, v220
	v_lshlrev_b32_e32 v140, 16, v221
	v_and_b32_e32 v141, 0xffff0000, v221
	v_add_f32_e32 v64, 1.0, v64
	v_add_f32_e32 v65, 1.0, v65
	v_add_f32_e32 v66, 1.0, v66
	v_add_f32_e32 v67, 1.0, v67
	v_rcp_f32_e32 v64, v64
	v_rcp_f32_e32 v65, v65
	v_rcp_f32_e32 v66, v66
	v_rcp_f32_e32 v67, v67
	s_nop 0
	v_pk_mul_f32 v[64:65], v[64:65], v[134:135]
	v_pk_mul_f32 v[66:67], v[66:67], v[140:141]
	v_cvt_pk_bf16_f32 v134, v64, v65
	v_cvt_pk_bf16_f32 v135, v66, v67
	global_store_dwordx2 v239, v[134:135], s[96:97] offset:288
	v_add_u32_e32 v239, 0x28000, v239
	s_waitcnt vmcnt(31)
	v_pk_add_f32 v[60:61], v[60:61], v[240:241]
	v_pk_add_f32 v[62:63], v[62:63], v[242:243]
	v_mul_f32_e32 v60, 0xbfb8aa3b, v60
	v_mul_f32_e32 v61, 0xbfb8aa3b, v61
	v_mul_f32_e32 v62, 0xbfb8aa3b, v62
	v_mul_f32_e32 v63, 0xbfb8aa3b, v63
	v_exp_f32_e32 v60, v60
	v_exp_f32_e32 v61, v61
	v_exp_f32_e32 v62, v62
	v_exp_f32_e32 v63, v63
	v_lshlrev_b32_e32 v134, 16, v222
	v_and_b32_e32 v135, 0xffff0000, v222
	v_lshlrev_b32_e32 v140, 16, v223
	v_and_b32_e32 v141, 0xffff0000, v223
	v_add_f32_e32 v60, 1.0, v60
	v_add_f32_e32 v61, 1.0, v61
	v_add_f32_e32 v62, 1.0, v62
	v_add_f32_e32 v63, 1.0, v63
	v_rcp_f32_e32 v60, v60
	v_rcp_f32_e32 v61, v61
	v_rcp_f32_e32 v62, v62
	v_rcp_f32_e32 v63, v63
	s_nop 0
	v_pk_mul_f32 v[60:61], v[60:61], v[134:135]
	v_pk_mul_f32 v[62:63], v[62:63], v[140:141]
	v_cvt_pk_bf16_f32 v134, v60, v61
	v_cvt_pk_bf16_f32 v135, v62, v63
	global_store_dwordx2 v239, v[134:135], s[96:97]
	s_waitcnt vmcnt(31)
	v_pk_add_f32 v[56:57], v[56:57], v[244:245]
	v_pk_add_f32 v[58:59], v[58:59], v[246:247]
	v_mul_f32_e32 v56, 0xbfb8aa3b, v56
	v_mul_f32_e32 v57, 0xbfb8aa3b, v57
	v_mul_f32_e32 v58, 0xbfb8aa3b, v58
	v_mul_f32_e32 v59, 0xbfb8aa3b, v59
	v_exp_f32_e32 v56, v56
	v_exp_f32_e32 v57, v57
	v_exp_f32_e32 v58, v58
	v_exp_f32_e32 v59, v59
	v_lshlrev_b32_e32 v134, 16, v146
	v_and_b32_e32 v135, 0xffff0000, v146
	v_lshlrev_b32_e32 v140, 16, v147
	v_and_b32_e32 v141, 0xffff0000, v147
	v_add_f32_e32 v56, 1.0, v56
	v_add_f32_e32 v57, 1.0, v57
	v_add_f32_e32 v58, 1.0, v58
	v_add_f32_e32 v59, 1.0, v59
	v_rcp_f32_e32 v56, v56
	v_rcp_f32_e32 v57, v57
	v_rcp_f32_e32 v58, v58
	v_rcp_f32_e32 v59, v59
	s_nop 0
	v_pk_mul_f32 v[56:57], v[56:57], v[134:135]
	v_pk_mul_f32 v[58:59], v[58:59], v[140:141]
	v_cvt_pk_bf16_f32 v134, v56, v57
	v_cvt_pk_bf16_f32 v135, v58, v59
	global_store_dwordx2 v239, v[134:135], s[96:97] offset:32
	s_waitcnt vmcnt(31)
	v_pk_add_f32 v[52:53], v[52:53], v[252:253]
	v_pk_add_f32 v[54:55], v[54:55], v[254:255]
	v_mul_f32_e32 v52, 0xbfb8aa3b, v52
	v_mul_f32_e32 v53, 0xbfb8aa3b, v53
	v_mul_f32_e32 v54, 0xbfb8aa3b, v54
	v_mul_f32_e32 v55, 0xbfb8aa3b, v55
	v_exp_f32_e32 v52, v52
	v_exp_f32_e32 v53, v53
	v_exp_f32_e32 v54, v54
	v_exp_f32_e32 v55, v55
	v_lshlrev_b32_e32 v134, 16, v148
	v_and_b32_e32 v135, 0xffff0000, v148
	v_lshlrev_b32_e32 v140, 16, v149
	v_and_b32_e32 v141, 0xffff0000, v149
	v_add_f32_e32 v52, 1.0, v52
	v_add_f32_e32 v53, 1.0, v53
	v_add_f32_e32 v54, 1.0, v54
	v_add_f32_e32 v55, 1.0, v55
	v_rcp_f32_e32 v52, v52
	v_rcp_f32_e32 v53, v53
	v_rcp_f32_e32 v54, v54
	v_rcp_f32_e32 v55, v55
	s_nop 0
	v_pk_mul_f32 v[52:53], v[52:53], v[134:135]
	v_pk_mul_f32 v[54:55], v[54:55], v[140:141]
	v_cvt_pk_bf16_f32 v134, v52, v53
	v_cvt_pk_bf16_f32 v135, v54, v55
	global_store_dwordx2 v239, v[134:135], s[96:97] offset:256
	s_waitcnt vmcnt(31)
	v_pk_add_f32 v[48:49], v[48:49], v[136:137]
	v_pk_add_f32 v[50:51], v[50:51], v[138:139]
	v_mul_f32_e32 v48, 0xbfb8aa3b, v48
	v_mul_f32_e32 v49, 0xbfb8aa3b, v49
	v_mul_f32_e32 v50, 0xbfb8aa3b, v50
	v_mul_f32_e32 v51, 0xbfb8aa3b, v51
	v_exp_f32_e32 v48, v48
	v_exp_f32_e32 v49, v49
	v_exp_f32_e32 v50, v50
	v_exp_f32_e32 v51, v51
	v_lshlrev_b32_e32 v134, 16, v150
	v_and_b32_e32 v135, 0xffff0000, v150
	v_lshlrev_b32_e32 v140, 16, v151
	v_and_b32_e32 v141, 0xffff0000, v151
	v_add_f32_e32 v48, 1.0, v48
	v_add_f32_e32 v49, 1.0, v49
	v_add_f32_e32 v50, 1.0, v50
	v_add_f32_e32 v51, 1.0, v51
	v_rcp_f32_e32 v48, v48
	v_rcp_f32_e32 v49, v49
	v_rcp_f32_e32 v50, v50
	v_rcp_f32_e32 v51, v51
	s_nop 0
	v_pk_mul_f32 v[48:49], v[48:49], v[134:135]
	v_pk_mul_f32 v[50:51], v[50:51], v[140:141]
	v_cvt_pk_bf16_f32 v134, v48, v49
	v_cvt_pk_bf16_f32 v135, v50, v51
	global_store_dwordx2 v239, v[134:135], s[96:97] offset:288
	v_add_u32_e32 v239, 0x8000, v239
	s_waitcnt vmcnt(31)
	v_pk_add_f32 v[44:45], v[44:45], v[240:241]
	v_pk_add_f32 v[46:47], v[46:47], v[242:243]
	v_mul_f32_e32 v44, 0xbfb8aa3b, v44
	v_mul_f32_e32 v45, 0xbfb8aa3b, v45
	v_mul_f32_e32 v46, 0xbfb8aa3b, v46
	v_mul_f32_e32 v47, 0xbfb8aa3b, v47
	v_exp_f32_e32 v44, v44
	v_exp_f32_e32 v45, v45
	v_exp_f32_e32 v46, v46
	v_exp_f32_e32 v47, v47
	v_lshlrev_b32_e32 v134, 16, v152
	v_and_b32_e32 v135, 0xffff0000, v152
	v_lshlrev_b32_e32 v140, 16, v153
	v_and_b32_e32 v141, 0xffff0000, v153
	v_add_f32_e32 v44, 1.0, v44
	v_add_f32_e32 v45, 1.0, v45
	v_add_f32_e32 v46, 1.0, v46
	v_add_f32_e32 v47, 1.0, v47
	v_rcp_f32_e32 v44, v44
	v_rcp_f32_e32 v45, v45
	v_rcp_f32_e32 v46, v46
	v_rcp_f32_e32 v47, v47
	s_nop 0
	v_pk_mul_f32 v[44:45], v[44:45], v[134:135]
	v_pk_mul_f32 v[46:47], v[46:47], v[140:141]
	v_cvt_pk_bf16_f32 v134, v44, v45
	v_cvt_pk_bf16_f32 v135, v46, v47
	global_store_dwordx2 v239, v[134:135], s[96:97]
	s_waitcnt vmcnt(31)
	v_pk_add_f32 v[40:41], v[40:41], v[244:245]
	v_pk_add_f32 v[42:43], v[42:43], v[246:247]
	v_mul_f32_e32 v40, 0xbfb8aa3b, v40
	v_mul_f32_e32 v41, 0xbfb8aa3b, v41
	v_mul_f32_e32 v42, 0xbfb8aa3b, v42
	v_mul_f32_e32 v43, 0xbfb8aa3b, v43
	v_exp_f32_e32 v40, v40
	v_exp_f32_e32 v41, v41
	v_exp_f32_e32 v42, v42
	v_exp_f32_e32 v43, v43
	v_lshlrev_b32_e32 v134, 16, v154
	v_and_b32_e32 v135, 0xffff0000, v154
	v_lshlrev_b32_e32 v140, 16, v155
	v_and_b32_e32 v141, 0xffff0000, v155
	v_add_f32_e32 v40, 1.0, v40
	v_add_f32_e32 v41, 1.0, v41
	v_add_f32_e32 v42, 1.0, v42
	v_add_f32_e32 v43, 1.0, v43
	v_rcp_f32_e32 v40, v40
	v_rcp_f32_e32 v41, v41
	v_rcp_f32_e32 v42, v42
	v_rcp_f32_e32 v43, v43
	s_nop 0
	v_pk_mul_f32 v[40:41], v[40:41], v[134:135]
	v_pk_mul_f32 v[42:43], v[42:43], v[140:141]
	v_cvt_pk_bf16_f32 v134, v40, v41
	v_cvt_pk_bf16_f32 v135, v42, v43
	global_store_dwordx2 v239, v[134:135], s[96:97] offset:32
	s_waitcnt vmcnt(31)
	v_pk_add_f32 v[36:37], v[36:37], v[252:253]
	v_pk_add_f32 v[38:39], v[38:39], v[254:255]
	v_mul_f32_e32 v36, 0xbfb8aa3b, v36
	v_mul_f32_e32 v37, 0xbfb8aa3b, v37
	v_mul_f32_e32 v38, 0xbfb8aa3b, v38
	v_mul_f32_e32 v39, 0xbfb8aa3b, v39
	v_exp_f32_e32 v36, v36
	v_exp_f32_e32 v37, v37
	v_exp_f32_e32 v38, v38
	v_exp_f32_e32 v39, v39
	v_lshlrev_b32_e32 v134, 16, v156
	v_and_b32_e32 v135, 0xffff0000, v156
	v_lshlrev_b32_e32 v140, 16, v157
	v_and_b32_e32 v141, 0xffff0000, v157
	v_add_f32_e32 v36, 1.0, v36
	v_add_f32_e32 v37, 1.0, v37
	v_add_f32_e32 v38, 1.0, v38
	v_add_f32_e32 v39, 1.0, v39
	v_rcp_f32_e32 v36, v36
	v_rcp_f32_e32 v37, v37
	v_rcp_f32_e32 v38, v38
	v_rcp_f32_e32 v39, v39
	s_nop 0
	v_pk_mul_f32 v[36:37], v[36:37], v[134:135]
	v_pk_mul_f32 v[38:39], v[38:39], v[140:141]
	v_cvt_pk_bf16_f32 v134, v36, v37
	v_cvt_pk_bf16_f32 v135, v38, v39
	global_store_dwordx2 v239, v[134:135], s[96:97] offset:256
	s_waitcnt vmcnt(31)
	v_pk_add_f32 v[32:33], v[32:33], v[136:137]
	v_pk_add_f32 v[34:35], v[34:35], v[138:139]
	v_mul_f32_e32 v32, 0xbfb8aa3b, v32
	v_mul_f32_e32 v33, 0xbfb8aa3b, v33
	v_mul_f32_e32 v34, 0xbfb8aa3b, v34
	v_mul_f32_e32 v35, 0xbfb8aa3b, v35
	v_exp_f32_e32 v32, v32
	v_exp_f32_e32 v33, v33
	v_exp_f32_e32 v34, v34
	v_exp_f32_e32 v35, v35
	v_lshlrev_b32_e32 v134, 16, v158
	v_and_b32_e32 v135, 0xffff0000, v158
	v_lshlrev_b32_e32 v140, 16, v159
	v_and_b32_e32 v141, 0xffff0000, v159
	v_add_f32_e32 v32, 1.0, v32
	v_add_f32_e32 v33, 1.0, v33
	v_add_f32_e32 v34, 1.0, v34
	v_add_f32_e32 v35, 1.0, v35
	v_rcp_f32_e32 v32, v32
	v_rcp_f32_e32 v33, v33
	v_rcp_f32_e32 v34, v34
	v_rcp_f32_e32 v35, v35
	s_nop 0
	v_pk_mul_f32 v[32:33], v[32:33], v[134:135]
	v_pk_mul_f32 v[34:35], v[34:35], v[140:141]
	v_cvt_pk_bf16_f32 v134, v32, v33
	v_cvt_pk_bf16_f32 v135, v34, v35
	global_store_dwordx2 v239, v[134:135], s[96:97] offset:288
	v_add_u32_e32 v239, 0x8000, v239
	s_waitcnt vmcnt(31)
	v_pk_add_f32 v[28:29], v[28:29], v[240:241]
	v_pk_add_f32 v[30:31], v[30:31], v[242:243]
	v_mul_f32_e32 v28, 0xbfb8aa3b, v28
	v_mul_f32_e32 v29, 0xbfb8aa3b, v29
	v_mul_f32_e32 v30, 0xbfb8aa3b, v30
	v_mul_f32_e32 v31, 0xbfb8aa3b, v31
	v_exp_f32_e32 v28, v28
	v_exp_f32_e32 v29, v29
	v_exp_f32_e32 v30, v30
	v_exp_f32_e32 v31, v31
	v_lshlrev_b32_e32 v134, 16, v160
	v_and_b32_e32 v135, 0xffff0000, v160
	v_lshlrev_b32_e32 v140, 16, v161
	v_and_b32_e32 v141, 0xffff0000, v161
	v_add_f32_e32 v28, 1.0, v28
	v_add_f32_e32 v29, 1.0, v29
	v_add_f32_e32 v30, 1.0, v30
	v_add_f32_e32 v31, 1.0, v31
	v_rcp_f32_e32 v28, v28
	v_rcp_f32_e32 v29, v29
	v_rcp_f32_e32 v30, v30
	v_rcp_f32_e32 v31, v31
	s_nop 0
	v_pk_mul_f32 v[28:29], v[28:29], v[134:135]
	v_pk_mul_f32 v[30:31], v[30:31], v[140:141]
	v_cvt_pk_bf16_f32 v134, v28, v29
	v_cvt_pk_bf16_f32 v135, v30, v31
	global_store_dwordx2 v239, v[134:135], s[96:97]
	s_waitcnt vmcnt(31)
	v_pk_add_f32 v[24:25], v[24:25], v[244:245]
	v_pk_add_f32 v[26:27], v[26:27], v[246:247]
	v_mul_f32_e32 v24, 0xbfb8aa3b, v24
	v_mul_f32_e32 v25, 0xbfb8aa3b, v25
	v_mul_f32_e32 v26, 0xbfb8aa3b, v26
	v_mul_f32_e32 v27, 0xbfb8aa3b, v27
	v_exp_f32_e32 v24, v24
	v_exp_f32_e32 v25, v25
	v_exp_f32_e32 v26, v26
	v_exp_f32_e32 v27, v27
	v_lshlrev_b32_e32 v134, 16, v162
	v_and_b32_e32 v135, 0xffff0000, v162
	v_lshlrev_b32_e32 v140, 16, v163
	v_and_b32_e32 v141, 0xffff0000, v163
	v_add_f32_e32 v24, 1.0, v24
	v_add_f32_e32 v25, 1.0, v25
	v_add_f32_e32 v26, 1.0, v26
	v_add_f32_e32 v27, 1.0, v27
	v_rcp_f32_e32 v24, v24
	v_rcp_f32_e32 v25, v25
	v_rcp_f32_e32 v26, v26
	v_rcp_f32_e32 v27, v27
	s_nop 0
	v_pk_mul_f32 v[24:25], v[24:25], v[134:135]
	v_pk_mul_f32 v[26:27], v[26:27], v[140:141]
	v_cvt_pk_bf16_f32 v134, v24, v25
	v_cvt_pk_bf16_f32 v135, v26, v27
	global_store_dwordx2 v239, v[134:135], s[96:97] offset:32
	s_waitcnt vmcnt(31)
	v_pk_add_f32 v[20:21], v[20:21], v[252:253]
	v_pk_add_f32 v[22:23], v[22:23], v[254:255]
	v_mul_f32_e32 v20, 0xbfb8aa3b, v20
	v_mul_f32_e32 v21, 0xbfb8aa3b, v21
	v_mul_f32_e32 v22, 0xbfb8aa3b, v22
	v_mul_f32_e32 v23, 0xbfb8aa3b, v23
	v_exp_f32_e32 v20, v20
	v_exp_f32_e32 v21, v21
	v_exp_f32_e32 v22, v22
	v_exp_f32_e32 v23, v23
	v_lshlrev_b32_e32 v134, 16, v164
	v_and_b32_e32 v135, 0xffff0000, v164
	v_lshlrev_b32_e32 v140, 16, v165
	v_and_b32_e32 v141, 0xffff0000, v165
	v_add_f32_e32 v20, 1.0, v20
	v_add_f32_e32 v21, 1.0, v21
	v_add_f32_e32 v22, 1.0, v22
	v_add_f32_e32 v23, 1.0, v23
	v_rcp_f32_e32 v20, v20
	v_rcp_f32_e32 v21, v21
	v_rcp_f32_e32 v22, v22
	v_rcp_f32_e32 v23, v23
	s_nop 0
	v_pk_mul_f32 v[20:21], v[20:21], v[134:135]
	v_pk_mul_f32 v[22:23], v[22:23], v[140:141]
	v_cvt_pk_bf16_f32 v134, v20, v21
	v_cvt_pk_bf16_f32 v135, v22, v23
	global_store_dwordx2 v239, v[134:135], s[96:97] offset:256
	s_waitcnt vmcnt(31)
	v_pk_add_f32 v[16:17], v[16:17], v[136:137]
	v_pk_add_f32 v[18:19], v[18:19], v[138:139]
	v_mul_f32_e32 v16, 0xbfb8aa3b, v16
	v_mul_f32_e32 v17, 0xbfb8aa3b, v17
	v_mul_f32_e32 v18, 0xbfb8aa3b, v18
	v_mul_f32_e32 v19, 0xbfb8aa3b, v19
	v_exp_f32_e32 v16, v16
	v_exp_f32_e32 v17, v17
	v_exp_f32_e32 v18, v18
	v_exp_f32_e32 v19, v19
	v_lshlrev_b32_e32 v134, 16, v166
	v_and_b32_e32 v135, 0xffff0000, v166
	v_lshlrev_b32_e32 v140, 16, v167
	v_and_b32_e32 v141, 0xffff0000, v167
	v_add_f32_e32 v16, 1.0, v16
	v_add_f32_e32 v17, 1.0, v17
	v_add_f32_e32 v18, 1.0, v18
	v_add_f32_e32 v19, 1.0, v19
	v_rcp_f32_e32 v16, v16
	v_rcp_f32_e32 v17, v17
	v_rcp_f32_e32 v18, v18
	v_rcp_f32_e32 v19, v19
	s_nop 0
	v_pk_mul_f32 v[16:17], v[16:17], v[134:135]
	v_pk_mul_f32 v[18:19], v[18:19], v[140:141]
	v_cvt_pk_bf16_f32 v134, v16, v17
	v_cvt_pk_bf16_f32 v135, v18, v19
	global_store_dwordx2 v239, v[134:135], s[96:97] offset:288
	v_add_u32_e32 v239, 0x8000, v239
	s_waitcnt vmcnt(31)
	v_pk_add_f32 v[12:13], v[12:13], v[240:241]
	v_pk_add_f32 v[14:15], v[14:15], v[242:243]
	v_mul_f32_e32 v12, 0xbfb8aa3b, v12
	v_mul_f32_e32 v13, 0xbfb8aa3b, v13
	v_mul_f32_e32 v14, 0xbfb8aa3b, v14
	v_mul_f32_e32 v15, 0xbfb8aa3b, v15
	v_exp_f32_e32 v12, v12
	v_exp_f32_e32 v13, v13
	v_exp_f32_e32 v14, v14
	v_exp_f32_e32 v15, v15
	v_lshlrev_b32_e32 v134, 16, v168
	v_and_b32_e32 v135, 0xffff0000, v168
	v_lshlrev_b32_e32 v140, 16, v169
	v_and_b32_e32 v141, 0xffff0000, v169
	v_add_f32_e32 v12, 1.0, v12
	v_add_f32_e32 v13, 1.0, v13
	v_add_f32_e32 v14, 1.0, v14
	v_add_f32_e32 v15, 1.0, v15
	v_rcp_f32_e32 v12, v12
	v_rcp_f32_e32 v13, v13
	v_rcp_f32_e32 v14, v14
	v_rcp_f32_e32 v15, v15
	s_nop 0
	v_pk_mul_f32 v[12:13], v[12:13], v[134:135]
	v_pk_mul_f32 v[14:15], v[14:15], v[140:141]
	v_cvt_pk_bf16_f32 v134, v12, v13
	v_cvt_pk_bf16_f32 v135, v14, v15
	global_store_dwordx2 v239, v[134:135], s[96:97]
	s_waitcnt vmcnt(31)
	v_pk_add_f32 v[8:9], v[8:9], v[244:245]
	v_pk_add_f32 v[10:11], v[10:11], v[246:247]
	v_mul_f32_e32 v8, 0xbfb8aa3b, v8
	v_mul_f32_e32 v9, 0xbfb8aa3b, v9
	v_mul_f32_e32 v10, 0xbfb8aa3b, v10
	v_mul_f32_e32 v11, 0xbfb8aa3b, v11
	v_exp_f32_e32 v8, v8
	v_exp_f32_e32 v9, v9
	v_exp_f32_e32 v10, v10
	v_exp_f32_e32 v11, v11
	v_lshlrev_b32_e32 v134, 16, v170
	v_and_b32_e32 v135, 0xffff0000, v170
	v_lshlrev_b32_e32 v140, 16, v171
	v_and_b32_e32 v141, 0xffff0000, v171
	v_add_f32_e32 v8, 1.0, v8
	v_add_f32_e32 v9, 1.0, v9
	v_add_f32_e32 v10, 1.0, v10
	v_add_f32_e32 v11, 1.0, v11
	v_rcp_f32_e32 v8, v8
	v_rcp_f32_e32 v9, v9
	v_rcp_f32_e32 v10, v10
	v_rcp_f32_e32 v11, v11
	s_nop 0
	v_pk_mul_f32 v[8:9], v[8:9], v[134:135]
	v_pk_mul_f32 v[10:11], v[10:11], v[140:141]
	v_cvt_pk_bf16_f32 v134, v8, v9
	v_cvt_pk_bf16_f32 v135, v10, v11
	global_store_dwordx2 v239, v[134:135], s[96:97] offset:32
	s_waitcnt vmcnt(31)
	v_pk_add_f32 v[4:5], v[4:5], v[252:253]
	v_pk_add_f32 v[6:7], v[6:7], v[254:255]
	v_mul_f32_e32 v4, 0xbfb8aa3b, v4
	v_mul_f32_e32 v5, 0xbfb8aa3b, v5
	v_mul_f32_e32 v6, 0xbfb8aa3b, v6
	v_mul_f32_e32 v7, 0xbfb8aa3b, v7
	v_exp_f32_e32 v4, v4
	v_exp_f32_e32 v5, v5
	v_exp_f32_e32 v6, v6
	v_exp_f32_e32 v7, v7
	v_lshlrev_b32_e32 v134, 16, v172
	v_and_b32_e32 v135, 0xffff0000, v172
	v_lshlrev_b32_e32 v140, 16, v173
	v_and_b32_e32 v141, 0xffff0000, v173
	v_add_f32_e32 v4, 1.0, v4
	v_add_f32_e32 v5, 1.0, v5
	v_add_f32_e32 v6, 1.0, v6
	v_add_f32_e32 v7, 1.0, v7
	v_rcp_f32_e32 v4, v4
	v_rcp_f32_e32 v5, v5
	v_rcp_f32_e32 v6, v6
	v_rcp_f32_e32 v7, v7
	s_nop 0
	v_pk_mul_f32 v[4:5], v[4:5], v[134:135]
	v_pk_mul_f32 v[6:7], v[6:7], v[140:141]
	v_cvt_pk_bf16_f32 v134, v4, v5
	v_cvt_pk_bf16_f32 v135, v6, v7
	global_store_dwordx2 v239, v[134:135], s[96:97] offset:256
	s_waitcnt vmcnt(31)
	v_pk_add_f32 v[0:1], v[0:1], v[136:137]
	v_pk_add_f32 v[2:3], v[2:3], v[138:139]
	v_mul_f32_e32 v0, 0xbfb8aa3b, v0
	v_mul_f32_e32 v1, 0xbfb8aa3b, v1
	v_mul_f32_e32 v2, 0xbfb8aa3b, v2
	v_mul_f32_e32 v3, 0xbfb8aa3b, v3
	v_exp_f32_e32 v0, v0
	v_exp_f32_e32 v1, v1
	v_exp_f32_e32 v2, v2
	v_exp_f32_e32 v3, v3
	v_lshlrev_b32_e32 v134, 16, v174
	v_and_b32_e32 v135, 0xffff0000, v174
	v_lshlrev_b32_e32 v140, 16, v175
	v_and_b32_e32 v141, 0xffff0000, v175
	v_add_f32_e32 v0, 1.0, v0
	v_add_f32_e32 v1, 1.0, v1
	v_add_f32_e32 v2, 1.0, v2
	v_add_f32_e32 v3, 1.0, v3
	v_rcp_f32_e32 v0, v0
	v_rcp_f32_e32 v1, v1
	v_rcp_f32_e32 v2, v2
	v_rcp_f32_e32 v3, v3
	s_nop 0
	v_pk_mul_f32 v[0:1], v[0:1], v[134:135]
	v_pk_mul_f32 v[2:3], v[2:3], v[140:141]
	v_cvt_pk_bf16_f32 v134, v0, v1
	v_cvt_pk_bf16_f32 v135, v2, v3
	global_store_dwordx2 v239, v[134:135], s[96:97] offset:288
	s_and_b64 vcc, exec, s[40:41]
	s_cbranch_vccz .LBB0_925
	s_waitcnt vmcnt(0)
	s_cmpk_gt_u32 s22, 0xff
	s_cbranch_scc1 .LBB0_936
	s_barrier

.Lmrg_fast:
	global_load_dwordx4 v[140:143], v[128:129], off
	global_load_dwordx4 v[136:139], v[128:129], off offset:64
	global_load_dwordx4 v[132:135], v[128:129], off offset:512
	s_nop 0
	global_load_dwordx4 v[128:131], v[128:129], off offset:576
	v_lshl_add_u64 v[246:247], v[172:173], 2, s[2:3]
	v_readfirstlane_b32 s40, v164
	v_readfirstlane_b32 s41, v165
	v_readfirstlane_b32 s42, v168
	v_readfirstlane_b32 s43, v169
	v_readlane_b32 s36, v249, 34
	v_readlane_b32 s37, v249, 35
	global_load_dword v190, v[246:247], off
	global_load_dword v191, v[246:247], off offset:64
	global_load_dword v192, v[246:247], off offset:128
	global_load_dword v193, v[246:247], off offset:192
	global_load_dword v194, v[246:247], off offset:512
	global_load_dword v195, v[246:247], off offset:576
	global_load_dword v196, v[246:247], off offset:640
	global_load_dword v197, v[246:247], off offset:704
	v_lshlrev_b32_e32 v255, 11, v172
	v_lshl_add_u32 v255, v166, 1, v255
	v_subrev_u32_e32 v252, s40, v164
	s_nop 1
	v_mov_b32_e32 v253, v252
	v_mov_b32_e32 v254, 1.0
	s_mov_b32 s45, 0xbfb8aa3b
	s_cmp_eq_u32 s44, 0
	s_cbranch_scc1 .Lmrg_b0
	s_cmp_eq_u32 s44, 3
	s_cbranch_scc1 .Lmrg_b3
	global_load_dwordx4 v[144:147], v252, s[40:41]
	global_load_dwordx4 v[148:151], v252, s[42:43]
	v_add_u32_e32 v252, 0x2000, v252
	global_load_dwordx4 v[152:155], v252, s[40:41]
	global_load_dwordx4 v[208:211], v252, s[42:43]
	v_add_u32_e32 v252, 0x2000, v252
	global_load_dwordx4 v[212:215], v252, s[40:41]
	global_load_dwordx4 v[216:219], v252, s[42:43]
	v_add_u32_e32 v252, 0x2000, v252
	global_load_dwordx4 v[220:223], v252, s[40:41]
	global_load_dwordx4 v[240:243], v252, s[42:43]
	v_add_u32_e32 v252, 0x2000, v252
	s_waitcnt vmcnt(6)
	v_mul_f32_e32 v128, s45, v128
	v_mul_f32_e32 v129, s45, v129
	v_mul_f32_e32 v130, s45, v130
	v_mul_f32_e32 v131, s45, v131
	v_mul_f32_e32 v132, s45, v132
	v_mul_f32_e32 v133, s45, v133
	v_mul_f32_e32 v134, s45, v134
	v_mul_f32_e32 v135, s45, v135
	v_mul_f32_e32 v136, s45, v136
	v_mul_f32_e32 v137, s45, v137
	v_mul_f32_e32 v138, s45, v138
	v_mul_f32_e32 v139, s45, v139
	v_mul_f32_e32 v140, s45, v140
	v_mul_f32_e32 v141, s45, v141
	v_mul_f32_e32 v142, s45, v142
	v_mul_f32_e32 v143, s45, v143
	v_fmamk_f32 v239, v190, 0x3a800000, v228
	v_rsq_f32_e32 v238, v239
	v_lshlrev_b32_e32 v164, 16, v144
	v_and_b32_e32 v165, 0xffff0000, v144
	v_lshlrev_b32_e32 v166, 16, v145
	v_and_b32_e32 v167, 0xffff0000, v145
	v_lshlrev_b32_e32 v168, 16, v146
	v_and_b32_e32 v169, 0xffff0000, v146
	v_lshlrev_b32_e32 v170, 16, v147
	v_and_b32_e32 v171, 0xffff0000, v147
	v_mul_f32_e32 v238, s45, v238
	v_lshlrev_b32_e32 v172, 16, v148
	v_and_b32_e32 v173, 0xffff0000, v148
	v_lshlrev_b32_e32 v174, 16, v149
	v_and_b32_e32 v175, 0xffff0000, v149
	v_lshlrev_b32_e32 v156, 16, v150
	v_and_b32_e32 v157, 0xffff0000, v150
	v_lshlrev_b32_e32 v246, 16, v151
	v_and_b32_e32 v247, 0xffff0000, v151
	v_pk_fma_f32 v[198:199], v[124:125], v[238:239], v[140:141] op_sel_hi:[1,0,1]
	v_pk_fma_f32 v[200:201], v[126:127], v[238:239], v[142:143] op_sel_hi:[1,0,1]
	v_pk_fma_f32 v[202:203], v[120:121], v[238:239], v[136:137] op_sel_hi:[1,0,1]
	v_pk_fma_f32 v[244:245], v[122:123], v[238:239], v[138:139] op_sel_hi:[1,0,1]
	global_load_dwordx4 v[124:127], v252, s[40:41]
	global_load_dwordx4 v[120:123], v252, s[42:43]
	v_add_u32_e32 v252, 0x2000, v252
	v_exp_f32_e32 v198, v198
	v_exp_f32_e32 v199, v199
	v_exp_f32_e32 v200, v200
	v_exp_f32_e32 v201, v201
	v_exp_f32_e32 v202, v202
	v_exp_f32_e32 v203, v203
	v_exp_f32_e32 v244, v244
	v_exp_f32_e32 v245, v245
	v_pk_add_f32 v[198:199], v[198:199], v[254:255] op_sel_hi:[1,0]
	v_pk_add_f32 v[200:201], v[200:201], v[254:255] op_sel_hi:[1,0]
	v_pk_add_f32 v[202:203], v[202:203], v[254:255] op_sel_hi:[1,0]
	v_pk_add_f32 v[244:245], v[244:245], v[254:255] op_sel_hi:[1,0]
	v_rcp_f32_e32 v198, v198
	v_rcp_f32_e32 v199, v199
	v_rcp_f32_e32 v200, v200
	v_rcp_f32_e32 v201, v201
	v_rcp_f32_e32 v202, v202
	v_rcp_f32_e32 v203, v203
	v_rcp_f32_e32 v244, v244
	v_rcp_f32_e32 v245, v245
	v_pk_fma_f32 v[198:199], v[198:199], v[164:165], v[172:173]
	v_pk_fma_f32 v[200:201], v[200:201], v[166:167], v[174:175]
	v_pk_fma_f32 v[202:203], v[202:203], v[168:169], v[156:157]
	v_pk_fma_f32 v[244:245], v[244:245], v[170:171], v[246:247]
	v_cvt_pk_bf16_f32 v164, v198, v199
	v_cvt_pk_bf16_f32 v165, v200, v201
	v_cvt_pk_bf16_f32 v166, v202, v203
	v_cvt_pk_bf16_f32 v167, v244, v245
	global_store_dwordx4 v253, v[164:167], s[42:43]
	s_nop 0
	v_add_u32_e32 v253, 0x2000, v253
	s_waitcnt vmcnt(7)
	v_fmamk_f32 v239, v191, 0x3a800000, v228
	v_rsq_f32_e32 v238, v239
	v_lshlrev_b32_e32 v164, 16, v152
	v_and_b32_e32 v165, 0xffff0000, v152
	v_lshlrev_b32_e32 v166, 16, v153
	v_and_b32_e32 v167, 0xffff0000, v153
	v_lshlrev_b32_e32 v168, 16, v154
	v_and_b32_e32 v169, 0xffff0000, v154
	v_lshlrev_b32_e32 v170, 16, v155
	v_and_b32_e32 v171, 0xffff0000, v155
	v_mul_f32_e32 v238, s45, v238
	v_lshlrev_b32_e32 v172, 16, v208
	v_and_b32_e32 v173, 0xffff0000, v208
	v_lshlrev_b32_e32 v174, 16, v209
	v_and_b32_e32 v175, 0xffff0000, v209
	v_lshlrev_b32_e32 v156, 16, v210
	v_and_b32_e32 v157, 0xffff0000, v210
	v_lshlrev_b32_e32 v246, 16, v211
	v_and_b32_e32 v247, 0xffff0000, v211
	v_pk_fma_f32 v[198:199], v[116:117], v[238:239], v[140:141] op_sel_hi:[1,0,1]
	v_pk_fma_f32 v[200:201], v[118:119], v[238:239], v[142:143] op_sel_hi:[1,0,1]
	v_pk_fma_f32 v[202:203], v[112:113], v[238:239], v[136:137] op_sel_hi:[1,0,1]
	v_pk_fma_f32 v[244:245], v[114:115], v[238:239], v[138:139] op_sel_hi:[1,0,1]
	global_load_dwordx4 v[116:119], v252, s[40:41]
	global_load_dwordx4 v[112:115], v252, s[42:43]
	v_add_u32_e32 v252, 0x2000, v252
	v_exp_f32_e32 v198, v198
	v_exp_f32_e32 v199, v199
	v_exp_f32_e32 v200, v200
	v_exp_f32_e32 v201, v201
	v_exp_f32_e32 v202, v202
	v_exp_f32_e32 v203, v203
	v_exp_f32_e32 v244, v244
	v_exp_f32_e32 v245, v245
	v_pk_add_f32 v[198:199], v[198:199], v[254:255] op_sel_hi:[1,0]
	v_pk_add_f32 v[200:201], v[200:201], v[254:255] op_sel_hi:[1,0]
	v_pk_add_f32 v[202:203], v[202:203], v[254:255] op_sel_hi:[1,0]
	v_pk_add_f32 v[244:245], v[244:245], v[254:255] op_sel_hi:[1,0]
	v_rcp_f32_e32 v198, v198
	v_rcp_f32_e32 v199, v199
	v_rcp_f32_e32 v200, v200
	v_rcp_f32_e32 v201, v201
	v_rcp_f32_e32 v202, v202
	v_rcp_f32_e32 v203, v203
	v_rcp_f32_e32 v244, v244
	v_rcp_f32_e32 v245, v245
	v_pk_fma_f32 v[198:199], v[198:199], v[164:165], v[172:173]
	v_pk_fma_f32 v[200:201], v[200:201], v[166:167], v[174:175]
	v_pk_fma_f32 v[202:203], v[202:203], v[168:169], v[156:157]
	v_pk_fma_f32 v[244:245], v[244:245], v[170:171], v[246:247]
	v_cvt_pk_bf16_f32 v164, v198, v199
	v_cvt_pk_bf16_f32 v165, v200, v201
	v_cvt_pk_bf16_f32 v166, v202, v203
	v_cvt_pk_bf16_f32 v167, v244, v245
	global_store_dwordx4 v253, v[164:167], s[42:43]
	s_nop 0
	v_add_u32_e32 v253, 0x2000, v253
	s_waitcnt vmcnt(8)
	v_fmamk_f32 v239, v192, 0x3a800000, v228
	v_rsq_f32_e32 v238, v239
	v_lshlrev_b32_e32 v164, 16, v212
	v_and_b32_e32 v165, 0xffff0000, v212
	v_lshlrev_b32_e32 v166, 16, v213
	v_and_b32_e32 v167, 0xffff0000, v213
	v_lshlrev_b32_e32 v168, 16, v214
	v_and_b32_e32 v169, 0xffff0000, v214
	v_lshlrev_b32_e32 v170, 16, v215
	v_and_b32_e32 v171, 0xffff0000, v215
	v_mul_f32_e32 v238, s45, v238
	v_lshlrev_b32_e32 v172, 16, v216
	v_and_b32_e32 v173, 0xffff0000, v216
	v_lshlrev_b32_e32 v174, 16, v217
	v_and_b32_e32 v175, 0xffff0000, v217
	v_lshlrev_b32_e32 v156, 16, v218
	v_and_b32_e32 v157, 0xffff0000, v218
	v_lshlrev_b32_e32 v246, 16, v219
	v_and_b32_e32 v247, 0xffff0000, v219
	v_pk_fma_f32 v[198:199], v[108:109], v[238:239], v[140:141] op_sel_hi:[1,0,1]
	v_pk_fma_f32 v[200:201], v[110:111], v[238:239], v[142:143] op_sel_hi:[1,0,1]
	v_pk_fma_f32 v[202:203], v[104:105], v[238:239], v[136:137] op_sel_hi:[1,0,1]
	v_pk_fma_f32 v[244:245], v[106:107], v[238:239], v[138:139] op_sel_hi:[1,0,1]
	global_load_dwordx4 v[108:111], v252, s[40:41]
	global_load_dwordx4 v[104:107], v252, s[42:43]
	v_add_u32_e32 v252, 0x2000, v252
	v_exp_f32_e32 v198, v198
	v_exp_f32_e32 v199, v199
	v_exp_f32_e32 v200, v200
	v_exp_f32_e32 v201, v201
	v_exp_f32_e32 v202, v202
	v_exp_f32_e32 v203, v203
	v_exp_f32_e32 v244, v244
	v_exp_f32_e32 v245, v245
	v_pk_add_f32 v[198:199], v[198:199], v[254:255] op_sel_hi:[1,0]
	v_pk_add_f32 v[200:201], v[200:201], v[254:255] op_sel_hi:[1,0]
	v_pk_add_f32 v[202:203], v[202:203], v[254:255] op_sel_hi:[1,0]
	v_pk_add_f32 v[244:245], v[244:245], v[254:255] op_sel_hi:[1,0]
	v_rcp_f32_e32 v198, v198
	v_rcp_f32_e32 v199, v199
	v_rcp_f32_e32 v200, v200
	v_rcp_f32_e32 v201, v201
	v_rcp_f32_e32 v202, v202
	v_rcp_f32_e32 v203, v203
	v_rcp_f32_e32 v244, v244
	v_rcp_f32_e32 v245, v245
	v_pk_fma_f32 v[198:199], v[198:199], v[164:165], v[172:173]
	v_pk_fma_f32 v[200:201], v[200:201], v[166:167], v[174:175]
	v_pk_fma_f32 v[202:203], v[202:203], v[168:169], v[156:157]
	v_pk_fma_f32 v[244:245], v[244:245], v[170:171], v[246:247]
	v_cvt_pk_bf16_f32 v164, v198, v199
	v_cvt_pk_bf16_f32 v165, v200, v201
	v_cvt_pk_bf16_f32 v166, v202, v203
	v_cvt_pk_bf16_f32 v167, v244, v245
	global_store_dwordx4 v253, v[164:167], s[42:43]
	s_nop 0
	v_add_u32_e32 v253, 0x2000, v253
	s_waitcnt vmcnt(9)
	v_fmamk_f32 v239, v193, 0x3a800000, v228
	v_rsq_f32_e32 v238, v239
	v_lshlrev_b32_e32 v164, 16, v220
	v_and_b32_e32 v165, 0xffff0000, v220
	v_lshlrev_b32_e32 v166, 16, v221
	v_and_b32_e32 v167, 0xffff0000, v221
	v_lshlrev_b32_e32 v168, 16, v222
	v_and_b32_e32 v169, 0xffff0000, v222
	v_lshlrev_b32_e32 v170, 16, v223
	v_and_b32_e32 v171, 0xffff0000, v223
	v_mul_f32_e32 v238, s45, v238
	v_lshlrev_b32_e32 v172, 16, v240
	v_and_b32_e32 v173, 0xffff0000, v240
	v_lshlrev_b32_e32 v174, 16, v241
	v_and_b32_e32 v175, 0xffff0000, v241
	v_lshlrev_b32_e32 v156, 16, v242
	v_and_b32_e32 v157, 0xffff0000, v242
	v_lshlrev_b32_e32 v246, 16, v243
	v_and_b32_e32 v247, 0xffff0000, v243
	v_pk_fma_f32 v[198:199], v[100:101], v[238:239], v[140:141] op_sel_hi:[1,0,1]
	v_pk_fma_f32 v[200:201], v[102:103], v[238:239], v[142:143] op_sel_hi:[1,0,1]
	v_pk_fma_f32 v[202:203], v[96:97], v[238:239], v[136:137] op_sel_hi:[1,0,1]
	v_pk_fma_f32 v[244:245], v[98:99], v[238:239], v[138:139] op_sel_hi:[1,0,1]
	global_load_dwordx4 v[100:103], v252, s[40:41]
	global_load_dwordx4 v[96:99], v252, s[42:43]
	v_add_u32_e32 v252, 0x2000, v252
	v_exp_f32_e32 v198, v198
	v_exp_f32_e32 v199, v199
	v_exp_f32_e32 v200, v200
	v_exp_f32_e32 v201, v201
	v_exp_f32_e32 v202, v202
	v_exp_f32_e32 v203, v203
	v_exp_f32_e32 v244, v244
	v_exp_f32_e32 v245, v245
	v_pk_add_f32 v[198:199], v[198:199], v[254:255] op_sel_hi:[1,0]
	v_pk_add_f32 v[200:201], v[200:201], v[254:255] op_sel_hi:[1,0]
	v_pk_add_f32 v[202:203], v[202:203], v[254:255] op_sel_hi:[1,0]
	v_pk_add_f32 v[244:245], v[244:245], v[254:255] op_sel_hi:[1,0]
	v_rcp_f32_e32 v198, v198
	v_rcp_f32_e32 v199, v199
	v_rcp_f32_e32 v200, v200
	v_rcp_f32_e32 v201, v201
	v_rcp_f32_e32 v202, v202
	v_rcp_f32_e32 v203, v203
	v_rcp_f32_e32 v244, v244
	v_rcp_f32_e32 v245, v245
	v_pk_fma_f32 v[198:199], v[198:199], v[164:165], v[172:173]
	v_pk_fma_f32 v[200:201], v[200:201], v[166:167], v[174:175]
	v_pk_fma_f32 v[202:203], v[202:203], v[168:169], v[156:157]
	v_pk_fma_f32 v[244:245], v[244:245], v[170:171], v[246:247]
	v_cvt_pk_bf16_f32 v164, v198, v199
	v_cvt_pk_bf16_f32 v165, v200, v201
	v_cvt_pk_bf16_f32 v166, v202, v203
	v_cvt_pk_bf16_f32 v167, v244, v245
	global_store_dwordx4 v253, v[164:167], s[42:43]
	s_nop 0
	v_add_u32_e32 v253, 0x2000, v253
	s_waitcnt vmcnt(10)
	v_fmamk_f32 v239, v190, 0x3a800000, v228
	v_rsq_f32_e32 v238, v239
	v_lshlrev_b32_e32 v164, 16, v124
	v_and_b32_e32 v165, 0xffff0000, v124
	v_lshlrev_b32_e32 v166, 16, v125
	v_and_b32_e32 v167, 0xffff0000, v125
	v_lshlrev_b32_e32 v168, 16, v126
	v_and_b32_e32 v169, 0xffff0000, v126
	v_lshlrev_b32_e32 v170, 16, v127
	v_and_b32_e32 v171, 0xffff0000, v127
	v_mul_f32_e32 v238, s45, v238
	v_lshlrev_b32_e32 v172, 16, v120
	v_and_b32_e32 v173, 0xffff0000, v120
	v_lshlrev_b32_e32 v174, 16, v121
	v_and_b32_e32 v175, 0xffff0000, v121
	v_lshlrev_b32_e32 v156, 16, v122
	v_and_b32_e32 v157, 0xffff0000, v122
	v_lshlrev_b32_e32 v246, 16, v123
	v_and_b32_e32 v247, 0xffff0000, v123
	v_pk_fma_f32 v[198:199], v[92:93], v[238:239], v[132:133] op_sel_hi:[1,0,1]
	v_pk_fma_f32 v[200:201], v[94:95], v[238:239], v[134:135] op_sel_hi:[1,0,1]
	v_pk_fma_f32 v[202:203], v[88:89], v[238:239], v[128:129] op_sel_hi:[1,0,1]
	v_pk_fma_f32 v[244:245], v[90:91], v[238:239], v[130:131] op_sel_hi:[1,0,1]
	global_load_dwordx4 v[92:95], v252, s[40:41]
	global_load_dwordx4 v[88:91], v252, s[42:43]
	v_add_u32_e32 v252, 0x2000, v252
	v_exp_f32_e32 v198, v198
	v_exp_f32_e32 v199, v199
	v_exp_f32_e32 v200, v200
	v_exp_f32_e32 v201, v201
	v_exp_f32_e32 v202, v202
	v_exp_f32_e32 v203, v203
	v_exp_f32_e32 v244, v244
	v_exp_f32_e32 v245, v245
	v_pk_add_f32 v[198:199], v[198:199], v[254:255] op_sel_hi:[1,0]
	v_pk_add_f32 v[200:201], v[200:201], v[254:255] op_sel_hi:[1,0]
	v_pk_add_f32 v[202:203], v[202:203], v[254:255] op_sel_hi:[1,0]
	v_pk_add_f32 v[244:245], v[244:245], v[254:255] op_sel_hi:[1,0]
	v_rcp_f32_e32 v198, v198
	v_rcp_f32_e32 v199, v199
	v_rcp_f32_e32 v200, v200
	v_rcp_f32_e32 v201, v201
	v_rcp_f32_e32 v202, v202
	v_rcp_f32_e32 v203, v203
	v_rcp_f32_e32 v244, v244
	v_rcp_f32_e32 v245, v245
	v_pk_fma_f32 v[198:199], v[198:199], v[164:165], v[172:173]
	v_pk_fma_f32 v[200:201], v[200:201], v[166:167], v[174:175]
	v_pk_fma_f32 v[202:203], v[202:203], v[168:169], v[156:157]
	v_pk_fma_f32 v[244:245], v[244:245], v[170:171], v[246:247]
	v_cvt_pk_bf16_f32 v164, v198, v199
	v_cvt_pk_bf16_f32 v165, v200, v201
	v_cvt_pk_bf16_f32 v166, v202, v203
	v_cvt_pk_bf16_f32 v167, v244, v245
	global_store_dwordx4 v253, v[164:167], s[42:43]
	s_nop 0
	v_add_u32_e32 v253, 0x2000, v253
	s_waitcnt vmcnt(10)
	v_fmamk_f32 v239, v191, 0x3a800000, v228
	v_rsq_f32_e32 v238, v239
	v_lshlrev_b32_e32 v164, 16, v116
	v_and_b32_e32 v165, 0xffff0000, v116
	v_lshlrev_b32_e32 v166, 16, v117
	v_and_b32_e32 v167, 0xffff0000, v117
	v_lshlrev_b32_e32 v168, 16, v118
	v_and_b32_e32 v169, 0xffff0000, v118
	v_lshlrev_b32_e32 v170, 16, v119
	v_and_b32_e32 v171, 0xffff0000, v119
	v_mul_f32_e32 v238, s45, v238
	v_lshlrev_b32_e32 v172, 16, v112
	v_and_b32_e32 v173, 0xffff0000, v112
	v_lshlrev_b32_e32 v174, 16, v113
	v_and_b32_e32 v175, 0xffff0000, v113
	v_lshlrev_b32_e32 v156, 16, v114
	v_and_b32_e32 v157, 0xffff0000, v114
	v_lshlrev_b32_e32 v246, 16, v115
	v_and_b32_e32 v247, 0xffff0000, v115
	v_pk_fma_f32 v[198:199], v[84:85], v[238:239], v[132:133] op_sel_hi:[1,0,1]
	v_pk_fma_f32 v[200:201], v[86:87], v[238:239], v[134:135] op_sel_hi:[1,0,1]
	v_pk_fma_f32 v[202:203], v[80:81], v[238:239], v[128:129] op_sel_hi:[1,0,1]
	v_pk_fma_f32 v[244:245], v[82:83], v[238:239], v[130:131] op_sel_hi:[1,0,1]
	global_load_dwordx4 v[84:87], v252, s[40:41]
	global_load_dwordx4 v[80:83], v252, s[42:43]
	v_add_u32_e32 v252, 0x2000, v252
	v_exp_f32_e32 v198, v198
	v_exp_f32_e32 v199, v199
	v_exp_f32_e32 v200, v200
	v_exp_f32_e32 v201, v201
	v_exp_f32_e32 v202, v202
	v_exp_f32_e32 v203, v203
	v_exp_f32_e32 v244, v244
	v_exp_f32_e32 v245, v245
	v_pk_add_f32 v[198:199], v[198:199], v[254:255] op_sel_hi:[1,0]
	v_pk_add_f32 v[200:201], v[200:201], v[254:255] op_sel_hi:[1,0]
	v_pk_add_f32 v[202:203], v[202:203], v[254:255] op_sel_hi:[1,0]
	v_pk_add_f32 v[244:245], v[244:245], v[254:255] op_sel_hi:[1,0]
	v_rcp_f32_e32 v198, v198
	v_rcp_f32_e32 v199, v199
	v_rcp_f32_e32 v200, v200
	v_rcp_f32_e32 v201, v201
	v_rcp_f32_e32 v202, v202
	v_rcp_f32_e32 v203, v203
	v_rcp_f32_e32 v244, v244
	v_rcp_f32_e32 v245, v245
	v_pk_fma_f32 v[198:199], v[198:199], v[164:165], v[172:173]
	v_pk_fma_f32 v[200:201], v[200:201], v[166:167], v[174:175]
	v_pk_fma_f32 v[202:203], v[202:203], v[168:169], v[156:157]
	v_pk_fma_f32 v[244:245], v[244:245], v[170:171], v[246:247]
	v_cvt_pk_bf16_f32 v164, v198, v199
	v_cvt_pk_bf16_f32 v165, v200, v201
	v_cvt_pk_bf16_f32 v166, v202, v203
	v_cvt_pk_bf16_f32 v167, v244, v245
	global_store_dwordx4 v253, v[164:167], s[42:43]
	s_nop 0
	v_add_u32_e32 v253, 0x2000, v253
	s_waitcnt vmcnt(10)
	v_fmamk_f32 v239, v192, 0x3a800000, v228
	v_rsq_f32_e32 v238, v239
	v_lshlrev_b32_e32 v164, 16, v108
	v_and_b32_e32 v165, 0xffff0000, v108
	v_lshlrev_b32_e32 v166, 16, v109
	v_and_b32_e32 v167, 0xffff0000, v109
	v_lshlrev_b32_e32 v168, 16, v110
	v_and_b32_e32 v169, 0xffff0000, v110
	v_lshlrev_b32_e32 v170, 16, v111
	v_and_b32_e32 v171, 0xffff0000, v111
	v_mul_f32_e32 v238, s45, v238
	v_lshlrev_b32_e32 v172, 16, v104
	v_and_b32_e32 v173, 0xffff0000, v104
	v_lshlrev_b32_e32 v174, 16, v105
	v_and_b32_e32 v175, 0xffff0000, v105
	v_lshlrev_b32_e32 v156, 16, v106
	v_and_b32_e32 v157, 0xffff0000, v106
	v_lshlrev_b32_e32 v246, 16, v107
	v_and_b32_e32 v247, 0xffff0000, v107
	v_pk_fma_f32 v[198:199], v[76:77], v[238:239], v[132:133] op_sel_hi:[1,0,1]
	v_pk_fma_f32 v[200:201], v[78:79], v[238:239], v[134:135] op_sel_hi:[1,0,1]
	v_pk_fma_f32 v[202:203], v[72:73], v[238:239], v[128:129] op_sel_hi:[1,0,1]
	v_pk_fma_f32 v[244:245], v[74:75], v[238:239], v[130:131] op_sel_hi:[1,0,1]
	global_load_dwordx4 v[76:79], v252, s[40:41]
	global_load_dwordx4 v[72:75], v252, s[42:43]
	v_add_u32_e32 v252, 0x2000, v252
	v_exp_f32_e32 v198, v198
	v_exp_f32_e32 v199, v199
	v_exp_f32_e32 v200, v200
	v_exp_f32_e32 v201, v201
	v_exp_f32_e32 v202, v202
	v_exp_f32_e32 v203, v203
	v_exp_f32_e32 v244, v244
	v_exp_f32_e32 v245, v245
	v_pk_add_f32 v[198:199], v[198:199], v[254:255] op_sel_hi:[1,0]
	v_pk_add_f32 v[200:201], v[200:201], v[254:255] op_sel_hi:[1,0]
	v_pk_add_f32 v[202:203], v[202:203], v[254:255] op_sel_hi:[1,0]
	v_pk_add_f32 v[244:245], v[244:245], v[254:255] op_sel_hi:[1,0]
	v_rcp_f32_e32 v198, v198
	v_rcp_f32_e32 v199, v199
	v_rcp_f32_e32 v200, v200
	v_rcp_f32_e32 v201, v201
	v_rcp_f32_e32 v202, v202
	v_rcp_f32_e32 v203, v203
	v_rcp_f32_e32 v244, v244
	v_rcp_f32_e32 v245, v245
	v_pk_fma_f32 v[198:199], v[198:199], v[164:165], v[172:173]
	v_pk_fma_f32 v[200:201], v[200:201], v[166:167], v[174:175]
	v_pk_fma_f32 v[202:203], v[202:203], v[168:169], v[156:157]
	v_pk_fma_f32 v[244:245], v[244:245], v[170:171], v[246:247]
	v_cvt_pk_bf16_f32 v164, v198, v199
	v_cvt_pk_bf16_f32 v165, v200, v201
	v_cvt_pk_bf16_f32 v166, v202, v203
	v_cvt_pk_bf16_f32 v167, v244, v245
	global_store_dwordx4 v253, v[164:167], s[42:43]
	s_nop 0
	v_add_u32_e32 v253, 0x2000, v253
	s_waitcnt vmcnt(10)
	v_fmamk_f32 v239, v193, 0x3a800000, v228
	v_rsq_f32_e32 v238, v239
	v_lshlrev_b32_e32 v164, 16, v100
	v_and_b32_e32 v165, 0xffff0000, v100
	v_lshlrev_b32_e32 v166, 16, v101
	v_and_b32_e32 v167, 0xffff0000, v101
	v_lshlrev_b32_e32 v168, 16, v102
	v_and_b32_e32 v169, 0xffff0000, v102
	v_lshlrev_b32_e32 v170, 16, v103
	v_and_b32_e32 v171, 0xffff0000, v103
	v_mul_f32_e32 v238, s45, v238
	v_lshlrev_b32_e32 v172, 16, v96
	v_and_b32_e32 v173, 0xffff0000, v96
	v_lshlrev_b32_e32 v174, 16, v97
	v_and_b32_e32 v175, 0xffff0000, v97
	v_lshlrev_b32_e32 v156, 16, v98
	v_and_b32_e32 v157, 0xffff0000, v98
	v_lshlrev_b32_e32 v246, 16, v99
	v_and_b32_e32 v247, 0xffff0000, v99
	v_pk_fma_f32 v[198:199], v[68:69], v[238:239], v[132:133] op_sel_hi:[1,0,1]
	v_pk_fma_f32 v[200:201], v[70:71], v[238:239], v[134:135] op_sel_hi:[1,0,1]
	v_pk_fma_f32 v[202:203], v[64:65], v[238:239], v[128:129] op_sel_hi:[1,0,1]
	v_pk_fma_f32 v[244:245], v[66:67], v[238:239], v[130:131] op_sel_hi:[1,0,1]
	global_load_dwordx4 v[68:71], v252, s[40:41]
	global_load_dwordx4 v[64:67], v252, s[42:43]
	v_add_u32_e32 v252, 0x2000, v252
	v_exp_f32_e32 v198, v198
	v_exp_f32_e32 v199, v199
	v_exp_f32_e32 v200, v200
	v_exp_f32_e32 v201, v201
	v_exp_f32_e32 v202, v202
	v_exp_f32_e32 v203, v203
	v_exp_f32_e32 v244, v244
	v_exp_f32_e32 v245, v245
	v_pk_add_f32 v[198:199], v[198:199], v[254:255] op_sel_hi:[1,0]
	v_pk_add_f32 v[200:201], v[200:201], v[254:255] op_sel_hi:[1,0]
	v_pk_add_f32 v[202:203], v[202:203], v[254:255] op_sel_hi:[1,0]
	v_pk_add_f32 v[244:245], v[244:245], v[254:255] op_sel_hi:[1,0]
	v_rcp_f32_e32 v198, v198
	v_rcp_f32_e32 v199, v199
	v_rcp_f32_e32 v200, v200
	v_rcp_f32_e32 v201, v201
	v_rcp_f32_e32 v202, v202
	v_rcp_f32_e32 v203, v203
	v_rcp_f32_e32 v244, v244
	v_rcp_f32_e32 v245, v245
	v_pk_fma_f32 v[198:199], v[198:199], v[164:165], v[172:173]
	v_pk_fma_f32 v[200:201], v[200:201], v[166:167], v[174:175]
	v_pk_fma_f32 v[202:203], v[202:203], v[168:169], v[156:157]
	v_pk_fma_f32 v[244:245], v[244:245], v[170:171], v[246:247]
	v_cvt_pk_bf16_f32 v164, v198, v199
	v_cvt_pk_bf16_f32 v165, v200, v201
	v_cvt_pk_bf16_f32 v166, v202, v203
	v_cvt_pk_bf16_f32 v167, v244, v245
	global_store_dwordx4 v253, v[164:167], s[42:43]
	s_nop 0
	v_add_u32_e32 v253, 0x2000, v253
	s_waitcnt vmcnt(10)
	v_fmamk_f32 v239, v194, 0x3a800000, v228
	v_rsq_f32_e32 v238, v239
	v_lshlrev_b32_e32 v164, 16, v92
	v_and_b32_e32 v165, 0xffff0000, v92
	v_lshlrev_b32_e32 v166, 16, v93
	v_and_b32_e32 v167, 0xffff0000, v93
	v_lshlrev_b32_e32 v168, 16, v94
	v_and_b32_e32 v169, 0xffff0000, v94
	v_lshlrev_b32_e32 v170, 16, v95
	v_and_b32_e32 v171, 0xffff0000, v95
	v_mul_f32_e32 v238, s45, v238
	v_lshlrev_b32_e32 v172, 16, v88
	v_and_b32_e32 v173, 0xffff0000, v88
	v_lshlrev_b32_e32 v174, 16, v89
	v_and_b32_e32 v175, 0xffff0000, v89
	v_lshlrev_b32_e32 v156, 16, v90
	v_and_b32_e32 v157, 0xffff0000, v90
	v_lshlrev_b32_e32 v246, 16, v91
	v_and_b32_e32 v247, 0xffff0000, v91
	v_pk_fma_f32 v[198:199], v[60:61], v[238:239], v[140:141] op_sel_hi:[1,0,1]
	v_pk_fma_f32 v[200:201], v[62:63], v[238:239], v[142:143] op_sel_hi:[1,0,1]
	v_pk_fma_f32 v[202:203], v[56:57], v[238:239], v[136:137] op_sel_hi:[1,0,1]
	v_pk_fma_f32 v[244:245], v[58:59], v[238:239], v[138:139] op_sel_hi:[1,0,1]
	global_load_dwordx4 v[60:63], v252, s[40:41]
	global_load_dwordx4 v[56:59], v252, s[42:43]
	v_add_u32_e32 v252, 0x2000, v252
	v_exp_f32_e32 v198, v198
	v_exp_f32_e32 v199, v199
	v_exp_f32_e32 v200, v200
	v_exp_f32_e32 v201, v201
	v_exp_f32_e32 v202, v202
	v_exp_f32_e32 v203, v203
	v_exp_f32_e32 v244, v244
	v_exp_f32_e32 v245, v245
	v_pk_add_f32 v[198:199], v[198:199], v[254:255] op_sel_hi:[1,0]
	v_pk_add_f32 v[200:201], v[200:201], v[254:255] op_sel_hi:[1,0]
	v_pk_add_f32 v[202:203], v[202:203], v[254:255] op_sel_hi:[1,0]
	v_pk_add_f32 v[244:245], v[244:245], v[254:255] op_sel_hi:[1,0]
	v_rcp_f32_e32 v198, v198
	v_rcp_f32_e32 v199, v199
	v_rcp_f32_e32 v200, v200
	v_rcp_f32_e32 v201, v201
	v_rcp_f32_e32 v202, v202
	v_rcp_f32_e32 v203, v203
	v_rcp_f32_e32 v244, v244
	v_rcp_f32_e32 v245, v245
	v_pk_fma_f32 v[198:199], v[198:199], v[164:165], v[172:173]
	v_pk_fma_f32 v[200:201], v[200:201], v[166:167], v[174:175]
	v_pk_fma_f32 v[202:203], v[202:203], v[168:169], v[156:157]
	v_pk_fma_f32 v[244:245], v[244:245], v[170:171], v[246:247]
	v_cvt_pk_bf16_f32 v164, v198, v199
	v_cvt_pk_bf16_f32 v165, v200, v201
	v_cvt_pk_bf16_f32 v166, v202, v203
	v_cvt_pk_bf16_f32 v167, v244, v245
	global_store_dwordx4 v253, v[164:167], s[42:43]
	s_nop 0
	v_add_u32_e32 v253, 0x2000, v253
	s_waitcnt vmcnt(10)
	v_fmamk_f32 v239, v195, 0x3a800000, v228
	v_rsq_f32_e32 v238, v239
	v_lshlrev_b32_e32 v164, 16, v84
	v_and_b32_e32 v165, 0xffff0000, v84
	v_lshlrev_b32_e32 v166, 16, v85
	v_and_b32_e32 v167, 0xffff0000, v85
	v_lshlrev_b32_e32 v168, 16, v86
	v_and_b32_e32 v169, 0xffff0000, v86
	v_lshlrev_b32_e32 v170, 16, v87
	v_and_b32_e32 v171, 0xffff0000, v87
	v_mul_f32_e32 v238, s45, v238
	v_lshlrev_b32_e32 v172, 16, v80
	v_and_b32_e32 v173, 0xffff0000, v80
	v_lshlrev_b32_e32 v174, 16, v81
	v_and_b32_e32 v175, 0xffff0000, v81
	v_lshlrev_b32_e32 v156, 16, v82
	v_and_b32_e32 v157, 0xffff0000, v82
	v_lshlrev_b32_e32 v246, 16, v83
	v_and_b32_e32 v247, 0xffff0000, v83
	v_pk_fma_f32 v[198:199], v[52:53], v[238:239], v[140:141] op_sel_hi:[1,0,1]
	v_pk_fma_f32 v[200:201], v[54:55], v[238:239], v[142:143] op_sel_hi:[1,0,1]
	v_pk_fma_f32 v[202:203], v[48:49], v[238:239], v[136:137] op_sel_hi:[1,0,1]
	v_pk_fma_f32 v[244:245], v[50:51], v[238:239], v[138:139] op_sel_hi:[1,0,1]
	global_load_dwordx4 v[52:55], v252, s[40:41]
	global_load_dwordx4 v[48:51], v252, s[42:43]
	v_add_u32_e32 v252, 0x2000, v252
	v_exp_f32_e32 v198, v198
	v_exp_f32_e32 v199, v199
	v_exp_f32_e32 v200, v200
	v_exp_f32_e32 v201, v201
	v_exp_f32_e32 v202, v202
	v_exp_f32_e32 v203, v203
	v_exp_f32_e32 v244, v244
	v_exp_f32_e32 v245, v245
	v_pk_add_f32 v[198:199], v[198:199], v[254:255] op_sel_hi:[1,0]
	v_pk_add_f32 v[200:201], v[200:201], v[254:255] op_sel_hi:[1,0]
	v_pk_add_f32 v[202:203], v[202:203], v[254:255] op_sel_hi:[1,0]
	v_pk_add_f32 v[244:245], v[244:245], v[254:255] op_sel_hi:[1,0]
	v_rcp_f32_e32 v198, v198
	v_rcp_f32_e32 v199, v199
	v_rcp_f32_e32 v200, v200
	v_rcp_f32_e32 v201, v201
	v_rcp_f32_e32 v202, v202
	v_rcp_f32_e32 v203, v203
	v_rcp_f32_e32 v244, v244
	v_rcp_f32_e32 v245, v245
	v_pk_fma_f32 v[198:199], v[198:199], v[164:165], v[172:173]
	v_pk_fma_f32 v[200:201], v[200:201], v[166:167], v[174:175]
	v_pk_fma_f32 v[202:203], v[202:203], v[168:169], v[156:157]
	v_pk_fma_f32 v[244:245], v[244:245], v[170:171], v[246:247]
	v_cvt_pk_bf16_f32 v164, v198, v199
	v_cvt_pk_bf16_f32 v165, v200, v201
	v_cvt_pk_bf16_f32 v166, v202, v203
	v_cvt_pk_bf16_f32 v167, v244, v245
	global_store_dwordx4 v253, v[164:167], s[42:43]
	s_nop 0
	v_add_u32_e32 v253, 0x2000, v253
	s_waitcnt vmcnt(10)
	v_fmamk_f32 v239, v196, 0x3a800000, v228
	v_rsq_f32_e32 v238, v239
	v_lshlrev_b32_e32 v164, 16, v76
	v_and_b32_e32 v165, 0xffff0000, v76
	v_lshlrev_b32_e32 v166, 16, v77
	v_and_b32_e32 v167, 0xffff0000, v77
	v_lshlrev_b32_e32 v168, 16, v78
	v_and_b32_e32 v169, 0xffff0000, v78
	v_lshlrev_b32_e32 v170, 16, v79
	v_and_b32_e32 v171, 0xffff0000, v79
	v_mul_f32_e32 v238, s45, v238
	v_lshlrev_b32_e32 v172, 16, v72
	v_and_b32_e32 v173, 0xffff0000, v72
	v_lshlrev_b32_e32 v174, 16, v73
	v_and_b32_e32 v175, 0xffff0000, v73
	v_lshlrev_b32_e32 v156, 16, v74
	v_and_b32_e32 v157, 0xffff0000, v74
	v_lshlrev_b32_e32 v246, 16, v75
	v_and_b32_e32 v247, 0xffff0000, v75
	v_pk_fma_f32 v[198:199], v[44:45], v[238:239], v[140:141] op_sel_hi:[1,0,1]
	v_pk_fma_f32 v[200:201], v[46:47], v[238:239], v[142:143] op_sel_hi:[1,0,1]
	v_pk_fma_f32 v[202:203], v[40:41], v[238:239], v[136:137] op_sel_hi:[1,0,1]
	v_pk_fma_f32 v[244:245], v[42:43], v[238:239], v[138:139] op_sel_hi:[1,0,1]
	global_load_dwordx4 v[44:47], v252, s[40:41]
	global_load_dwordx4 v[40:43], v252, s[42:43]
	v_add_u32_e32 v252, 0x2000, v252
	v_exp_f32_e32 v198, v198
	v_exp_f32_e32 v199, v199
	v_exp_f32_e32 v200, v200
	v_exp_f32_e32 v201, v201
	v_exp_f32_e32 v202, v202
	v_exp_f32_e32 v203, v203
	v_exp_f32_e32 v244, v244
	v_exp_f32_e32 v245, v245
	v_pk_add_f32 v[198:199], v[198:199], v[254:255] op_sel_hi:[1,0]
	v_pk_add_f32 v[200:201], v[200:201], v[254:255] op_sel_hi:[1,0]
	v_pk_add_f32 v[202:203], v[202:203], v[254:255] op_sel_hi:[1,0]
	v_pk_add_f32 v[244:245], v[244:245], v[254:255] op_sel_hi:[1,0]
	v_rcp_f32_e32 v198, v198
	v_rcp_f32_e32 v199, v199
	v_rcp_f32_e32 v200, v200
	v_rcp_f32_e32 v201, v201
	v_rcp_f32_e32 v202, v202
	v_rcp_f32_e32 v203, v203
	v_rcp_f32_e32 v244, v244
	v_rcp_f32_e32 v245, v245
	v_pk_fma_f32 v[198:199], v[198:199], v[164:165], v[172:173]
	v_pk_fma_f32 v[200:201], v[200:201], v[166:167], v[174:175]
	v_pk_fma_f32 v[202:203], v[202:203], v[168:169], v[156:157]
	v_pk_fma_f32 v[244:245], v[244:245], v[170:171], v[246:247]
	v_cvt_pk_bf16_f32 v164, v198, v199
	v_cvt_pk_bf16_f32 v165, v200, v201
	v_cvt_pk_bf16_f32 v166, v202, v203
	v_cvt_pk_bf16_f32 v167, v244, v245
	global_store_dwordx4 v253, v[164:167], s[42:43]
	s_nop 0
	v_add_u32_e32 v253, 0x2000, v253
	s_waitcnt vmcnt(10)
	v_fmamk_f32 v239, v197, 0x3a800000, v228
	v_rsq_f32_e32 v238, v239
	v_lshlrev_b32_e32 v164, 16, v68
	v_and_b32_e32 v165, 0xffff0000, v68
	v_lshlrev_b32_e32 v166, 16, v69
	v_and_b32_e32 v167, 0xffff0000, v69
	v_lshlrev_b32_e32 v168, 16, v70
	v_and_b32_e32 v169, 0xffff0000, v70
	v_lshlrev_b32_e32 v170, 16, v71
	v_and_b32_e32 v171, 0xffff0000, v71
	v_mul_f32_e32 v238, s45, v238
	v_lshlrev_b32_e32 v172, 16, v64
	v_and_b32_e32 v173, 0xffff0000, v64
	v_lshlrev_b32_e32 v174, 16, v65
	v_and_b32_e32 v175, 0xffff0000, v65
	v_lshlrev_b32_e32 v156, 16, v66
	v_and_b32_e32 v157, 0xffff0000, v66
	v_lshlrev_b32_e32 v246, 16, v67
	v_and_b32_e32 v247, 0xffff0000, v67
	v_pk_fma_f32 v[198:199], v[36:37], v[238:239], v[140:141] op_sel_hi:[1,0,1]
	v_pk_fma_f32 v[200:201], v[38:39], v[238:239], v[142:143] op_sel_hi:[1,0,1]
	v_pk_fma_f32 v[202:203], v[32:33], v[238:239], v[136:137] op_sel_hi:[1,0,1]
	v_pk_fma_f32 v[244:245], v[34:35], v[238:239], v[138:139] op_sel_hi:[1,0,1]
	global_load_dwordx4 v[36:39], v252, s[40:41]
	global_load_dwordx4 v[32:35], v252, s[42:43]
	v_add_u32_e32 v252, 0x2000, v252
	v_exp_f32_e32 v198, v198
	v_exp_f32_e32 v199, v199
	v_exp_f32_e32 v200, v200
	v_exp_f32_e32 v201, v201
	v_exp_f32_e32 v202, v202
	v_exp_f32_e32 v203, v203
	v_exp_f32_e32 v244, v244
	v_exp_f32_e32 v245, v245
	v_pk_add_f32 v[198:199], v[198:199], v[254:255] op_sel_hi:[1,0]
	v_pk_add_f32 v[200:201], v[200:201], v[254:255] op_sel_hi:[1,0]
	v_pk_add_f32 v[202:203], v[202:203], v[254:255] op_sel_hi:[1,0]
	v_pk_add_f32 v[244:245], v[244:245], v[254:255] op_sel_hi:[1,0]
	v_rcp_f32_e32 v198, v198
	v_rcp_f32_e32 v199, v199
	v_rcp_f32_e32 v200, v200
	v_rcp_f32_e32 v201, v201
	v_rcp_f32_e32 v202, v202
	v_rcp_f32_e32 v203, v203
	v_rcp_f32_e32 v244, v244
	v_rcp_f32_e32 v245, v245
	v_pk_fma_f32 v[198:199], v[198:199], v[164:165], v[172:173]
	v_pk_fma_f32 v[200:201], v[200:201], v[166:167], v[174:175]
	v_pk_fma_f32 v[202:203], v[202:203], v[168:169], v[156:157]
	v_pk_fma_f32 v[244:245], v[244:245], v[170:171], v[246:247]
	v_cvt_pk_bf16_f32 v164, v198, v199
	v_cvt_pk_bf16_f32 v165, v200, v201
	v_cvt_pk_bf16_f32 v166, v202, v203
	v_cvt_pk_bf16_f32 v167, v244, v245
	global_store_dwordx4 v253, v[164:167], s[42:43]
	s_nop 0
	v_add_u32_e32 v253, 0x2000, v253
	s_waitcnt vmcnt(10)
	v_fmamk_f32 v239, v194, 0x3a800000, v228
	v_rsq_f32_e32 v238, v239
	v_lshlrev_b32_e32 v164, 16, v60
	v_and_b32_e32 v165, 0xffff0000, v60
	v_lshlrev_b32_e32 v166, 16, v61
	v_and_b32_e32 v167, 0xffff0000, v61
	v_lshlrev_b32_e32 v168, 16, v62
	v_and_b32_e32 v169, 0xffff0000, v62
	v_lshlrev_b32_e32 v170, 16, v63
	v_and_b32_e32 v171, 0xffff0000, v63
	v_mul_f32_e32 v238, s45, v238
	v_lshlrev_b32_e32 v172, 16, v56
	v_and_b32_e32 v173, 0xffff0000, v56
	v_lshlrev_b32_e32 v174, 16, v57
	v_and_b32_e32 v175, 0xffff0000, v57
	v_lshlrev_b32_e32 v156, 16, v58
	v_and_b32_e32 v157, 0xffff0000, v58
	v_lshlrev_b32_e32 v246, 16, v59
	v_and_b32_e32 v247, 0xffff0000, v59
	v_pk_fma_f32 v[198:199], v[28:29], v[238:239], v[132:133] op_sel_hi:[1,0,1]
	v_pk_fma_f32 v[200:201], v[30:31], v[238:239], v[134:135] op_sel_hi:[1,0,1]
	v_pk_fma_f32 v[202:203], v[24:25], v[238:239], v[128:129] op_sel_hi:[1,0,1]
	v_pk_fma_f32 v[244:245], v[26:27], v[238:239], v[130:131] op_sel_hi:[1,0,1]
	v_exp_f32_e32 v198, v198
	v_exp_f32_e32 v199, v199
	v_exp_f32_e32 v200, v200
	v_exp_f32_e32 v201, v201
	v_exp_f32_e32 v202, v202
	v_exp_f32_e32 v203, v203
	v_exp_f32_e32 v244, v244
	v_exp_f32_e32 v245, v245
	v_pk_add_f32 v[198:199], v[198:199], v[254:255] op_sel_hi:[1,0]
	v_pk_add_f32 v[200:201], v[200:201], v[254:255] op_sel_hi:[1,0]
	v_pk_add_f32 v[202:203], v[202:203], v[254:255] op_sel_hi:[1,0]
	v_pk_add_f32 v[244:245], v[244:245], v[254:255] op_sel_hi:[1,0]
	v_rcp_f32_e32 v198, v198
	v_rcp_f32_e32 v199, v199
	v_rcp_f32_e32 v200, v200
	v_rcp_f32_e32 v201, v201
	v_rcp_f32_e32 v202, v202
	v_rcp_f32_e32 v203, v203
	v_rcp_f32_e32 v244, v244
	v_rcp_f32_e32 v245, v245
	v_pk_fma_f32 v[198:199], v[198:199], v[164:165], v[172:173]
	v_pk_fma_f32 v[200:201], v[200:201], v[166:167], v[174:175]
	v_pk_fma_f32 v[202:203], v[202:203], v[168:169], v[156:157]
	v_pk_fma_f32 v[244:245], v[244:245], v[170:171], v[246:247]
	v_cvt_pk_bf16_f32 v164, v198, v199
	v_cvt_pk_bf16_f32 v165, v200, v201
	v_cvt_pk_bf16_f32 v166, v202, v203
	v_cvt_pk_bf16_f32 v167, v244, v245
	global_store_dwordx4 v253, v[164:167], s[42:43]
	s_nop 0
	v_add_u32_e32 v253, 0x2000, v253
	s_waitcnt vmcnt(8)
	v_fmamk_f32 v239, v195, 0x3a800000, v228
	v_rsq_f32_e32 v238, v239
	v_lshlrev_b32_e32 v164, 16, v52
	v_and_b32_e32 v165, 0xffff0000, v52
	v_lshlrev_b32_e32 v166, 16, v53
	v_and_b32_e32 v167, 0xffff0000, v53
	v_lshlrev_b32_e32 v168, 16, v54
	v_and_b32_e32 v169, 0xffff0000, v54
	v_lshlrev_b32_e32 v170, 16, v55
	v_and_b32_e32 v171, 0xffff0000, v55
	v_mul_f32_e32 v238, s45, v238
	v_lshlrev_b32_e32 v172, 16, v48
	v_and_b32_e32 v173, 0xffff0000, v48
	v_lshlrev_b32_e32 v174, 16, v49
	v_and_b32_e32 v175, 0xffff0000, v49
	v_lshlrev_b32_e32 v156, 16, v50
	v_and_b32_e32 v157, 0xffff0000, v50
	v_lshlrev_b32_e32 v246, 16, v51
	v_and_b32_e32 v247, 0xffff0000, v51
	v_pk_fma_f32 v[198:199], v[20:21], v[238:239], v[132:133] op_sel_hi:[1,0,1]
	v_pk_fma_f32 v[200:201], v[22:23], v[238:239], v[134:135] op_sel_hi:[1,0,1]
	v_pk_fma_f32 v[202:203], v[16:17], v[238:239], v[128:129] op_sel_hi:[1,0,1]
	v_pk_fma_f32 v[244:245], v[18:19], v[238:239], v[130:131] op_sel_hi:[1,0,1]
	v_exp_f32_e32 v198, v198
	v_exp_f32_e32 v199, v199
	v_exp_f32_e32 v200, v200
	v_exp_f32_e32 v201, v201
	v_exp_f32_e32 v202, v202
	v_exp_f32_e32 v203, v203
	v_exp_f32_e32 v244, v244
	v_exp_f32_e32 v245, v245
	v_pk_add_f32 v[198:199], v[198:199], v[254:255] op_sel_hi:[1,0]
	v_pk_add_f32 v[200:201], v[200:201], v[254:255] op_sel_hi:[1,0]
	v_pk_add_f32 v[202:203], v[202:203], v[254:255] op_sel_hi:[1,0]
	v_pk_add_f32 v[244:245], v[244:245], v[254:255] op_sel_hi:[1,0]
	v_rcp_f32_e32 v198, v198
	v_rcp_f32_e32 v199, v199
	v_rcp_f32_e32 v200, v200
	v_rcp_f32_e32 v201, v201
	v_rcp_f32_e32 v202, v202
	v_rcp_f32_e32 v203, v203
	v_rcp_f32_e32 v244, v244
	v_rcp_f32_e32 v245, v245
	v_pk_fma_f32 v[198:199], v[198:199], v[164:165], v[172:173]
	v_pk_fma_f32 v[200:201], v[200:201], v[166:167], v[174:175]
	v_pk_fma_f32 v[202:203], v[202:203], v[168:169], v[156:157]
	v_pk_fma_f32 v[244:245], v[244:245], v[170:171], v[246:247]
	v_cvt_pk_bf16_f32 v164, v198, v199
	v_cvt_pk_bf16_f32 v165, v200, v201
	v_cvt_pk_bf16_f32 v166, v202, v203
	v_cvt_pk_bf16_f32 v167, v244, v245
	global_store_dwordx4 v253, v[164:167], s[42:43]
	s_nop 0
	v_add_u32_e32 v253, 0x2000, v253
	s_waitcnt vmcnt(6)
	v_fmamk_f32 v239, v196, 0x3a800000, v228
	v_rsq_f32_e32 v238, v239
	v_lshlrev_b32_e32 v164, 16, v44
	v_and_b32_e32 v165, 0xffff0000, v44
	v_lshlrev_b32_e32 v166, 16, v45
	v_and_b32_e32 v167, 0xffff0000, v45
	v_lshlrev_b32_e32 v168, 16, v46
	v_and_b32_e32 v169, 0xffff0000, v46
	v_lshlrev_b32_e32 v170, 16, v47
	v_and_b32_e32 v171, 0xffff0000, v47
	v_mul_f32_e32 v238, s45, v238
	v_lshlrev_b32_e32 v172, 16, v40
	v_and_b32_e32 v173, 0xffff0000, v40
	v_lshlrev_b32_e32 v174, 16, v41
	v_and_b32_e32 v175, 0xffff0000, v41
	v_lshlrev_b32_e32 v156, 16, v42
	v_and_b32_e32 v157, 0xffff0000, v42
	v_lshlrev_b32_e32 v246, 16, v43
	v_and_b32_e32 v247, 0xffff0000, v43
	v_pk_fma_f32 v[198:199], v[12:13], v[238:239], v[132:133] op_sel_hi:[1,0,1]
	v_pk_fma_f32 v[200:201], v[14:15], v[238:239], v[134:135] op_sel_hi:[1,0,1]
	v_pk_fma_f32 v[202:203], v[8:9], v[238:239], v[128:129] op_sel_hi:[1,0,1]
	v_pk_fma_f32 v[244:245], v[10:11], v[238:239], v[130:131] op_sel_hi:[1,0,1]
	v_exp_f32_e32 v198, v198
	v_exp_f32_e32 v199, v199
	v_exp_f32_e32 v200, v200
	v_exp_f32_e32 v201, v201
	v_exp_f32_e32 v202, v202
	v_exp_f32_e32 v203, v203
	v_exp_f32_e32 v244, v244
	v_exp_f32_e32 v245, v245
	v_pk_add_f32 v[198:199], v[198:199], v[254:255] op_sel_hi:[1,0]
	v_pk_add_f32 v[200:201], v[200:201], v[254:255] op_sel_hi:[1,0]
	v_pk_add_f32 v[202:203], v[202:203], v[254:255] op_sel_hi:[1,0]
	v_pk_add_f32 v[244:245], v[244:245], v[254:255] op_sel_hi:[1,0]
	v_rcp_f32_e32 v198, v198
	v_rcp_f32_e32 v199, v199
	v_rcp_f32_e32 v200, v200
	v_rcp_f32_e32 v201, v201
	v_rcp_f32_e32 v202, v202
	v_rcp_f32_e32 v203, v203
	v_rcp_f32_e32 v244, v244
	v_rcp_f32_e32 v245, v245
	v_pk_fma_f32 v[198:199], v[198:199], v[164:165], v[172:173]
	v_pk_fma_f32 v[200:201], v[200:201], v[166:167], v[174:175]
	v_pk_fma_f32 v[202:203], v[202:203], v[168:169], v[156:157]
	v_pk_fma_f32 v[244:245], v[244:245], v[170:171], v[246:247]
	v_cvt_pk_bf16_f32 v164, v198, v199
	v_cvt_pk_bf16_f32 v165, v200, v201
	v_cvt_pk_bf16_f32 v166, v202, v203
	v_cvt_pk_bf16_f32 v167, v244, v245
	global_store_dwordx4 v253, v[164:167], s[42:43]
	s_nop 0
	v_add_u32_e32 v253, 0x2000, v253
	s_waitcnt vmcnt(4)
	v_fmamk_f32 v239, v197, 0x3a800000, v228
	v_rsq_f32_e32 v238, v239
	v_lshlrev_b32_e32 v164, 16, v36
	v_and_b32_e32 v165, 0xffff0000, v36
	v_lshlrev_b32_e32 v166, 16, v37
	v_and_b32_e32 v167, 0xffff0000, v37
	v_lshlrev_b32_e32 v168, 16, v38
	v_and_b32_e32 v169, 0xffff0000, v38
	v_lshlrev_b32_e32 v170, 16, v39
	v_and_b32_e32 v171, 0xffff0000, v39
	v_mul_f32_e32 v238, s45, v238
	v_lshlrev_b32_e32 v172, 16, v32
	v_and_b32_e32 v173, 0xffff0000, v32
	v_lshlrev_b32_e32 v174, 16, v33
	v_and_b32_e32 v175, 0xffff0000, v33
	v_lshlrev_b32_e32 v156, 16, v34
	v_and_b32_e32 v157, 0xffff0000, v34
	v_lshlrev_b32_e32 v246, 16, v35
	v_and_b32_e32 v247, 0xffff0000, v35
	v_pk_fma_f32 v[198:199], v[4:5], v[238:239], v[132:133] op_sel_hi:[1,0,1]
	v_pk_fma_f32 v[200:201], v[6:7], v[238:239], v[134:135] op_sel_hi:[1,0,1]
	v_pk_fma_f32 v[202:203], v[0:1], v[238:239], v[128:129] op_sel_hi:[1,0,1]
	v_pk_fma_f32 v[244:245], v[2:3], v[238:239], v[130:131] op_sel_hi:[1,0,1]
	v_exp_f32_e32 v198, v198
	v_exp_f32_e32 v199, v199
	v_exp_f32_e32 v200, v200
	v_exp_f32_e32 v201, v201
	v_exp_f32_e32 v202, v202
	v_exp_f32_e32 v203, v203
	v_exp_f32_e32 v244, v244
	v_exp_f32_e32 v245, v245
	v_pk_add_f32 v[198:199], v[198:199], v[254:255] op_sel_hi:[1,0]
	v_pk_add_f32 v[200:201], v[200:201], v[254:255] op_sel_hi:[1,0]
	v_pk_add_f32 v[202:203], v[202:203], v[254:255] op_sel_hi:[1,0]
	v_pk_add_f32 v[244:245], v[244:245], v[254:255] op_sel_hi:[1,0]
	v_rcp_f32_e32 v198, v198
	v_rcp_f32_e32 v199, v199
	v_rcp_f32_e32 v200, v200
	v_rcp_f32_e32 v201, v201
	v_rcp_f32_e32 v202, v202
	v_rcp_f32_e32 v203, v203
	v_rcp_f32_e32 v244, v244
	v_rcp_f32_e32 v245, v245
	v_pk_fma_f32 v[198:199], v[198:199], v[164:165], v[172:173]
	v_pk_fma_f32 v[200:201], v[200:201], v[166:167], v[174:175]
	v_pk_fma_f32 v[202:203], v[202:203], v[168:169], v[156:157]
	v_pk_fma_f32 v[244:245], v[244:245], v[170:171], v[246:247]
	v_cvt_pk_bf16_f32 v164, v198, v199
	v_cvt_pk_bf16_f32 v165, v200, v201
	v_cvt_pk_bf16_f32 v166, v202, v203
	v_cvt_pk_bf16_f32 v167, v244, v245
	global_store_dwordx4 v253, v[164:167], s[42:43]
	s_nop 0
	v_add_u32_e32 v253, 0x2000, v253
	s_branch .LBB0_1002
.Lmrg_b0:
	v_mov_b32_e32 v172, 0
	v_mov_b32_e32 v173, 0
	v_mov_b32_e32 v174, 0
	v_mov_b32_e32 v175, 0
	v_mov_b32_e32 v156, 0
	v_mov_b32_e32 v157, 0
	v_mov_b32_e32 v246, 0
	v_mov_b32_e32 v247, 0
	global_load_dwordx4 v[144:147], v252, s[40:41]
	v_add_u32_e32 v252, 0x2000, v252
	global_load_dwordx4 v[152:155], v252, s[40:41]
	v_add_u32_e32 v252, 0x2000, v252
	global_load_dwordx4 v[212:215], v252, s[40:41]
	v_add_u32_e32 v252, 0x2000, v252
	global_load_dwordx4 v[220:223], v252, s[40:41]
	v_add_u32_e32 v252, 0x2000, v252
	s_waitcnt vmcnt(3)
	v_mul_f32_e32 v128, s45, v128
	v_mul_f32_e32 v129, s45, v129
	v_mul_f32_e32 v130, s45, v130
	v_mul_f32_e32 v131, s45, v131
	v_mul_f32_e32 v132, s45, v132
	v_mul_f32_e32 v133, s45, v133
	v_mul_f32_e32 v134, s45, v134
	v_mul_f32_e32 v135, s45, v135
	v_mul_f32_e32 v136, s45, v136
	v_mul_f32_e32 v137, s45, v137
	v_mul_f32_e32 v138, s45, v138
	v_mul_f32_e32 v139, s45, v139
	v_mul_f32_e32 v140, s45, v140
	v_mul_f32_e32 v141, s45, v141
	v_mul_f32_e32 v142, s45, v142
	v_mul_f32_e32 v143, s45, v143
	v_fmamk_f32 v239, v190, 0x3a800000, v228
	v_rsq_f32_e32 v238, v239
	v_lshlrev_b32_e32 v164, 16, v144
	v_and_b32_e32 v165, 0xffff0000, v144
	v_lshlrev_b32_e32 v166, 16, v145
	v_and_b32_e32 v167, 0xffff0000, v145
	v_lshlrev_b32_e32 v168, 16, v146
	v_and_b32_e32 v169, 0xffff0000, v146
	v_lshlrev_b32_e32 v170, 16, v147
	v_and_b32_e32 v171, 0xffff0000, v147
	v_mul_f32_e32 v238, s45, v238
	v_pk_fma_f32 v[198:199], v[124:125], v[238:239], v[140:141] op_sel_hi:[1,0,1]
	v_pk_fma_f32 v[200:201], v[126:127], v[238:239], v[142:143] op_sel_hi:[1,0,1]
	v_pk_fma_f32 v[202:203], v[120:121], v[238:239], v[136:137] op_sel_hi:[1,0,1]
	v_pk_fma_f32 v[244:245], v[122:123], v[238:239], v[138:139] op_sel_hi:[1,0,1]
	global_load_dwordx4 v[124:127], v252, s[40:41]
	v_add_u32_e32 v252, 0x2000, v252
	v_exp_f32_e32 v198, v198
	v_exp_f32_e32 v199, v199
	v_exp_f32_e32 v200, v200
	v_exp_f32_e32 v201, v201
	v_exp_f32_e32 v202, v202
	v_exp_f32_e32 v203, v203
	v_exp_f32_e32 v244, v244
	v_exp_f32_e32 v245, v245
	v_pk_add_f32 v[198:199], v[198:199], v[254:255] op_sel_hi:[1,0]
	v_pk_add_f32 v[200:201], v[200:201], v[254:255] op_sel_hi:[1,0]
	v_pk_add_f32 v[202:203], v[202:203], v[254:255] op_sel_hi:[1,0]
	v_pk_add_f32 v[244:245], v[244:245], v[254:255] op_sel_hi:[1,0]
	v_rcp_f32_e32 v198, v198
	v_rcp_f32_e32 v199, v199
	v_rcp_f32_e32 v200, v200
	v_rcp_f32_e32 v201, v201
	v_rcp_f32_e32 v202, v202
	v_rcp_f32_e32 v203, v203
	v_rcp_f32_e32 v244, v244
	v_rcp_f32_e32 v245, v245
	v_pk_fma_f32 v[198:199], v[198:199], v[164:165], v[172:173]
	v_pk_fma_f32 v[200:201], v[200:201], v[166:167], v[174:175]
	v_pk_fma_f32 v[202:203], v[202:203], v[168:169], v[156:157]
	v_pk_fma_f32 v[244:245], v[244:245], v[170:171], v[246:247]
	v_cvt_pk_bf16_f32 v164, v198, v199
	v_cvt_pk_bf16_f32 v165, v200, v201
	v_cvt_pk_bf16_f32 v166, v202, v203
	v_cvt_pk_bf16_f32 v167, v244, v245
	global_store_dwordx4 v253, v[164:167], s[42:43]
	s_nop 0
	v_add_u32_e32 v253, 0x2000, v253
	s_waitcnt vmcnt(4)
	v_fmamk_f32 v239, v191, 0x3a800000, v228
	v_rsq_f32_e32 v238, v239
	v_lshlrev_b32_e32 v164, 16, v152
	v_and_b32_e32 v165, 0xffff0000, v152
	v_lshlrev_b32_e32 v166, 16, v153
	v_and_b32_e32 v167, 0xffff0000, v153
	v_lshlrev_b32_e32 v168, 16, v154
	v_and_b32_e32 v169, 0xffff0000, v154
	v_lshlrev_b32_e32 v170, 16, v155
	v_and_b32_e32 v171, 0xffff0000, v155
	v_mul_f32_e32 v238, s45, v238
	v_pk_fma_f32 v[198:199], v[116:117], v[238:239], v[140:141] op_sel_hi:[1,0,1]
	v_pk_fma_f32 v[200:201], v[118:119], v[238:239], v[142:143] op_sel_hi:[1,0,1]
	v_pk_fma_f32 v[202:203], v[112:113], v[238:239], v[136:137] op_sel_hi:[1,0,1]
	v_pk_fma_f32 v[244:245], v[114:115], v[238:239], v[138:139] op_sel_hi:[1,0,1]
	global_load_dwordx4 v[116:119], v252, s[40:41]
	v_add_u32_e32 v252, 0x2000, v252
	v_exp_f32_e32 v198, v198
	v_exp_f32_e32 v199, v199
	v_exp_f32_e32 v200, v200
	v_exp_f32_e32 v201, v201
	v_exp_f32_e32 v202, v202
	v_exp_f32_e32 v203, v203
	v_exp_f32_e32 v244, v244
	v_exp_f32_e32 v245, v245
	v_pk_add_f32 v[198:199], v[198:199], v[254:255] op_sel_hi:[1,0]
	v_pk_add_f32 v[200:201], v[200:201], v[254:255] op_sel_hi:[1,0]
	v_pk_add_f32 v[202:203], v[202:203], v[254:255] op_sel_hi:[1,0]
	v_pk_add_f32 v[244:245], v[244:245], v[254:255] op_sel_hi:[1,0]
	v_rcp_f32_e32 v198, v198
	v_rcp_f32_e32 v199, v199
	v_rcp_f32_e32 v200, v200
	v_rcp_f32_e32 v201, v201
	v_rcp_f32_e32 v202, v202
	v_rcp_f32_e32 v203, v203
	v_rcp_f32_e32 v244, v244
	v_rcp_f32_e32 v245, v245
	v_pk_fma_f32 v[198:199], v[198:199], v[164:165], v[172:173]
	v_pk_fma_f32 v[200:201], v[200:201], v[166:167], v[174:175]
	v_pk_fma_f32 v[202:203], v[202:203], v[168:169], v[156:157]
	v_pk_fma_f32 v[244:245], v[244:245], v[170:171], v[246:247]
	v_cvt_pk_bf16_f32 v164, v198, v199
	v_cvt_pk_bf16_f32 v165, v200, v201
	v_cvt_pk_bf16_f32 v166, v202, v203
	v_cvt_pk_bf16_f32 v167, v244, v245
	global_store_dwordx4 v253, v[164:167], s[42:43]
	s_nop 0
	v_add_u32_e32 v253, 0x2000, v253
	s_waitcnt vmcnt(5)
	v_fmamk_f32 v239, v192, 0x3a800000, v228
	v_rsq_f32_e32 v238, v239
	v_lshlrev_b32_e32 v164, 16, v212
	v_and_b32_e32 v165, 0xffff0000, v212
	v_lshlrev_b32_e32 v166, 16, v213
	v_and_b32_e32 v167, 0xffff0000, v213
	v_lshlrev_b32_e32 v168, 16, v214
	v_and_b32_e32 v169, 0xffff0000, v214
	v_lshlrev_b32_e32 v170, 16, v215
	v_and_b32_e32 v171, 0xffff0000, v215
	v_mul_f32_e32 v238, s45, v238
	v_pk_fma_f32 v[198:199], v[108:109], v[238:239], v[140:141] op_sel_hi:[1,0,1]
	v_pk_fma_f32 v[200:201], v[110:111], v[238:239], v[142:143] op_sel_hi:[1,0,1]
	v_pk_fma_f32 v[202:203], v[104:105], v[238:239], v[136:137] op_sel_hi:[1,0,1]
	v_pk_fma_f32 v[244:245], v[106:107], v[238:239], v[138:139] op_sel_hi:[1,0,1]
	global_load_dwordx4 v[108:111], v252, s[40:41]
	v_add_u32_e32 v252, 0x2000, v252
	v_exp_f32_e32 v198, v198
	v_exp_f32_e32 v199, v199
	v_exp_f32_e32 v200, v200
	v_exp_f32_e32 v201, v201
	v_exp_f32_e32 v202, v202
	v_exp_f32_e32 v203, v203
	v_exp_f32_e32 v244, v244
	v_exp_f32_e32 v245, v245
	v_pk_add_f32 v[198:199], v[198:199], v[254:255] op_sel_hi:[1,0]
	v_pk_add_f32 v[200:201], v[200:201], v[254:255] op_sel_hi:[1,0]
	v_pk_add_f32 v[202:203], v[202:203], v[254:255] op_sel_hi:[1,0]
	v_pk_add_f32 v[244:245], v[244:245], v[254:255] op_sel_hi:[1,0]
	v_rcp_f32_e32 v198, v198
	v_rcp_f32_e32 v199, v199
	v_rcp_f32_e32 v200, v200
	v_rcp_f32_e32 v201, v201
	v_rcp_f32_e32 v202, v202
	v_rcp_f32_e32 v203, v203
	v_rcp_f32_e32 v244, v244
	v_rcp_f32_e32 v245, v245
	v_pk_fma_f32 v[198:199], v[198:199], v[164:165], v[172:173]
	v_pk_fma_f32 v[200:201], v[200:201], v[166:167], v[174:175]
	v_pk_fma_f32 v[202:203], v[202:203], v[168:169], v[156:157]
	v_pk_fma_f32 v[244:245], v[244:245], v[170:171], v[246:247]
	v_cvt_pk_bf16_f32 v164, v198, v199
	v_cvt_pk_bf16_f32 v165, v200, v201
	v_cvt_pk_bf16_f32 v166, v202, v203
	v_cvt_pk_bf16_f32 v167, v244, v245
	global_store_dwordx4 v253, v[164:167], s[42:43]
	s_nop 0
	v_add_u32_e32 v253, 0x2000, v253
	s_waitcnt vmcnt(6)
	v_fmamk_f32 v239, v193, 0x3a800000, v228
	v_rsq_f32_e32 v238, v239
	v_lshlrev_b32_e32 v164, 16, v220
	v_and_b32_e32 v165, 0xffff0000, v220
	v_lshlrev_b32_e32 v166, 16, v221
	v_and_b32_e32 v167, 0xffff0000, v221
	v_lshlrev_b32_e32 v168, 16, v222
	v_and_b32_e32 v169, 0xffff0000, v222
	v_lshlrev_b32_e32 v170, 16, v223
	v_and_b32_e32 v171, 0xffff0000, v223
	v_mul_f32_e32 v238, s45, v238
	v_pk_fma_f32 v[198:199], v[100:101], v[238:239], v[140:141] op_sel_hi:[1,0,1]
	v_pk_fma_f32 v[200:201], v[102:103], v[238:239], v[142:143] op_sel_hi:[1,0,1]
	v_pk_fma_f32 v[202:203], v[96:97], v[238:239], v[136:137] op_sel_hi:[1,0,1]
	v_pk_fma_f32 v[244:245], v[98:99], v[238:239], v[138:139] op_sel_hi:[1,0,1]
	global_load_dwordx4 v[100:103], v252, s[40:41]
	v_add_u32_e32 v252, 0x2000, v252
	v_exp_f32_e32 v198, v198
	v_exp_f32_e32 v199, v199
	v_exp_f32_e32 v200, v200
	v_exp_f32_e32 v201, v201
	v_exp_f32_e32 v202, v202
	v_exp_f32_e32 v203, v203
	v_exp_f32_e32 v244, v244
	v_exp_f32_e32 v245, v245
	v_pk_add_f32 v[198:199], v[198:199], v[254:255] op_sel_hi:[1,0]
	v_pk_add_f32 v[200:201], v[200:201], v[254:255] op_sel_hi:[1,0]
	v_pk_add_f32 v[202:203], v[202:203], v[254:255] op_sel_hi:[1,0]
	v_pk_add_f32 v[244:245], v[244:245], v[254:255] op_sel_hi:[1,0]
	v_rcp_f32_e32 v198, v198
	v_rcp_f32_e32 v199, v199
	v_rcp_f32_e32 v200, v200
	v_rcp_f32_e32 v201, v201
	v_rcp_f32_e32 v202, v202
	v_rcp_f32_e32 v203, v203
	v_rcp_f32_e32 v244, v244
	v_rcp_f32_e32 v245, v245
	v_pk_fma_f32 v[198:199], v[198:199], v[164:165], v[172:173]
	v_pk_fma_f32 v[200:201], v[200:201], v[166:167], v[174:175]
	v_pk_fma_f32 v[202:203], v[202:203], v[168:169], v[156:157]
	v_pk_fma_f32 v[244:245], v[244:245], v[170:171], v[246:247]
	v_cvt_pk_bf16_f32 v164, v198, v199
	v_cvt_pk_bf16_f32 v165, v200, v201
	v_cvt_pk_bf16_f32 v166, v202, v203
	v_cvt_pk_bf16_f32 v167, v244, v245
	global_store_dwordx4 v253, v[164:167], s[42:43]
	s_nop 0
	v_add_u32_e32 v253, 0x2000, v253
	s_waitcnt vmcnt(7)
	v_fmamk_f32 v239, v190, 0x3a800000, v228
	v_rsq_f32_e32 v238, v239
	v_lshlrev_b32_e32 v164, 16, v124
	v_and_b32_e32 v165, 0xffff0000, v124
	v_lshlrev_b32_e32 v166, 16, v125
	v_and_b32_e32 v167, 0xffff0000, v125
	v_lshlrev_b32_e32 v168, 16, v126
	v_and_b32_e32 v169, 0xffff0000, v126
	v_lshlrev_b32_e32 v170, 16, v127
	v_and_b32_e32 v171, 0xffff0000, v127
	v_mul_f32_e32 v238, s45, v238
	v_pk_fma_f32 v[198:199], v[92:93], v[238:239], v[132:133] op_sel_hi:[1,0,1]
	v_pk_fma_f32 v[200:201], v[94:95], v[238:239], v[134:135] op_sel_hi:[1,0,1]
	v_pk_fma_f32 v[202:203], v[88:89], v[238:239], v[128:129] op_sel_hi:[1,0,1]
	v_pk_fma_f32 v[244:245], v[90:91], v[238:239], v[130:131] op_sel_hi:[1,0,1]
	global_load_dwordx4 v[92:95], v252, s[40:41]
	v_add_u32_e32 v252, 0x2000, v252
	v_exp_f32_e32 v198, v198
	v_exp_f32_e32 v199, v199
	v_exp_f32_e32 v200, v200
	v_exp_f32_e32 v201, v201
	v_exp_f32_e32 v202, v202
	v_exp_f32_e32 v203, v203
	v_exp_f32_e32 v244, v244
	v_exp_f32_e32 v245, v245
	v_pk_add_f32 v[198:199], v[198:199], v[254:255] op_sel_hi:[1,0]
	v_pk_add_f32 v[200:201], v[200:201], v[254:255] op_sel_hi:[1,0]
	v_pk_add_f32 v[202:203], v[202:203], v[254:255] op_sel_hi:[1,0]
	v_pk_add_f32 v[244:245], v[244:245], v[254:255] op_sel_hi:[1,0]
	v_rcp_f32_e32 v198, v198
	v_rcp_f32_e32 v199, v199
	v_rcp_f32_e32 v200, v200
	v_rcp_f32_e32 v201, v201
	v_rcp_f32_e32 v202, v202
	v_rcp_f32_e32 v203, v203
	v_rcp_f32_e32 v244, v244
	v_rcp_f32_e32 v245, v245
	v_pk_fma_f32 v[198:199], v[198:199], v[164:165], v[172:173]
	v_pk_fma_f32 v[200:201], v[200:201], v[166:167], v[174:175]
	v_pk_fma_f32 v[202:203], v[202:203], v[168:169], v[156:157]
	v_pk_fma_f32 v[244:245], v[244:245], v[170:171], v[246:247]
	v_cvt_pk_bf16_f32 v164, v198, v199
	v_cvt_pk_bf16_f32 v165, v200, v201
	v_cvt_pk_bf16_f32 v166, v202, v203
	v_cvt_pk_bf16_f32 v167, v244, v245
	global_store_dwordx4 v253, v[164:167], s[42:43]
	s_nop 0
	v_add_u32_e32 v253, 0x2000, v253
	s_waitcnt vmcnt(7)
	v_fmamk_f32 v239, v191, 0x3a800000, v228
	v_rsq_f32_e32 v238, v239
	v_lshlrev_b32_e32 v164, 16, v116
	v_and_b32_e32 v165, 0xffff0000, v116
	v_lshlrev_b32_e32 v166, 16, v117
	v_and_b32_e32 v167, 0xffff0000, v117
	v_lshlrev_b32_e32 v168, 16, v118
	v_and_b32_e32 v169, 0xffff0000, v118
	v_lshlrev_b32_e32 v170, 16, v119
	v_and_b32_e32 v171, 0xffff0000, v119
	v_mul_f32_e32 v238, s45, v238
	v_pk_fma_f32 v[198:199], v[84:85], v[238:239], v[132:133] op_sel_hi:[1,0,1]
	v_pk_fma_f32 v[200:201], v[86:87], v[238:239], v[134:135] op_sel_hi:[1,0,1]
	v_pk_fma_f32 v[202:203], v[80:81], v[238:239], v[128:129] op_sel_hi:[1,0,1]
	v_pk_fma_f32 v[244:245], v[82:83], v[238:239], v[130:131] op_sel_hi:[1,0,1]
	global_load_dwordx4 v[84:87], v252, s[40:41]
	v_add_u32_e32 v252, 0x2000, v252
	v_exp_f32_e32 v198, v198
	v_exp_f32_e32 v199, v199
	v_exp_f32_e32 v200, v200
	v_exp_f32_e32 v201, v201
	v_exp_f32_e32 v202, v202
	v_exp_f32_e32 v203, v203
	v_exp_f32_e32 v244, v244
	v_exp_f32_e32 v245, v245
	v_pk_add_f32 v[198:199], v[198:199], v[254:255] op_sel_hi:[1,0]
	v_pk_add_f32 v[200:201], v[200:201], v[254:255] op_sel_hi:[1,0]
	v_pk_add_f32 v[202:203], v[202:203], v[254:255] op_sel_hi:[1,0]
	v_pk_add_f32 v[244:245], v[244:245], v[254:255] op_sel_hi:[1,0]
	v_rcp_f32_e32 v198, v198
	v_rcp_f32_e32 v199, v199
	v_rcp_f32_e32 v200, v200
	v_rcp_f32_e32 v201, v201
	v_rcp_f32_e32 v202, v202
	v_rcp_f32_e32 v203, v203
	v_rcp_f32_e32 v244, v244
	v_rcp_f32_e32 v245, v245
	v_pk_fma_f32 v[198:199], v[198:199], v[164:165], v[172:173]
	v_pk_fma_f32 v[200:201], v[200:201], v[166:167], v[174:175]
	v_pk_fma_f32 v[202:203], v[202:203], v[168:169], v[156:157]
	v_pk_fma_f32 v[244:245], v[244:245], v[170:171], v[246:247]
	v_cvt_pk_bf16_f32 v164, v198, v199
	v_cvt_pk_bf16_f32 v165, v200, v201
	v_cvt_pk_bf16_f32 v166, v202, v203
	v_cvt_pk_bf16_f32 v167, v244, v245
	global_store_dwordx4 v253, v[164:167], s[42:43]
	s_nop 0
	v_add_u32_e32 v253, 0x2000, v253
	s_waitcnt vmcnt(7)
	v_fmamk_f32 v239, v192, 0x3a800000, v228
	v_rsq_f32_e32 v238, v239
	v_lshlrev_b32_e32 v164, 16, v108
	v_and_b32_e32 v165, 0xffff0000, v108
	v_lshlrev_b32_e32 v166, 16, v109
	v_and_b32_e32 v167, 0xffff0000, v109
	v_lshlrev_b32_e32 v168, 16, v110
	v_and_b32_e32 v169, 0xffff0000, v110
	v_lshlrev_b32_e32 v170, 16, v111
	v_and_b32_e32 v171, 0xffff0000, v111
	v_mul_f32_e32 v238, s45, v238
	v_pk_fma_f32 v[198:199], v[76:77], v[238:239], v[132:133] op_sel_hi:[1,0,1]
	v_pk_fma_f32 v[200:201], v[78:79], v[238:239], v[134:135] op_sel_hi:[1,0,1]
	v_pk_fma_f32 v[202:203], v[72:73], v[238:239], v[128:129] op_sel_hi:[1,0,1]
	v_pk_fma_f32 v[244:245], v[74:75], v[238:239], v[130:131] op_sel_hi:[1,0,1]
	global_load_dwordx4 v[76:79], v252, s[40:41]
	v_add_u32_e32 v252, 0x2000, v252
	v_exp_f32_e32 v198, v198
	v_exp_f32_e32 v199, v199
	v_exp_f32_e32 v200, v200
	v_exp_f32_e32 v201, v201
	v_exp_f32_e32 v202, v202
	v_exp_f32_e32 v203, v203
	v_exp_f32_e32 v244, v244
	v_exp_f32_e32 v245, v245
	v_pk_add_f32 v[198:199], v[198:199], v[254:255] op_sel_hi:[1,0]
	v_pk_add_f32 v[200:201], v[200:201], v[254:255] op_sel_hi:[1,0]
	v_pk_add_f32 v[202:203], v[202:203], v[254:255] op_sel_hi:[1,0]
	v_pk_add_f32 v[244:245], v[244:245], v[254:255] op_sel_hi:[1,0]
	v_rcp_f32_e32 v198, v198
	v_rcp_f32_e32 v199, v199
	v_rcp_f32_e32 v200, v200
	v_rcp_f32_e32 v201, v201
	v_rcp_f32_e32 v202, v202
	v_rcp_f32_e32 v203, v203
	v_rcp_f32_e32 v244, v244
	v_rcp_f32_e32 v245, v245
	v_pk_fma_f32 v[198:199], v[198:199], v[164:165], v[172:173]
	v_pk_fma_f32 v[200:201], v[200:201], v[166:167], v[174:175]
	v_pk_fma_f32 v[202:203], v[202:203], v[168:169], v[156:157]
	v_pk_fma_f32 v[244:245], v[244:245], v[170:171], v[246:247]
	v_cvt_pk_bf16_f32 v164, v198, v199
	v_cvt_pk_bf16_f32 v165, v200, v201
	v_cvt_pk_bf16_f32 v166, v202, v203
	v_cvt_pk_bf16_f32 v167, v244, v245
	global_store_dwordx4 v253, v[164:167], s[42:43]
	s_nop 0
	v_add_u32_e32 v253, 0x2000, v253
	s_waitcnt vmcnt(7)
	v_fmamk_f32 v239, v193, 0x3a800000, v228
	v_rsq_f32_e32 v238, v239
	v_lshlrev_b32_e32 v164, 16, v100
	v_and_b32_e32 v165, 0xffff0000, v100
	v_lshlrev_b32_e32 v166, 16, v101
	v_and_b32_e32 v167, 0xffff0000, v101
	v_lshlrev_b32_e32 v168, 16, v102
	v_and_b32_e32 v169, 0xffff0000, v102
	v_lshlrev_b32_e32 v170, 16, v103
	v_and_b32_e32 v171, 0xffff0000, v103
	v_mul_f32_e32 v238, s45, v238
	v_pk_fma_f32 v[198:199], v[68:69], v[238:239], v[132:133] op_sel_hi:[1,0,1]
	v_pk_fma_f32 v[200:201], v[70:71], v[238:239], v[134:135] op_sel_hi:[1,0,1]
	v_pk_fma_f32 v[202:203], v[64:65], v[238:239], v[128:129] op_sel_hi:[1,0,1]
	v_pk_fma_f32 v[244:245], v[66:67], v[238:239], v[130:131] op_sel_hi:[1,0,1]
	global_load_dwordx4 v[68:71], v252, s[40:41]
	v_add_u32_e32 v252, 0x2000, v252
	v_exp_f32_e32 v198, v198
	v_exp_f32_e32 v199, v199
	v_exp_f32_e32 v200, v200
	v_exp_f32_e32 v201, v201
	v_exp_f32_e32 v202, v202
	v_exp_f32_e32 v203, v203
	v_exp_f32_e32 v244, v244
	v_exp_f32_e32 v245, v245
	v_pk_add_f32 v[198:199], v[198:199], v[254:255] op_sel_hi:[1,0]
	v_pk_add_f32 v[200:201], v[200:201], v[254:255] op_sel_hi:[1,0]
	v_pk_add_f32 v[202:203], v[202:203], v[254:255] op_sel_hi:[1,0]
	v_pk_add_f32 v[244:245], v[244:245], v[254:255] op_sel_hi:[1,0]
	v_rcp_f32_e32 v198, v198
	v_rcp_f32_e32 v199, v199
	v_rcp_f32_e32 v200, v200
	v_rcp_f32_e32 v201, v201
	v_rcp_f32_e32 v202, v202
	v_rcp_f32_e32 v203, v203
	v_rcp_f32_e32 v244, v244
	v_rcp_f32_e32 v245, v245
	v_pk_fma_f32 v[198:199], v[198:199], v[164:165], v[172:173]
	v_pk_fma_f32 v[200:201], v[200:201], v[166:167], v[174:175]
	v_pk_fma_f32 v[202:203], v[202:203], v[168:169], v[156:157]
	v_pk_fma_f32 v[244:245], v[244:245], v[170:171], v[246:247]
	v_cvt_pk_bf16_f32 v164, v198, v199
	v_cvt_pk_bf16_f32 v165, v200, v201
	v_cvt_pk_bf16_f32 v166, v202, v203
	v_cvt_pk_bf16_f32 v167, v244, v245
	global_store_dwordx4 v253, v[164:167], s[42:43]
	s_nop 0
	v_add_u32_e32 v253, 0x2000, v253
	s_waitcnt vmcnt(7)
	v_fmamk_f32 v239, v194, 0x3a800000, v228
	v_rsq_f32_e32 v238, v239
	v_lshlrev_b32_e32 v164, 16, v92
	v_and_b32_e32 v165, 0xffff0000, v92
	v_lshlrev_b32_e32 v166, 16, v93
	v_and_b32_e32 v167, 0xffff0000, v93
	v_lshlrev_b32_e32 v168, 16, v94
	v_and_b32_e32 v169, 0xffff0000, v94
	v_lshlrev_b32_e32 v170, 16, v95
	v_and_b32_e32 v171, 0xffff0000, v95
	v_mul_f32_e32 v238, s45, v238
	v_pk_fma_f32 v[198:199], v[60:61], v[238:239], v[140:141] op_sel_hi:[1,0,1]
	v_pk_fma_f32 v[200:201], v[62:63], v[238:239], v[142:143] op_sel_hi:[1,0,1]
	v_pk_fma_f32 v[202:203], v[56:57], v[238:239], v[136:137] op_sel_hi:[1,0,1]
	v_pk_fma_f32 v[244:245], v[58:59], v[238:239], v[138:139] op_sel_hi:[1,0,1]
	global_load_dwordx4 v[60:63], v252, s[40:41]
	v_add_u32_e32 v252, 0x2000, v252
	v_exp_f32_e32 v198, v198
	v_exp_f32_e32 v199, v199
	v_exp_f32_e32 v200, v200
	v_exp_f32_e32 v201, v201
	v_exp_f32_e32 v202, v202
	v_exp_f32_e32 v203, v203
	v_exp_f32_e32 v244, v244
	v_exp_f32_e32 v245, v245
	v_pk_add_f32 v[198:199], v[198:199], v[254:255] op_sel_hi:[1,0]
	v_pk_add_f32 v[200:201], v[200:201], v[254:255] op_sel_hi:[1,0]
	v_pk_add_f32 v[202:203], v[202:203], v[254:255] op_sel_hi:[1,0]
	v_pk_add_f32 v[244:245], v[244:245], v[254:255] op_sel_hi:[1,0]
	v_rcp_f32_e32 v198, v198
	v_rcp_f32_e32 v199, v199
	v_rcp_f32_e32 v200, v200
	v_rcp_f32_e32 v201, v201
	v_rcp_f32_e32 v202, v202
	v_rcp_f32_e32 v203, v203
	v_rcp_f32_e32 v244, v244
	v_rcp_f32_e32 v245, v245
	v_pk_fma_f32 v[198:199], v[198:199], v[164:165], v[172:173]
	v_pk_fma_f32 v[200:201], v[200:201], v[166:167], v[174:175]
	v_pk_fma_f32 v[202:203], v[202:203], v[168:169], v[156:157]
	v_pk_fma_f32 v[244:245], v[244:245], v[170:171], v[246:247]
	v_cvt_pk_bf16_f32 v164, v198, v199
	v_cvt_pk_bf16_f32 v165, v200, v201
	v_cvt_pk_bf16_f32 v166, v202, v203
	v_cvt_pk_bf16_f32 v167, v244, v245
	global_store_dwordx4 v253, v[164:167], s[42:43]
	s_nop 0
	v_add_u32_e32 v253, 0x2000, v253
	s_waitcnt vmcnt(7)
	v_fmamk_f32 v239, v195, 0x3a800000, v228
	v_rsq_f32_e32 v238, v239
	v_lshlrev_b32_e32 v164, 16, v84
	v_and_b32_e32 v165, 0xffff0000, v84
	v_lshlrev_b32_e32 v166, 16, v85
	v_and_b32_e32 v167, 0xffff0000, v85
	v_lshlrev_b32_e32 v168, 16, v86
	v_and_b32_e32 v169, 0xffff0000, v86
	v_lshlrev_b32_e32 v170, 16, v87
	v_and_b32_e32 v171, 0xffff0000, v87
	v_mul_f32_e32 v238, s45, v238
	v_pk_fma_f32 v[198:199], v[52:53], v[238:239], v[140:141] op_sel_hi:[1,0,1]
	v_pk_fma_f32 v[200:201], v[54:55], v[238:239], v[142:143] op_sel_hi:[1,0,1]
	v_pk_fma_f32 v[202:203], v[48:49], v[238:239], v[136:137] op_sel_hi:[1,0,1]
	v_pk_fma_f32 v[244:245], v[50:51], v[238:239], v[138:139] op_sel_hi:[1,0,1]
	global_load_dwordx4 v[52:55], v252, s[40:41]
	v_add_u32_e32 v252, 0x2000, v252
	v_exp_f32_e32 v198, v198
	v_exp_f32_e32 v199, v199
	v_exp_f32_e32 v200, v200
	v_exp_f32_e32 v201, v201
	v_exp_f32_e32 v202, v202
	v_exp_f32_e32 v203, v203
	v_exp_f32_e32 v244, v244
	v_exp_f32_e32 v245, v245
	v_pk_add_f32 v[198:199], v[198:199], v[254:255] op_sel_hi:[1,0]
	v_pk_add_f32 v[200:201], v[200:201], v[254:255] op_sel_hi:[1,0]
	v_pk_add_f32 v[202:203], v[202:203], v[254:255] op_sel_hi:[1,0]
	v_pk_add_f32 v[244:245], v[244:245], v[254:255] op_sel_hi:[1,0]
	v_rcp_f32_e32 v198, v198
	v_rcp_f32_e32 v199, v199
	v_rcp_f32_e32 v200, v200
	v_rcp_f32_e32 v201, v201
	v_rcp_f32_e32 v202, v202
	v_rcp_f32_e32 v203, v203
	v_rcp_f32_e32 v244, v244
	v_rcp_f32_e32 v245, v245
	v_pk_fma_f32 v[198:199], v[198:199], v[164:165], v[172:173]
	v_pk_fma_f32 v[200:201], v[200:201], v[166:167], v[174:175]
	v_pk_fma_f32 v[202:203], v[202:203], v[168:169], v[156:157]
	v_pk_fma_f32 v[244:245], v[244:245], v[170:171], v[246:247]
	v_cvt_pk_bf16_f32 v164, v198, v199
	v_cvt_pk_bf16_f32 v165, v200, v201
	v_cvt_pk_bf16_f32 v166, v202, v203
	v_cvt_pk_bf16_f32 v167, v244, v245
	global_store_dwordx4 v253, v[164:167], s[42:43]
	s_nop 0
	v_add_u32_e32 v253, 0x2000, v253
	s_waitcnt vmcnt(7)
	v_fmamk_f32 v239, v196, 0x3a800000, v228
	v_rsq_f32_e32 v238, v239
	v_lshlrev_b32_e32 v164, 16, v76
	v_and_b32_e32 v165, 0xffff0000, v76
	v_lshlrev_b32_e32 v166, 16, v77
	v_and_b32_e32 v167, 0xffff0000, v77
	v_lshlrev_b32_e32 v168, 16, v78
	v_and_b32_e32 v169, 0xffff0000, v78
	v_lshlrev_b32_e32 v170, 16, v79
	v_and_b32_e32 v171, 0xffff0000, v79
	v_mul_f32_e32 v238, s45, v238
	v_pk_fma_f32 v[198:199], v[44:45], v[238:239], v[140:141] op_sel_hi:[1,0,1]
	v_pk_fma_f32 v[200:201], v[46:47], v[238:239], v[142:143] op_sel_hi:[1,0,1]
	v_pk_fma_f32 v[202:203], v[40:41], v[238:239], v[136:137] op_sel_hi:[1,0,1]
	v_pk_fma_f32 v[244:245], v[42:43], v[238:239], v[138:139] op_sel_hi:[1,0,1]
	global_load_dwordx4 v[44:47], v252, s[40:41]
	v_add_u32_e32 v252, 0x2000, v252
	v_exp_f32_e32 v198, v198
	v_exp_f32_e32 v199, v199
	v_exp_f32_e32 v200, v200
	v_exp_f32_e32 v201, v201
	v_exp_f32_e32 v202, v202
	v_exp_f32_e32 v203, v203
	v_exp_f32_e32 v244, v244
	v_exp_f32_e32 v245, v245
	v_pk_add_f32 v[198:199], v[198:199], v[254:255] op_sel_hi:[1,0]
	v_pk_add_f32 v[200:201], v[200:201], v[254:255] op_sel_hi:[1,0]
	v_pk_add_f32 v[202:203], v[202:203], v[254:255] op_sel_hi:[1,0]
	v_pk_add_f32 v[244:245], v[244:245], v[254:255] op_sel_hi:[1,0]
	v_rcp_f32_e32 v198, v198
	v_rcp_f32_e32 v199, v199
	v_rcp_f32_e32 v200, v200
	v_rcp_f32_e32 v201, v201
	v_rcp_f32_e32 v202, v202
	v_rcp_f32_e32 v203, v203
	v_rcp_f32_e32 v244, v244
	v_rcp_f32_e32 v245, v245
	v_pk_fma_f32 v[198:199], v[198:199], v[164:165], v[172:173]
	v_pk_fma_f32 v[200:201], v[200:201], v[166:167], v[174:175]
	v_pk_fma_f32 v[202:203], v[202:203], v[168:169], v[156:157]
	v_pk_fma_f32 v[244:245], v[244:245], v[170:171], v[246:247]
	v_cvt_pk_bf16_f32 v164, v198, v199
	v_cvt_pk_bf16_f32 v165, v200, v201
	v_cvt_pk_bf16_f32 v166, v202, v203
	v_cvt_pk_bf16_f32 v167, v244, v245
	global_store_dwordx4 v253, v[164:167], s[42:43]
	s_nop 0
	v_add_u32_e32 v253, 0x2000, v253
	s_waitcnt vmcnt(7)
	v_fmamk_f32 v239, v197, 0x3a800000, v228
	v_rsq_f32_e32 v238, v239
	v_lshlrev_b32_e32 v164, 16, v68
	v_and_b32_e32 v165, 0xffff0000, v68
	v_lshlrev_b32_e32 v166, 16, v69
	v_and_b32_e32 v167, 0xffff0000, v69
	v_lshlrev_b32_e32 v168, 16, v70
	v_and_b32_e32 v169, 0xffff0000, v70
	v_lshlrev_b32_e32 v170, 16, v71
	v_and_b32_e32 v171, 0xffff0000, v71
	v_mul_f32_e32 v238, s45, v238
	v_pk_fma_f32 v[198:199], v[36:37], v[238:239], v[140:141] op_sel_hi:[1,0,1]
	v_pk_fma_f32 v[200:201], v[38:39], v[238:239], v[142:143] op_sel_hi:[1,0,1]
	v_pk_fma_f32 v[202:203], v[32:33], v[238:239], v[136:137] op_sel_hi:[1,0,1]
	v_pk_fma_f32 v[244:245], v[34:35], v[238:239], v[138:139] op_sel_hi:[1,0,1]
	global_load_dwordx4 v[36:39], v252, s[40:41]
	v_add_u32_e32 v252, 0x2000, v252
	v_exp_f32_e32 v198, v198
	v_exp_f32_e32 v199, v199
	v_exp_f32_e32 v200, v200
	v_exp_f32_e32 v201, v201
	v_exp_f32_e32 v202, v202
	v_exp_f32_e32 v203, v203
	v_exp_f32_e32 v244, v244
	v_exp_f32_e32 v245, v245
	v_pk_add_f32 v[198:199], v[198:199], v[254:255] op_sel_hi:[1,0]
	v_pk_add_f32 v[200:201], v[200:201], v[254:255] op_sel_hi:[1,0]
	v_pk_add_f32 v[202:203], v[202:203], v[254:255] op_sel_hi:[1,0]
	v_pk_add_f32 v[244:245], v[244:245], v[254:255] op_sel_hi:[1,0]
	v_rcp_f32_e32 v198, v198
	v_rcp_f32_e32 v199, v199
	v_rcp_f32_e32 v200, v200
	v_rcp_f32_e32 v201, v201
	v_rcp_f32_e32 v202, v202
	v_rcp_f32_e32 v203, v203
	v_rcp_f32_e32 v244, v244
	v_rcp_f32_e32 v245, v245
	v_pk_fma_f32 v[198:199], v[198:199], v[164:165], v[172:173]
	v_pk_fma_f32 v[200:201], v[200:201], v[166:167], v[174:175]
	v_pk_fma_f32 v[202:203], v[202:203], v[168:169], v[156:157]
	v_pk_fma_f32 v[244:245], v[244:245], v[170:171], v[246:247]
	v_cvt_pk_bf16_f32 v164, v198, v199
	v_cvt_pk_bf16_f32 v165, v200, v201
	v_cvt_pk_bf16_f32 v166, v202, v203
	v_cvt_pk_bf16_f32 v167, v244, v245
	global_store_dwordx4 v253, v[164:167], s[42:43]
	s_nop 0
	v_add_u32_e32 v253, 0x2000, v253
	s_waitcnt vmcnt(7)
	v_fmamk_f32 v239, v194, 0x3a800000, v228
	v_rsq_f32_e32 v238, v239
	v_lshlrev_b32_e32 v164, 16, v60
	v_and_b32_e32 v165, 0xffff0000, v60
	v_lshlrev_b32_e32 v166, 16, v61
	v_and_b32_e32 v167, 0xffff0000, v61
	v_lshlrev_b32_e32 v168, 16, v62
	v_and_b32_e32 v169, 0xffff0000, v62
	v_lshlrev_b32_e32 v170, 16, v63
	v_and_b32_e32 v171, 0xffff0000, v63
	v_mul_f32_e32 v238, s45, v238
	v_pk_fma_f32 v[198:199], v[28:29], v[238:239], v[132:133] op_sel_hi:[1,0,1]
	v_pk_fma_f32 v[200:201], v[30:31], v[238:239], v[134:135] op_sel_hi:[1,0,1]
	v_pk_fma_f32 v[202:203], v[24:25], v[238:239], v[128:129] op_sel_hi:[1,0,1]
	v_pk_fma_f32 v[244:245], v[26:27], v[238:239], v[130:131] op_sel_hi:[1,0,1]
	v_exp_f32_e32 v198, v198
	v_exp_f32_e32 v199, v199
	v_exp_f32_e32 v200, v200
	v_exp_f32_e32 v201, v201
	v_exp_f32_e32 v202, v202
	v_exp_f32_e32 v203, v203
	v_exp_f32_e32 v244, v244
	v_exp_f32_e32 v245, v245
	v_pk_add_f32 v[198:199], v[198:199], v[254:255] op_sel_hi:[1,0]
	v_pk_add_f32 v[200:201], v[200:201], v[254:255] op_sel_hi:[1,0]
	v_pk_add_f32 v[202:203], v[202:203], v[254:255] op_sel_hi:[1,0]
	v_pk_add_f32 v[244:245], v[244:245], v[254:255] op_sel_hi:[1,0]
	v_rcp_f32_e32 v198, v198
	v_rcp_f32_e32 v199, v199
	v_rcp_f32_e32 v200, v200
	v_rcp_f32_e32 v201, v201
	v_rcp_f32_e32 v202, v202
	v_rcp_f32_e32 v203, v203
	v_rcp_f32_e32 v244, v244
	v_rcp_f32_e32 v245, v245
	v_pk_fma_f32 v[198:199], v[198:199], v[164:165], v[172:173]
	v_pk_fma_f32 v[200:201], v[200:201], v[166:167], v[174:175]
	v_pk_fma_f32 v[202:203], v[202:203], v[168:169], v[156:157]
	v_pk_fma_f32 v[244:245], v[244:245], v[170:171], v[246:247]
	v_cvt_pk_bf16_f32 v164, v198, v199
	v_cvt_pk_bf16_f32 v165, v200, v201
	v_cvt_pk_bf16_f32 v166, v202, v203
	v_cvt_pk_bf16_f32 v167, v244, v245
	global_store_dwordx4 v253, v[164:167], s[42:43]
	s_nop 0
	v_add_u32_e32 v253, 0x2000, v253
	s_waitcnt vmcnt(6)
	v_fmamk_f32 v239, v195, 0x3a800000, v228
	v_rsq_f32_e32 v238, v239
	v_lshlrev_b32_e32 v164, 16, v52
	v_and_b32_e32 v165, 0xffff0000, v52
	v_lshlrev_b32_e32 v166, 16, v53
	v_and_b32_e32 v167, 0xffff0000, v53
	v_lshlrev_b32_e32 v168, 16, v54
	v_and_b32_e32 v169, 0xffff0000, v54
	v_lshlrev_b32_e32 v170, 16, v55
	v_and_b32_e32 v171, 0xffff0000, v55
	v_mul_f32_e32 v238, s45, v238
	v_pk_fma_f32 v[198:199], v[20:21], v[238:239], v[132:133] op_sel_hi:[1,0,1]
	v_pk_fma_f32 v[200:201], v[22:23], v[238:239], v[134:135] op_sel_hi:[1,0,1]
	v_pk_fma_f32 v[202:203], v[16:17], v[238:239], v[128:129] op_sel_hi:[1,0,1]
	v_pk_fma_f32 v[244:245], v[18:19], v[238:239], v[130:131] op_sel_hi:[1,0,1]
	v_exp_f32_e32 v198, v198
	v_exp_f32_e32 v199, v199
	v_exp_f32_e32 v200, v200
	v_exp_f32_e32 v201, v201
	v_exp_f32_e32 v202, v202
	v_exp_f32_e32 v203, v203
	v_exp_f32_e32 v244, v244
	v_exp_f32_e32 v245, v245
	v_pk_add_f32 v[198:199], v[198:199], v[254:255] op_sel_hi:[1,0]
	v_pk_add_f32 v[200:201], v[200:201], v[254:255] op_sel_hi:[1,0]
	v_pk_add_f32 v[202:203], v[202:203], v[254:255] op_sel_hi:[1,0]
	v_pk_add_f32 v[244:245], v[244:245], v[254:255] op_sel_hi:[1,0]
	v_rcp_f32_e32 v198, v198
	v_rcp_f32_e32 v199, v199
	v_rcp_f32_e32 v200, v200
	v_rcp_f32_e32 v201, v201
	v_rcp_f32_e32 v202, v202
	v_rcp_f32_e32 v203, v203
	v_rcp_f32_e32 v244, v244
	v_rcp_f32_e32 v245, v245
	v_pk_fma_f32 v[198:199], v[198:199], v[164:165], v[172:173]
	v_pk_fma_f32 v[200:201], v[200:201], v[166:167], v[174:175]
	v_pk_fma_f32 v[202:203], v[202:203], v[168:169], v[156:157]
	v_pk_fma_f32 v[244:245], v[244:245], v[170:171], v[246:247]
	v_cvt_pk_bf16_f32 v164, v198, v199
	v_cvt_pk_bf16_f32 v165, v200, v201
	v_cvt_pk_bf16_f32 v166, v202, v203
	v_cvt_pk_bf16_f32 v167, v244, v245
	global_store_dwordx4 v253, v[164:167], s[42:43]
	s_nop 0
	v_add_u32_e32 v253, 0x2000, v253
	s_waitcnt vmcnt(5)
	v_fmamk_f32 v239, v196, 0x3a800000, v228
	v_rsq_f32_e32 v238, v239
	v_lshlrev_b32_e32 v164, 16, v44
	v_and_b32_e32 v165, 0xffff0000, v44
	v_lshlrev_b32_e32 v166, 16, v45
	v_and_b32_e32 v167, 0xffff0000, v45
	v_lshlrev_b32_e32 v168, 16, v46
	v_and_b32_e32 v169, 0xffff0000, v46
	v_lshlrev_b32_e32 v170, 16, v47
	v_and_b32_e32 v171, 0xffff0000, v47
	v_mul_f32_e32 v238, s45, v238
	v_pk_fma_f32 v[198:199], v[12:13], v[238:239], v[132:133] op_sel_hi:[1,0,1]
	v_pk_fma_f32 v[200:201], v[14:15], v[238:239], v[134:135] op_sel_hi:[1,0,1]
	v_pk_fma_f32 v[202:203], v[8:9], v[238:239], v[128:129] op_sel_hi:[1,0,1]
	v_pk_fma_f32 v[244:245], v[10:11], v[238:239], v[130:131] op_sel_hi:[1,0,1]
	v_exp_f32_e32 v198, v198
	v_exp_f32_e32 v199, v199
	v_exp_f32_e32 v200, v200
	v_exp_f32_e32 v201, v201
	v_exp_f32_e32 v202, v202
	v_exp_f32_e32 v203, v203
	v_exp_f32_e32 v244, v244
	v_exp_f32_e32 v245, v245
	v_pk_add_f32 v[198:199], v[198:199], v[254:255] op_sel_hi:[1,0]
	v_pk_add_f32 v[200:201], v[200:201], v[254:255] op_sel_hi:[1,0]
	v_pk_add_f32 v[202:203], v[202:203], v[254:255] op_sel_hi:[1,0]
	v_pk_add_f32 v[244:245], v[244:245], v[254:255] op_sel_hi:[1,0]
	v_rcp_f32_e32 v198, v198
	v_rcp_f32_e32 v199, v199
	v_rcp_f32_e32 v200, v200
	v_rcp_f32_e32 v201, v201
	v_rcp_f32_e32 v202, v202
	v_rcp_f32_e32 v203, v203
	v_rcp_f32_e32 v244, v244
	v_rcp_f32_e32 v245, v245
	v_pk_fma_f32 v[198:199], v[198:199], v[164:165], v[172:173]
	v_pk_fma_f32 v[200:201], v[200:201], v[166:167], v[174:175]
	v_pk_fma_f32 v[202:203], v[202:203], v[168:169], v[156:157]
	v_pk_fma_f32 v[244:245], v[244:245], v[170:171], v[246:247]
	v_cvt_pk_bf16_f32 v164, v198, v199
	v_cvt_pk_bf16_f32 v165, v200, v201
	v_cvt_pk_bf16_f32 v166, v202, v203
	v_cvt_pk_bf16_f32 v167, v244, v245
	global_store_dwordx4 v253, v[164:167], s[42:43]
	s_nop 0
	v_add_u32_e32 v253, 0x2000, v253
	s_waitcnt vmcnt(4)
	v_fmamk_f32 v239, v197, 0x3a800000, v228
	v_rsq_f32_e32 v238, v239
	v_lshlrev_b32_e32 v164, 16, v36
	v_and_b32_e32 v165, 0xffff0000, v36
	v_lshlrev_b32_e32 v166, 16, v37
	v_and_b32_e32 v167, 0xffff0000, v37
	v_lshlrev_b32_e32 v168, 16, v38
	v_and_b32_e32 v169, 0xffff0000, v38
	v_lshlrev_b32_e32 v170, 16, v39
	v_and_b32_e32 v171, 0xffff0000, v39
	v_mul_f32_e32 v238, s45, v238
	v_pk_fma_f32 v[198:199], v[4:5], v[238:239], v[132:133] op_sel_hi:[1,0,1]
	v_pk_fma_f32 v[200:201], v[6:7], v[238:239], v[134:135] op_sel_hi:[1,0,1]
	v_pk_fma_f32 v[202:203], v[0:1], v[238:239], v[128:129] op_sel_hi:[1,0,1]
	v_pk_fma_f32 v[244:245], v[2:3], v[238:239], v[130:131] op_sel_hi:[1,0,1]
	v_exp_f32_e32 v198, v198
	v_exp_f32_e32 v199, v199
	v_exp_f32_e32 v200, v200
	v_exp_f32_e32 v201, v201
	v_exp_f32_e32 v202, v202
	v_exp_f32_e32 v203, v203
	v_exp_f32_e32 v244, v244
	v_exp_f32_e32 v245, v245
	v_pk_add_f32 v[198:199], v[198:199], v[254:255] op_sel_hi:[1,0]
	v_pk_add_f32 v[200:201], v[200:201], v[254:255] op_sel_hi:[1,0]
	v_pk_add_f32 v[202:203], v[202:203], v[254:255] op_sel_hi:[1,0]
	v_pk_add_f32 v[244:245], v[244:245], v[254:255] op_sel_hi:[1,0]
	v_rcp_f32_e32 v198, v198
	v_rcp_f32_e32 v199, v199
	v_rcp_f32_e32 v200, v200
	v_rcp_f32_e32 v201, v201
	v_rcp_f32_e32 v202, v202
	v_rcp_f32_e32 v203, v203
	v_rcp_f32_e32 v244, v244
	v_rcp_f32_e32 v245, v245
	v_pk_fma_f32 v[198:199], v[198:199], v[164:165], v[172:173]
	v_pk_fma_f32 v[200:201], v[200:201], v[166:167], v[174:175]
	v_pk_fma_f32 v[202:203], v[202:203], v[168:169], v[156:157]
	v_pk_fma_f32 v[244:245], v[244:245], v[170:171], v[246:247]
	v_cvt_pk_bf16_f32 v164, v198, v199
	v_cvt_pk_bf16_f32 v165, v200, v201
	v_cvt_pk_bf16_f32 v166, v202, v203
	v_cvt_pk_bf16_f32 v167, v244, v245
	global_store_dwordx4 v253, v[164:167], s[42:43]
	s_nop 0
	v_add_u32_e32 v253, 0x2000, v253
	s_branch .LBB0_1002
.Lmrg_b3:
	global_load_dwordx4 v[144:147], v252, s[40:41]
	global_load_dwordx4 v[148:151], v252, s[42:43]
	v_add_u32_e32 v252, 0x2000, v252
	global_load_dwordx4 v[152:155], v252, s[40:41]
	global_load_dwordx4 v[208:211], v252, s[42:43]
	v_add_u32_e32 v252, 0x2000, v252
	global_load_dwordx4 v[212:215], v252, s[40:41]
	global_load_dwordx4 v[216:219], v252, s[42:43]
	v_add_u32_e32 v252, 0x2000, v252
	global_load_dwordx4 v[220:223], v252, s[40:41]
	global_load_dwordx4 v[240:243], v252, s[42:43]
	v_add_u32_e32 v252, 0x2000, v252
	s_waitcnt vmcnt(6)
	v_mul_f32_e32 v128, s45, v128
	v_mul_f32_e32 v129, s45, v129
	v_mul_f32_e32 v130, s45, v130
	v_mul_f32_e32 v131, s45, v131
	v_mul_f32_e32 v132, s45, v132
	v_mul_f32_e32 v133, s45, v133
	v_mul_f32_e32 v134, s45, v134
	v_mul_f32_e32 v135, s45, v135
	v_mul_f32_e32 v136, s45, v136
	v_mul_f32_e32 v137, s45, v137
	v_mul_f32_e32 v138, s45, v138
	v_mul_f32_e32 v139, s45, v139
	v_mul_f32_e32 v140, s45, v140
	v_mul_f32_e32 v141, s45, v141
	v_mul_f32_e32 v142, s45, v142
	v_mul_f32_e32 v143, s45, v143
	v_fmamk_f32 v239, v190, 0x3a800000, v228
	v_rsq_f32_e32 v238, v239
	v_lshlrev_b32_e32 v164, 16, v144
	v_and_b32_e32 v165, 0xffff0000, v144
	v_lshlrev_b32_e32 v166, 16, v145
	v_and_b32_e32 v167, 0xffff0000, v145
	v_lshlrev_b32_e32 v168, 16, v146
	v_and_b32_e32 v169, 0xffff0000, v146
	v_lshlrev_b32_e32 v170, 16, v147
	v_and_b32_e32 v171, 0xffff0000, v147
	v_mul_f32_e32 v238, s45, v238
	v_lshlrev_b32_e32 v172, 16, v148
	v_and_b32_e32 v173, 0xffff0000, v148
	v_lshlrev_b32_e32 v174, 16, v149
	v_and_b32_e32 v175, 0xffff0000, v149
	v_lshlrev_b32_e32 v156, 16, v150
	v_and_b32_e32 v157, 0xffff0000, v150
	v_lshlrev_b32_e32 v246, 16, v151
	v_and_b32_e32 v247, 0xffff0000, v151
	v_pk_fma_f32 v[198:199], v[124:125], v[238:239], v[140:141] op_sel_hi:[1,0,1]
	v_pk_fma_f32 v[200:201], v[126:127], v[238:239], v[142:143] op_sel_hi:[1,0,1]
	v_pk_fma_f32 v[202:203], v[120:121], v[238:239], v[136:137] op_sel_hi:[1,0,1]
	v_pk_fma_f32 v[244:245], v[122:123], v[238:239], v[138:139] op_sel_hi:[1,0,1]
	global_load_dwordx4 v[124:127], v252, s[40:41]
	global_load_dwordx4 v[120:123], v252, s[42:43]
	v_add_u32_e32 v252, 0x2000, v252
	v_exp_f32_e32 v198, v198
	v_exp_f32_e32 v199, v199
	v_exp_f32_e32 v200, v200
	v_exp_f32_e32 v201, v201
	v_exp_f32_e32 v202, v202
	v_exp_f32_e32 v203, v203
	v_exp_f32_e32 v244, v244
	v_exp_f32_e32 v245, v245
	v_pk_add_f32 v[198:199], v[198:199], v[254:255] op_sel_hi:[1,0]
	v_pk_add_f32 v[200:201], v[200:201], v[254:255] op_sel_hi:[1,0]
	v_pk_add_f32 v[202:203], v[202:203], v[254:255] op_sel_hi:[1,0]
	v_pk_add_f32 v[244:245], v[244:245], v[254:255] op_sel_hi:[1,0]
	v_rcp_f32_e32 v198, v198
	v_rcp_f32_e32 v199, v199
	v_rcp_f32_e32 v200, v200
	v_rcp_f32_e32 v201, v201
	v_rcp_f32_e32 v202, v202
	v_rcp_f32_e32 v203, v203
	v_rcp_f32_e32 v244, v244
	v_rcp_f32_e32 v245, v245
	v_pk_fma_f32 v[198:199], v[198:199], v[164:165], v[172:173]
	v_pk_fma_f32 v[200:201], v[200:201], v[166:167], v[174:175]
	v_pk_fma_f32 v[202:203], v[202:203], v[168:169], v[156:157]
	v_pk_fma_f32 v[244:245], v[244:245], v[170:171], v[246:247]
	v_cvt_pk_bf16_f32 v164, v198, v199
	v_cvt_pk_bf16_f32 v165, v200, v201
	v_cvt_pk_bf16_f32 v166, v202, v203
	v_cvt_pk_bf16_f32 v167, v244, v245
	v_add_u32_e32 v253, 0x0, v255
	global_store_dwordx2 v253, v[164:165], s[36:37]
	global_store_dwordx2 v253, v[166:167], s[36:37] offset:32
	s_waitcnt vmcnt(8)
	v_fmamk_f32 v239, v191, 0x3a800000, v228
	v_rsq_f32_e32 v238, v239
	v_lshlrev_b32_e32 v164, 16, v152
	v_and_b32_e32 v165, 0xffff0000, v152
	v_lshlrev_b32_e32 v166, 16, v153
	v_and_b32_e32 v167, 0xffff0000, v153
	v_lshlrev_b32_e32 v168, 16, v154
	v_and_b32_e32 v169, 0xffff0000, v154
	v_lshlrev_b32_e32 v170, 16, v155
	v_and_b32_e32 v171, 0xffff0000, v155
	v_mul_f32_e32 v238, s45, v238
	v_lshlrev_b32_e32 v172, 16, v208
	v_and_b32_e32 v173, 0xffff0000, v208
	v_lshlrev_b32_e32 v174, 16, v209
	v_and_b32_e32 v175, 0xffff0000, v209
	v_lshlrev_b32_e32 v156, 16, v210
	v_and_b32_e32 v157, 0xffff0000, v210
	v_lshlrev_b32_e32 v246, 16, v211
	v_and_b32_e32 v247, 0xffff0000, v211
	v_pk_fma_f32 v[198:199], v[116:117], v[238:239], v[140:141] op_sel_hi:[1,0,1]
	v_pk_fma_f32 v[200:201], v[118:119], v[238:239], v[142:143] op_sel_hi:[1,0,1]
	v_pk_fma_f32 v[202:203], v[112:113], v[238:239], v[136:137] op_sel_hi:[1,0,1]
	v_pk_fma_f32 v[244:245], v[114:115], v[238:239], v[138:139] op_sel_hi:[1,0,1]
	global_load_dwordx4 v[116:119], v252, s[40:41]
	global_load_dwordx4 v[112:115], v252, s[42:43]
	v_add_u32_e32 v252, 0x2000, v252
	v_exp_f32_e32 v198, v198
	v_exp_f32_e32 v199, v199
	v_exp_f32_e32 v200, v200
	v_exp_f32_e32 v201, v201
	v_exp_f32_e32 v202, v202
	v_exp_f32_e32 v203, v203
	v_exp_f32_e32 v244, v244
	v_exp_f32_e32 v245, v245
	v_pk_add_f32 v[198:199], v[198:199], v[254:255] op_sel_hi:[1,0]
	v_pk_add_f32 v[200:201], v[200:201], v[254:255] op_sel_hi:[1,0]
	v_pk_add_f32 v[202:203], v[202:203], v[254:255] op_sel_hi:[1,0]
	v_pk_add_f32 v[244:245], v[244:245], v[254:255] op_sel_hi:[1,0]
	v_rcp_f32_e32 v198, v198
	v_rcp_f32_e32 v199, v199
	v_rcp_f32_e32 v200, v200
	v_rcp_f32_e32 v201, v201
	v_rcp_f32_e32 v202, v202
	v_rcp_f32_e32 v203, v203
	v_rcp_f32_e32 v244, v244
	v_rcp_f32_e32 v245, v245
	v_pk_fma_f32 v[198:199], v[198:199], v[164:165], v[172:173]
	v_pk_fma_f32 v[200:201], v[200:201], v[166:167], v[174:175]
	v_pk_fma_f32 v[202:203], v[202:203], v[168:169], v[156:157]
	v_pk_fma_f32 v[244:245], v[244:245], v[170:171], v[246:247]
	v_cvt_pk_bf16_f32 v164, v198, v199
	v_cvt_pk_bf16_f32 v165, v200, v201
	v_cvt_pk_bf16_f32 v166, v202, v203
	v_cvt_pk_bf16_f32 v167, v244, v245
	v_add_u32_e32 v253, 0x8000, v255
	global_store_dwordx2 v253, v[164:165], s[36:37]
	global_store_dwordx2 v253, v[166:167], s[36:37] offset:32
	s_waitcnt vmcnt(10)
	v_fmamk_f32 v239, v192, 0x3a800000, v228
	v_rsq_f32_e32 v238, v239
	v_lshlrev_b32_e32 v164, 16, v212
	v_and_b32_e32 v165, 0xffff0000, v212
	v_lshlrev_b32_e32 v166, 16, v213
	v_and_b32_e32 v167, 0xffff0000, v213
	v_lshlrev_b32_e32 v168, 16, v214
	v_and_b32_e32 v169, 0xffff0000, v214
	v_lshlrev_b32_e32 v170, 16, v215
	v_and_b32_e32 v171, 0xffff0000, v215
	v_mul_f32_e32 v238, s45, v238
	v_lshlrev_b32_e32 v172, 16, v216
	v_and_b32_e32 v173, 0xffff0000, v216
	v_lshlrev_b32_e32 v174, 16, v217
	v_and_b32_e32 v175, 0xffff0000, v217
	v_lshlrev_b32_e32 v156, 16, v218
	v_and_b32_e32 v157, 0xffff0000, v218
	v_lshlrev_b32_e32 v246, 16, v219
	v_and_b32_e32 v247, 0xffff0000, v219
	v_pk_fma_f32 v[198:199], v[108:109], v[238:239], v[140:141] op_sel_hi:[1,0,1]
	v_pk_fma_f32 v[200:201], v[110:111], v[238:239], v[142:143] op_sel_hi:[1,0,1]
	v_pk_fma_f32 v[202:203], v[104:105], v[238:239], v[136:137] op_sel_hi:[1,0,1]
	v_pk_fma_f32 v[244:245], v[106:107], v[238:239], v[138:139] op_sel_hi:[1,0,1]
	global_load_dwordx4 v[108:111], v252, s[40:41]
	global_load_dwordx4 v[104:107], v252, s[42:43]
	v_add_u32_e32 v252, 0x2000, v252
	v_exp_f32_e32 v198, v198
	v_exp_f32_e32 v199, v199
	v_exp_f32_e32 v200, v200
	v_exp_f32_e32 v201, v201
	v_exp_f32_e32 v202, v202
	v_exp_f32_e32 v203, v203
	v_exp_f32_e32 v244, v244
	v_exp_f32_e32 v245, v245
	v_pk_add_f32 v[198:199], v[198:199], v[254:255] op_sel_hi:[1,0]
	v_pk_add_f32 v[200:201], v[200:201], v[254:255] op_sel_hi:[1,0]
	v_pk_add_f32 v[202:203], v[202:203], v[254:255] op_sel_hi:[1,0]
	v_pk_add_f32 v[244:245], v[244:245], v[254:255] op_sel_hi:[1,0]
	v_rcp_f32_e32 v198, v198
	v_rcp_f32_e32 v199, v199
	v_rcp_f32_e32 v200, v200
	v_rcp_f32_e32 v201, v201
	v_rcp_f32_e32 v202, v202
	v_rcp_f32_e32 v203, v203
	v_rcp_f32_e32 v244, v244
	v_rcp_f32_e32 v245, v245
	v_pk_fma_f32 v[198:199], v[198:199], v[164:165], v[172:173]
	v_pk_fma_f32 v[200:201], v[200:201], v[166:167], v[174:175]
	v_pk_fma_f32 v[202:203], v[202:203], v[168:169], v[156:157]
	v_pk_fma_f32 v[244:245], v[244:245], v[170:171], v[246:247]
	v_cvt_pk_bf16_f32 v164, v198, v199
	v_cvt_pk_bf16_f32 v165, v200, v201
	v_cvt_pk_bf16_f32 v166, v202, v203
	v_cvt_pk_bf16_f32 v167, v244, v245
	v_add_u32_e32 v253, 0x10000, v255
	global_store_dwordx2 v253, v[164:165], s[36:37]
	global_store_dwordx2 v253, v[166:167], s[36:37] offset:32
	s_waitcnt vmcnt(12)
	v_fmamk_f32 v239, v193, 0x3a800000, v228
	v_rsq_f32_e32 v238, v239
	v_lshlrev_b32_e32 v164, 16, v220
	v_and_b32_e32 v165, 0xffff0000, v220
	v_lshlrev_b32_e32 v166, 16, v221
	v_and_b32_e32 v167, 0xffff0000, v221
	v_lshlrev_b32_e32 v168, 16, v222
	v_and_b32_e32 v169, 0xffff0000, v222
	v_lshlrev_b32_e32 v170, 16, v223
	v_and_b32_e32 v171, 0xffff0000, v223
	v_mul_f32_e32 v238, s45, v238
	v_lshlrev_b32_e32 v172, 16, v240
	v_and_b32_e32 v173, 0xffff0000, v240
	v_lshlrev_b32_e32 v174, 16, v241
	v_and_b32_e32 v175, 0xffff0000, v241
	v_lshlrev_b32_e32 v156, 16, v242
	v_and_b32_e32 v157, 0xffff0000, v242
	v_lshlrev_b32_e32 v246, 16, v243
	v_and_b32_e32 v247, 0xffff0000, v243
	v_pk_fma_f32 v[198:199], v[100:101], v[238:239], v[140:141] op_sel_hi:[1,0,1]
	v_pk_fma_f32 v[200:201], v[102:103], v[238:239], v[142:143] op_sel_hi:[1,0,1]
	v_pk_fma_f32 v[202:203], v[96:97], v[238:239], v[136:137] op_sel_hi:[1,0,1]
	v_pk_fma_f32 v[244:245], v[98:99], v[238:239], v[138:139] op_sel_hi:[1,0,1]
	global_load_dwordx4 v[100:103], v252, s[40:41]
	global_load_dwordx4 v[96:99], v252, s[42:43]
	v_add_u32_e32 v252, 0x2000, v252
	v_exp_f32_e32 v198, v198
	v_exp_f32_e32 v199, v199
	v_exp_f32_e32 v200, v200
	v_exp_f32_e32 v201, v201
	v_exp_f32_e32 v202, v202
	v_exp_f32_e32 v203, v203
	v_exp_f32_e32 v244, v244
	v_exp_f32_e32 v245, v245
	v_pk_add_f32 v[198:199], v[198:199], v[254:255] op_sel_hi:[1,0]
	v_pk_add_f32 v[200:201], v[200:201], v[254:255] op_sel_hi:[1,0]
	v_pk_add_f32 v[202:203], v[202:203], v[254:255] op_sel_hi:[1,0]
	v_pk_add_f32 v[244:245], v[244:245], v[254:255] op_sel_hi:[1,0]
	v_rcp_f32_e32 v198, v198
	v_rcp_f32_e32 v199, v199
	v_rcp_f32_e32 v200, v200
	v_rcp_f32_e32 v201, v201
	v_rcp_f32_e32 v202, v202
	v_rcp_f32_e32 v203, v203
	v_rcp_f32_e32 v244, v244
	v_rcp_f32_e32 v245, v245
	v_pk_fma_f32 v[198:199], v[198:199], v[164:165], v[172:173]
	v_pk_fma_f32 v[200:201], v[200:201], v[166:167], v[174:175]
	v_pk_fma_f32 v[202:203], v[202:203], v[168:169], v[156:157]
	v_pk_fma_f32 v[244:245], v[244:245], v[170:171], v[246:247]
	v_cvt_pk_bf16_f32 v164, v198, v199
	v_cvt_pk_bf16_f32 v165, v200, v201
	v_cvt_pk_bf16_f32 v166, v202, v203
	v_cvt_pk_bf16_f32 v167, v244, v245
	v_add_u32_e32 v253, 0x18000, v255
	global_store_dwordx2 v253, v[164:165], s[36:37]
	global_store_dwordx2 v253, v[166:167], s[36:37] offset:32
	s_waitcnt vmcnt(14)
	v_fmamk_f32 v239, v190, 0x3a800000, v228
	v_rsq_f32_e32 v238, v239
	v_lshlrev_b32_e32 v164, 16, v124
	v_and_b32_e32 v165, 0xffff0000, v124
	v_lshlrev_b32_e32 v166, 16, v125
	v_and_b32_e32 v167, 0xffff0000, v125
	v_lshlrev_b32_e32 v168, 16, v126
	v_and_b32_e32 v169, 0xffff0000, v126
	v_lshlrev_b32_e32 v170, 16, v127
	v_and_b32_e32 v171, 0xffff0000, v127
	v_mul_f32_e32 v238, s45, v238
	v_lshlrev_b32_e32 v172, 16, v120
	v_and_b32_e32 v173, 0xffff0000, v120
	v_lshlrev_b32_e32 v174, 16, v121
	v_and_b32_e32 v175, 0xffff0000, v121
	v_lshlrev_b32_e32 v156, 16, v122
	v_and_b32_e32 v157, 0xffff0000, v122
	v_lshlrev_b32_e32 v246, 16, v123
	v_and_b32_e32 v247, 0xffff0000, v123
	v_pk_fma_f32 v[198:199], v[92:93], v[238:239], v[132:133] op_sel_hi:[1,0,1]
	v_pk_fma_f32 v[200:201], v[94:95], v[238:239], v[134:135] op_sel_hi:[1,0,1]
	v_pk_fma_f32 v[202:203], v[88:89], v[238:239], v[128:129] op_sel_hi:[1,0,1]
	v_pk_fma_f32 v[244:245], v[90:91], v[238:239], v[130:131] op_sel_hi:[1,0,1]
	global_load_dwordx4 v[92:95], v252, s[40:41]
	global_load_dwordx4 v[88:91], v252, s[42:43]
	v_add_u32_e32 v252, 0x2000, v252
	v_exp_f32_e32 v198, v198
	v_exp_f32_e32 v199, v199
	v_exp_f32_e32 v200, v200
	v_exp_f32_e32 v201, v201
	v_exp_f32_e32 v202, v202
	v_exp_f32_e32 v203, v203
	v_exp_f32_e32 v244, v244
	v_exp_f32_e32 v245, v245
	v_pk_add_f32 v[198:199], v[198:199], v[254:255] op_sel_hi:[1,0]
	v_pk_add_f32 v[200:201], v[200:201], v[254:255] op_sel_hi:[1,0]
	v_pk_add_f32 v[202:203], v[202:203], v[254:255] op_sel_hi:[1,0]
	v_pk_add_f32 v[244:245], v[244:245], v[254:255] op_sel_hi:[1,0]
	v_rcp_f32_e32 v198, v198
	v_rcp_f32_e32 v199, v199
	v_rcp_f32_e32 v200, v200
	v_rcp_f32_e32 v201, v201
	v_rcp_f32_e32 v202, v202
	v_rcp_f32_e32 v203, v203
	v_rcp_f32_e32 v244, v244
	v_rcp_f32_e32 v245, v245
	v_pk_fma_f32 v[198:199], v[198:199], v[164:165], v[172:173]
	v_pk_fma_f32 v[200:201], v[200:201], v[166:167], v[174:175]
	v_pk_fma_f32 v[202:203], v[202:203], v[168:169], v[156:157]
	v_pk_fma_f32 v[244:245], v[244:245], v[170:171], v[246:247]
	v_cvt_pk_bf16_f32 v164, v198, v199
	v_cvt_pk_bf16_f32 v165, v200, v201
	v_cvt_pk_bf16_f32 v166, v202, v203
	v_cvt_pk_bf16_f32 v167, v244, v245
	v_add_u32_e32 v253, 0x100, v255
	global_store_dwordx2 v253, v[164:165], s[36:37]
	global_store_dwordx2 v253, v[166:167], s[36:37] offset:32
	s_waitcnt vmcnt(14)
	v_fmamk_f32 v239, v191, 0x3a800000, v228
	v_rsq_f32_e32 v238, v239
	v_lshlrev_b32_e32 v164, 16, v116
	v_and_b32_e32 v165, 0xffff0000, v116
	v_lshlrev_b32_e32 v166, 16, v117
	v_and_b32_e32 v167, 0xffff0000, v117
	v_lshlrev_b32_e32 v168, 16, v118
	v_and_b32_e32 v169, 0xffff0000, v118
	v_lshlrev_b32_e32 v170, 16, v119
	v_and_b32_e32 v171, 0xffff0000, v119
	v_mul_f32_e32 v238, s45, v238
	v_lshlrev_b32_e32 v172, 16, v112
	v_and_b32_e32 v173, 0xffff0000, v112
	v_lshlrev_b32_e32 v174, 16, v113
	v_and_b32_e32 v175, 0xffff0000, v113
	v_lshlrev_b32_e32 v156, 16, v114
	v_and_b32_e32 v157, 0xffff0000, v114
	v_lshlrev_b32_e32 v246, 16, v115
	v_and_b32_e32 v247, 0xffff0000, v115
	v_pk_fma_f32 v[198:199], v[84:85], v[238:239], v[132:133] op_sel_hi:[1,0,1]
	v_pk_fma_f32 v[200:201], v[86:87], v[238:239], v[134:135] op_sel_hi:[1,0,1]
	v_pk_fma_f32 v[202:203], v[80:81], v[238:239], v[128:129] op_sel_hi:[1,0,1]
	v_pk_fma_f32 v[244:245], v[82:83], v[238:239], v[130:131] op_sel_hi:[1,0,1]
	global_load_dwordx4 v[84:87], v252, s[40:41]
	global_load_dwordx4 v[80:83], v252, s[42:43]
	v_add_u32_e32 v252, 0x2000, v252
	v_exp_f32_e32 v198, v198
	v_exp_f32_e32 v199, v199
	v_exp_f32_e32 v200, v200
	v_exp_f32_e32 v201, v201
	v_exp_f32_e32 v202, v202
	v_exp_f32_e32 v203, v203
	v_exp_f32_e32 v244, v244
	v_exp_f32_e32 v245, v245
	v_pk_add_f32 v[198:199], v[198:199], v[254:255] op_sel_hi:[1,0]
	v_pk_add_f32 v[200:201], v[200:201], v[254:255] op_sel_hi:[1,0]
	v_pk_add_f32 v[202:203], v[202:203], v[254:255] op_sel_hi:[1,0]
	v_pk_add_f32 v[244:245], v[244:245], v[254:255] op_sel_hi:[1,0]
	v_rcp_f32_e32 v198, v198
	v_rcp_f32_e32 v199, v199
	v_rcp_f32_e32 v200, v200
	v_rcp_f32_e32 v201, v201
	v_rcp_f32_e32 v202, v202
	v_rcp_f32_e32 v203, v203
	v_rcp_f32_e32 v244, v244
	v_rcp_f32_e32 v245, v245
	v_pk_fma_f32 v[198:199], v[198:199], v[164:165], v[172:173]
	v_pk_fma_f32 v[200:201], v[200:201], v[166:167], v[174:175]
	v_pk_fma_f32 v[202:203], v[202:203], v[168:169], v[156:157]
	v_pk_fma_f32 v[244:245], v[244:245], v[170:171], v[246:247]
	v_cvt_pk_bf16_f32 v164, v198, v199
	v_cvt_pk_bf16_f32 v165, v200, v201
	v_cvt_pk_bf16_f32 v166, v202, v203
	v_cvt_pk_bf16_f32 v167, v244, v245
	v_add_u32_e32 v253, 0x8100, v255
	global_store_dwordx2 v253, v[164:165], s[36:37]
	global_store_dwordx2 v253, v[166:167], s[36:37] offset:32
	s_waitcnt vmcnt(14)
	v_fmamk_f32 v239, v192, 0x3a800000, v228
	v_rsq_f32_e32 v238, v239
	v_lshlrev_b32_e32 v164, 16, v108
	v_and_b32_e32 v165, 0xffff0000, v108
	v_lshlrev_b32_e32 v166, 16, v109
	v_and_b32_e32 v167, 0xffff0000, v109
	v_lshlrev_b32_e32 v168, 16, v110
	v_and_b32_e32 v169, 0xffff0000, v110
	v_lshlrev_b32_e32 v170, 16, v111
	v_and_b32_e32 v171, 0xffff0000, v111
	v_mul_f32_e32 v238, s45, v238
	v_lshlrev_b32_e32 v172, 16, v104
	v_and_b32_e32 v173, 0xffff0000, v104
	v_lshlrev_b32_e32 v174, 16, v105
	v_and_b32_e32 v175, 0xffff0000, v105
	v_lshlrev_b32_e32 v156, 16, v106
	v_and_b32_e32 v157, 0xffff0000, v106
	v_lshlrev_b32_e32 v246, 16, v107
	v_and_b32_e32 v247, 0xffff0000, v107
	v_pk_fma_f32 v[198:199], v[76:77], v[238:239], v[132:133] op_sel_hi:[1,0,1]
	v_pk_fma_f32 v[200:201], v[78:79], v[238:239], v[134:135] op_sel_hi:[1,0,1]
	v_pk_fma_f32 v[202:203], v[72:73], v[238:239], v[128:129] op_sel_hi:[1,0,1]
	v_pk_fma_f32 v[244:245], v[74:75], v[238:239], v[130:131] op_sel_hi:[1,0,1]
	global_load_dwordx4 v[76:79], v252, s[40:41]
	global_load_dwordx4 v[72:75], v252, s[42:43]
	v_add_u32_e32 v252, 0x2000, v252
	v_exp_f32_e32 v198, v198
	v_exp_f32_e32 v199, v199
	v_exp_f32_e32 v200, v200
	v_exp_f32_e32 v201, v201
	v_exp_f32_e32 v202, v202
	v_exp_f32_e32 v203, v203
	v_exp_f32_e32 v244, v244
	v_exp_f32_e32 v245, v245
	v_pk_add_f32 v[198:199], v[198:199], v[254:255] op_sel_hi:[1,0]
	v_pk_add_f32 v[200:201], v[200:201], v[254:255] op_sel_hi:[1,0]
	v_pk_add_f32 v[202:203], v[202:203], v[254:255] op_sel_hi:[1,0]
	v_pk_add_f32 v[244:245], v[244:245], v[254:255] op_sel_hi:[1,0]
	v_rcp_f32_e32 v198, v198
	v_rcp_f32_e32 v199, v199
	v_rcp_f32_e32 v200, v200
	v_rcp_f32_e32 v201, v201
	v_rcp_f32_e32 v202, v202
	v_rcp_f32_e32 v203, v203
	v_rcp_f32_e32 v244, v244
	v_rcp_f32_e32 v245, v245
	v_pk_fma_f32 v[198:199], v[198:199], v[164:165], v[172:173]
	v_pk_fma_f32 v[200:201], v[200:201], v[166:167], v[174:175]
	v_pk_fma_f32 v[202:203], v[202:203], v[168:169], v[156:157]
	v_pk_fma_f32 v[244:245], v[244:245], v[170:171], v[246:247]
	v_cvt_pk_bf16_f32 v164, v198, v199
	v_cvt_pk_bf16_f32 v165, v200, v201
	v_cvt_pk_bf16_f32 v166, v202, v203
	v_cvt_pk_bf16_f32 v167, v244, v245
	v_add_u32_e32 v253, 0x10100, v255
	global_store_dwordx2 v253, v[164:165], s[36:37]
	global_store_dwordx2 v253, v[166:167], s[36:37] offset:32
	s_waitcnt vmcnt(14)
	v_fmamk_f32 v239, v193, 0x3a800000, v228
	v_rsq_f32_e32 v238, v239
	v_lshlrev_b32_e32 v164, 16, v100
	v_and_b32_e32 v165, 0xffff0000, v100
	v_lshlrev_b32_e32 v166, 16, v101
	v_and_b32_e32 v167, 0xffff0000, v101
	v_lshlrev_b32_e32 v168, 16, v102
	v_and_b32_e32 v169, 0xffff0000, v102
	v_lshlrev_b32_e32 v170, 16, v103
	v_and_b32_e32 v171, 0xffff0000, v103
	v_mul_f32_e32 v238, s45, v238
	v_lshlrev_b32_e32 v172, 16, v96
	v_and_b32_e32 v173, 0xffff0000, v96
	v_lshlrev_b32_e32 v174, 16, v97
	v_and_b32_e32 v175, 0xffff0000, v97
	v_lshlrev_b32_e32 v156, 16, v98
	v_and_b32_e32 v157, 0xffff0000, v98
	v_lshlrev_b32_e32 v246, 16, v99
	v_and_b32_e32 v247, 0xffff0000, v99
	v_pk_fma_f32 v[198:199], v[68:69], v[238:239], v[132:133] op_sel_hi:[1,0,1]
	v_pk_fma_f32 v[200:201], v[70:71], v[238:239], v[134:135] op_sel_hi:[1,0,1]
	v_pk_fma_f32 v[202:203], v[64:65], v[238:239], v[128:129] op_sel_hi:[1,0,1]
	v_pk_fma_f32 v[244:245], v[66:67], v[238:239], v[130:131] op_sel_hi:[1,0,1]
	global_load_dwordx4 v[68:71], v252, s[40:41]
	global_load_dwordx4 v[64:67], v252, s[42:43]
	v_add_u32_e32 v252, 0x2000, v252
	v_exp_f32_e32 v198, v198
	v_exp_f32_e32 v199, v199
	v_exp_f32_e32 v200, v200
	v_exp_f32_e32 v201, v201
	v_exp_f32_e32 v202, v202
	v_exp_f32_e32 v203, v203
	v_exp_f32_e32 v244, v244
	v_exp_f32_e32 v245, v245
	v_pk_add_f32 v[198:199], v[198:199], v[254:255] op_sel_hi:[1,0]
	v_pk_add_f32 v[200:201], v[200:201], v[254:255] op_sel_hi:[1,0]
	v_pk_add_f32 v[202:203], v[202:203], v[254:255] op_sel_hi:[1,0]
	v_pk_add_f32 v[244:245], v[244:245], v[254:255] op_sel_hi:[1,0]
	v_rcp_f32_e32 v198, v198
	v_rcp_f32_e32 v199, v199
	v_rcp_f32_e32 v200, v200
	v_rcp_f32_e32 v201, v201
	v_rcp_f32_e32 v202, v202
	v_rcp_f32_e32 v203, v203
	v_rcp_f32_e32 v244, v244
	v_rcp_f32_e32 v245, v245
	v_pk_fma_f32 v[198:199], v[198:199], v[164:165], v[172:173]
	v_pk_fma_f32 v[200:201], v[200:201], v[166:167], v[174:175]
	v_pk_fma_f32 v[202:203], v[202:203], v[168:169], v[156:157]
	v_pk_fma_f32 v[244:245], v[244:245], v[170:171], v[246:247]
	v_cvt_pk_bf16_f32 v164, v198, v199
	v_cvt_pk_bf16_f32 v165, v200, v201
	v_cvt_pk_bf16_f32 v166, v202, v203
	v_cvt_pk_bf16_f32 v167, v244, v245
	v_add_u32_e32 v253, 0x18100, v255
	global_store_dwordx2 v253, v[164:165], s[36:37]
	global_store_dwordx2 v253, v[166:167], s[36:37] offset:32
	s_waitcnt vmcnt(14)
	v_fmamk_f32 v239, v194, 0x3a800000, v228
	v_rsq_f32_e32 v238, v239
	v_lshlrev_b32_e32 v164, 16, v92
	v_and_b32_e32 v165, 0xffff0000, v92
	v_lshlrev_b32_e32 v166, 16, v93
	v_and_b32_e32 v167, 0xffff0000, v93
	v_lshlrev_b32_e32 v168, 16, v94
	v_and_b32_e32 v169, 0xffff0000, v94
	v_lshlrev_b32_e32 v170, 16, v95
	v_and_b32_e32 v171, 0xffff0000, v95
	v_mul_f32_e32 v238, s45, v238
	v_lshlrev_b32_e32 v172, 16, v88
	v_and_b32_e32 v173, 0xffff0000, v88
	v_lshlrev_b32_e32 v174, 16, v89
	v_and_b32_e32 v175, 0xffff0000, v89
	v_lshlrev_b32_e32 v156, 16, v90
	v_and_b32_e32 v157, 0xffff0000, v90
	v_lshlrev_b32_e32 v246, 16, v91
	v_and_b32_e32 v247, 0xffff0000, v91
	v_pk_fma_f32 v[198:199], v[60:61], v[238:239], v[140:141] op_sel_hi:[1,0,1]
	v_pk_fma_f32 v[200:201], v[62:63], v[238:239], v[142:143] op_sel_hi:[1,0,1]
	v_pk_fma_f32 v[202:203], v[56:57], v[238:239], v[136:137] op_sel_hi:[1,0,1]
	v_pk_fma_f32 v[244:245], v[58:59], v[238:239], v[138:139] op_sel_hi:[1,0,1]
	global_load_dwordx4 v[60:63], v252, s[40:41]
	global_load_dwordx4 v[56:59], v252, s[42:43]
	v_add_u32_e32 v252, 0x2000, v252
	v_exp_f32_e32 v198, v198
	v_exp_f32_e32 v199, v199
	v_exp_f32_e32 v200, v200
	v_exp_f32_e32 v201, v201
	v_exp_f32_e32 v202, v202
	v_exp_f32_e32 v203, v203
	v_exp_f32_e32 v244, v244
	v_exp_f32_e32 v245, v245
	v_pk_add_f32 v[198:199], v[198:199], v[254:255] op_sel_hi:[1,0]
	v_pk_add_f32 v[200:201], v[200:201], v[254:255] op_sel_hi:[1,0]
	v_pk_add_f32 v[202:203], v[202:203], v[254:255] op_sel_hi:[1,0]
	v_pk_add_f32 v[244:245], v[244:245], v[254:255] op_sel_hi:[1,0]
	v_rcp_f32_e32 v198, v198
	v_rcp_f32_e32 v199, v199
	v_rcp_f32_e32 v200, v200
	v_rcp_f32_e32 v201, v201
	v_rcp_f32_e32 v202, v202
	v_rcp_f32_e32 v203, v203
	v_rcp_f32_e32 v244, v244
	v_rcp_f32_e32 v245, v245
	v_pk_fma_f32 v[198:199], v[198:199], v[164:165], v[172:173]
	v_pk_fma_f32 v[200:201], v[200:201], v[166:167], v[174:175]
	v_pk_fma_f32 v[202:203], v[202:203], v[168:169], v[156:157]
	v_pk_fma_f32 v[244:245], v[244:245], v[170:171], v[246:247]
	v_cvt_pk_bf16_f32 v164, v198, v199
	v_cvt_pk_bf16_f32 v165, v200, v201
	v_cvt_pk_bf16_f32 v166, v202, v203
	v_cvt_pk_bf16_f32 v167, v244, v245
	v_add_u32_e32 v253, 0x40000, v255
	global_store_dwordx2 v253, v[164:165], s[36:37]
	global_store_dwordx2 v253, v[166:167], s[36:37] offset:32
	s_waitcnt vmcnt(14)
	v_fmamk_f32 v239, v195, 0x3a800000, v228
	v_rsq_f32_e32 v238, v239
	v_lshlrev_b32_e32 v164, 16, v84
	v_and_b32_e32 v165, 0xffff0000, v84
	v_lshlrev_b32_e32 v166, 16, v85
	v_and_b32_e32 v167, 0xffff0000, v85
	v_lshlrev_b32_e32 v168, 16, v86
	v_and_b32_e32 v169, 0xffff0000, v86
	v_lshlrev_b32_e32 v170, 16, v87
	v_and_b32_e32 v171, 0xffff0000, v87
	v_mul_f32_e32 v238, s45, v238
	v_lshlrev_b32_e32 v172, 16, v80
	v_and_b32_e32 v173, 0xffff0000, v80
	v_lshlrev_b32_e32 v174, 16, v81
	v_and_b32_e32 v175, 0xffff0000, v81
	v_lshlrev_b32_e32 v156, 16, v82
	v_and_b32_e32 v157, 0xffff0000, v82
	v_lshlrev_b32_e32 v246, 16, v83
	v_and_b32_e32 v247, 0xffff0000, v83
	v_pk_fma_f32 v[198:199], v[52:53], v[238:239], v[140:141] op_sel_hi:[1,0,1]
	v_pk_fma_f32 v[200:201], v[54:55], v[238:239], v[142:143] op_sel_hi:[1,0,1]
	v_pk_fma_f32 v[202:203], v[48:49], v[238:239], v[136:137] op_sel_hi:[1,0,1]
	v_pk_fma_f32 v[244:245], v[50:51], v[238:239], v[138:139] op_sel_hi:[1,0,1]
	global_load_dwordx4 v[52:55], v252, s[40:41]
	global_load_dwordx4 v[48:51], v252, s[42:43]
	v_add_u32_e32 v252, 0x2000, v252
	v_exp_f32_e32 v198, v198
	v_exp_f32_e32 v199, v199
	v_exp_f32_e32 v200, v200
	v_exp_f32_e32 v201, v201
	v_exp_f32_e32 v202, v202
	v_exp_f32_e32 v203, v203
	v_exp_f32_e32 v244, v244
	v_exp_f32_e32 v245, v245
	v_pk_add_f32 v[198:199], v[198:199], v[254:255] op_sel_hi:[1,0]
	v_pk_add_f32 v[200:201], v[200:201], v[254:255] op_sel_hi:[1,0]
	v_pk_add_f32 v[202:203], v[202:203], v[254:255] op_sel_hi:[1,0]
	v_pk_add_f32 v[244:245], v[244:245], v[254:255] op_sel_hi:[1,0]
	v_rcp_f32_e32 v198, v198
	v_rcp_f32_e32 v199, v199
	v_rcp_f32_e32 v200, v200
	v_rcp_f32_e32 v201, v201
	v_rcp_f32_e32 v202, v202
	v_rcp_f32_e32 v203, v203
	v_rcp_f32_e32 v244, v244
	v_rcp_f32_e32 v245, v245
	v_pk_fma_f32 v[198:199], v[198:199], v[164:165], v[172:173]
	v_pk_fma_f32 v[200:201], v[200:201], v[166:167], v[174:175]
	v_pk_fma_f32 v[202:203], v[202:203], v[168:169], v[156:157]
	v_pk_fma_f32 v[244:245], v[244:245], v[170:171], v[246:247]
	v_cvt_pk_bf16_f32 v164, v198, v199
	v_cvt_pk_bf16_f32 v165, v200, v201
	v_cvt_pk_bf16_f32 v166, v202, v203
	v_cvt_pk_bf16_f32 v167, v244, v245
	v_add_u32_e32 v253, 0x48000, v255
	global_store_dwordx2 v253, v[164:165], s[36:37]
	global_store_dwordx2 v253, v[166:167], s[36:37] offset:32
	s_waitcnt vmcnt(14)
	v_fmamk_f32 v239, v196, 0x3a800000, v228
	v_rsq_f32_e32 v238, v239
	v_lshlrev_b32_e32 v164, 16, v76
	v_and_b32_e32 v165, 0xffff0000, v76
	v_lshlrev_b32_e32 v166, 16, v77
	v_and_b32_e32 v167, 0xffff0000, v77
	v_lshlrev_b32_e32 v168, 16, v78
	v_and_b32_e32 v169, 0xffff0000, v78
	v_lshlrev_b32_e32 v170, 16, v79
	v_and_b32_e32 v171, 0xffff0000, v79
	v_mul_f32_e32 v238, s45, v238
	v_lshlrev_b32_e32 v172, 16, v72
	v_and_b32_e32 v173, 0xffff0000, v72
	v_lshlrev_b32_e32 v174, 16, v73
	v_and_b32_e32 v175, 0xffff0000, v73
	v_lshlrev_b32_e32 v156, 16, v74
	v_and_b32_e32 v157, 0xffff0000, v74
	v_lshlrev_b32_e32 v246, 16, v75
	v_and_b32_e32 v247, 0xffff0000, v75
	v_pk_fma_f32 v[198:199], v[44:45], v[238:239], v[140:141] op_sel_hi:[1,0,1]
	v_pk_fma_f32 v[200:201], v[46:47], v[238:239], v[142:143] op_sel_hi:[1,0,1]
	v_pk_fma_f32 v[202:203], v[40:41], v[238:239], v[136:137] op_sel_hi:[1,0,1]
	v_pk_fma_f32 v[244:245], v[42:43], v[238:239], v[138:139] op_sel_hi:[1,0,1]
	global_load_dwordx4 v[44:47], v252, s[40:41]
	global_load_dwordx4 v[40:43], v252, s[42:43]
	v_add_u32_e32 v252, 0x2000, v252
	v_exp_f32_e32 v198, v198
	v_exp_f32_e32 v199, v199
	v_exp_f32_e32 v200, v200
	v_exp_f32_e32 v201, v201
	v_exp_f32_e32 v202, v202
	v_exp_f32_e32 v203, v203
	v_exp_f32_e32 v244, v244
	v_exp_f32_e32 v245, v245
	v_pk_add_f32 v[198:199], v[198:199], v[254:255] op_sel_hi:[1,0]
	v_pk_add_f32 v[200:201], v[200:201], v[254:255] op_sel_hi:[1,0]
	v_pk_add_f32 v[202:203], v[202:203], v[254:255] op_sel_hi:[1,0]
	v_pk_add_f32 v[244:245], v[244:245], v[254:255] op_sel_hi:[1,0]
	v_rcp_f32_e32 v198, v198
	v_rcp_f32_e32 v199, v199
	v_rcp_f32_e32 v200, v200
	v_rcp_f32_e32 v201, v201
	v_rcp_f32_e32 v202, v202
	v_rcp_f32_e32 v203, v203
	v_rcp_f32_e32 v244, v244
	v_rcp_f32_e32 v245, v245
	v_pk_fma_f32 v[198:199], v[198:199], v[164:165], v[172:173]
	v_pk_fma_f32 v[200:201], v[200:201], v[166:167], v[174:175]
	v_pk_fma_f32 v[202:203], v[202:203], v[168:169], v[156:157]
	v_pk_fma_f32 v[244:245], v[244:245], v[170:171], v[246:247]
	v_cvt_pk_bf16_f32 v164, v198, v199
	v_cvt_pk_bf16_f32 v165, v200, v201
	v_cvt_pk_bf16_f32 v166, v202, v203
	v_cvt_pk_bf16_f32 v167, v244, v245
	v_add_u32_e32 v253, 0x50000, v255
	global_store_dwordx2 v253, v[164:165], s[36:37]
	global_store_dwordx2 v253, v[166:167], s[36:37] offset:32
	s_waitcnt vmcnt(14)
	v_fmamk_f32 v239, v197, 0x3a800000, v228
	v_rsq_f32_e32 v238, v239
	v_lshlrev_b32_e32 v164, 16, v68
	v_and_b32_e32 v165, 0xffff0000, v68
	v_lshlrev_b32_e32 v166, 16, v69
	v_and_b32_e32 v167, 0xffff0000, v69
	v_lshlrev_b32_e32 v168, 16, v70
	v_and_b32_e32 v169, 0xffff0000, v70
	v_lshlrev_b32_e32 v170, 16, v71
	v_and_b32_e32 v171, 0xffff0000, v71
	v_mul_f32_e32 v238, s45, v238
	v_lshlrev_b32_e32 v172, 16, v64
	v_and_b32_e32 v173, 0xffff0000, v64
	v_lshlrev_b32_e32 v174, 16, v65
	v_and_b32_e32 v175, 0xffff0000, v65
	v_lshlrev_b32_e32 v156, 16, v66
	v_and_b32_e32 v157, 0xffff0000, v66
	v_lshlrev_b32_e32 v246, 16, v67
	v_and_b32_e32 v247, 0xffff0000, v67
	v_pk_fma_f32 v[198:199], v[36:37], v[238:239], v[140:141] op_sel_hi:[1,0,1]
	v_pk_fma_f32 v[200:201], v[38:39], v[238:239], v[142:143] op_sel_hi:[1,0,1]
	v_pk_fma_f32 v[202:203], v[32:33], v[238:239], v[136:137] op_sel_hi:[1,0,1]
	v_pk_fma_f32 v[244:245], v[34:35], v[238:239], v[138:139] op_sel_hi:[1,0,1]
	global_load_dwordx4 v[36:39], v252, s[40:41]
	global_load_dwordx4 v[32:35], v252, s[42:43]
	v_add_u32_e32 v252, 0x2000, v252
	v_exp_f32_e32 v198, v198
	v_exp_f32_e32 v199, v199
	v_exp_f32_e32 v200, v200
	v_exp_f32_e32 v201, v201
	v_exp_f32_e32 v202, v202
	v_exp_f32_e32 v203, v203
	v_exp_f32_e32 v244, v244
	v_exp_f32_e32 v245, v245
	v_pk_add_f32 v[198:199], v[198:199], v[254:255] op_sel_hi:[1,0]
	v_pk_add_f32 v[200:201], v[200:201], v[254:255] op_sel_hi:[1,0]
	v_pk_add_f32 v[202:203], v[202:203], v[254:255] op_sel_hi:[1,0]
	v_pk_add_f32 v[244:245], v[244:245], v[254:255] op_sel_hi:[1,0]
	v_rcp_f32_e32 v198, v198
	v_rcp_f32_e32 v199, v199
	v_rcp_f32_e32 v200, v200
	v_rcp_f32_e32 v201, v201
	v_rcp_f32_e32 v202, v202
	v_rcp_f32_e32 v203, v203
	v_rcp_f32_e32 v244, v244
	v_rcp_f32_e32 v245, v245
	v_pk_fma_f32 v[198:199], v[198:199], v[164:165], v[172:173]
	v_pk_fma_f32 v[200:201], v[200:201], v[166:167], v[174:175]
	v_pk_fma_f32 v[202:203], v[202:203], v[168:169], v[156:157]
	v_pk_fma_f32 v[244:245], v[244:245], v[170:171], v[246:247]
	v_cvt_pk_bf16_f32 v164, v198, v199
	v_cvt_pk_bf16_f32 v165, v200, v201
	v_cvt_pk_bf16_f32 v166, v202, v203
	v_cvt_pk_bf16_f32 v167, v244, v245
	v_add_u32_e32 v253, 0x58000, v255
	global_store_dwordx2 v253, v[164:165], s[36:37]
	global_store_dwordx2 v253, v[166:167], s[36:37] offset:32
	s_waitcnt vmcnt(14)
	v_fmamk_f32 v239, v194, 0x3a800000, v228
	v_rsq_f32_e32 v238, v239
	v_lshlrev_b32_e32 v164, 16, v60
	v_and_b32_e32 v165, 0xffff0000, v60
	v_lshlrev_b32_e32 v166, 16, v61
	v_and_b32_e32 v167, 0xffff0000, v61
	v_lshlrev_b32_e32 v168, 16, v62
	v_and_b32_e32 v169, 0xffff0000, v62
	v_lshlrev_b32_e32 v170, 16, v63
	v_and_b32_e32 v171, 0xffff0000, v63
	v_mul_f32_e32 v238, s45, v238
	v_lshlrev_b32_e32 v172, 16, v56
	v_and_b32_e32 v173, 0xffff0000, v56
	v_lshlrev_b32_e32 v174, 16, v57
	v_and_b32_e32 v175, 0xffff0000, v57
	v_lshlrev_b32_e32 v156, 16, v58
	v_and_b32_e32 v157, 0xffff0000, v58
	v_lshlrev_b32_e32 v246, 16, v59
	v_and_b32_e32 v247, 0xffff0000, v59
	v_pk_fma_f32 v[198:199], v[28:29], v[238:239], v[132:133] op_sel_hi:[1,0,1]
	v_pk_fma_f32 v[200:201], v[30:31], v[238:239], v[134:135] op_sel_hi:[1,0,1]
	v_pk_fma_f32 v[202:203], v[24:25], v[238:239], v[128:129] op_sel_hi:[1,0,1]
	v_pk_fma_f32 v[244:245], v[26:27], v[238:239], v[130:131] op_sel_hi:[1,0,1]
	v_exp_f32_e32 v198, v198
	v_exp_f32_e32 v199, v199
	v_exp_f32_e32 v200, v200
	v_exp_f32_e32 v201, v201
	v_exp_f32_e32 v202, v202
	v_exp_f32_e32 v203, v203
	v_exp_f32_e32 v244, v244
	v_exp_f32_e32 v245, v245
	v_pk_add_f32 v[198:199], v[198:199], v[254:255] op_sel_hi:[1,0]
	v_pk_add_f32 v[200:201], v[200:201], v[254:255] op_sel_hi:[1,0]
	v_pk_add_f32 v[202:203], v[202:203], v[254:255] op_sel_hi:[1,0]
	v_pk_add_f32 v[244:245], v[244:245], v[254:255] op_sel_hi:[1,0]
	v_rcp_f32_e32 v198, v198
	v_rcp_f32_e32 v199, v199
	v_rcp_f32_e32 v200, v200
	v_rcp_f32_e32 v201, v201
	v_rcp_f32_e32 v202, v202
	v_rcp_f32_e32 v203, v203
	v_rcp_f32_e32 v244, v244
	v_rcp_f32_e32 v245, v245
	v_pk_fma_f32 v[198:199], v[198:199], v[164:165], v[172:173]
	v_pk_fma_f32 v[200:201], v[200:201], v[166:167], v[174:175]
	v_pk_fma_f32 v[202:203], v[202:203], v[168:169], v[156:157]
	v_pk_fma_f32 v[244:245], v[244:245], v[170:171], v[246:247]
	v_cvt_pk_bf16_f32 v164, v198, v199
	v_cvt_pk_bf16_f32 v165, v200, v201
	v_cvt_pk_bf16_f32 v166, v202, v203
	v_cvt_pk_bf16_f32 v167, v244, v245
	v_add_u32_e32 v253, 0x40100, v255
	global_store_dwordx2 v253, v[164:165], s[36:37]
	global_store_dwordx2 v253, v[166:167], s[36:37] offset:32
	s_waitcnt vmcnt(12)
	v_fmamk_f32 v239, v195, 0x3a800000, v228
	v_rsq_f32_e32 v238, v239
	v_lshlrev_b32_e32 v164, 16, v52
	v_and_b32_e32 v165, 0xffff0000, v52
	v_lshlrev_b32_e32 v166, 16, v53
	v_and_b32_e32 v167, 0xffff0000, v53
	v_lshlrev_b32_e32 v168, 16, v54
	v_and_b32_e32 v169, 0xffff0000, v54
	v_lshlrev_b32_e32 v170, 16, v55
	v_and_b32_e32 v171, 0xffff0000, v55
	v_mul_f32_e32 v238, s45, v238
	v_lshlrev_b32_e32 v172, 16, v48
	v_and_b32_e32 v173, 0xffff0000, v48
	v_lshlrev_b32_e32 v174, 16, v49
	v_and_b32_e32 v175, 0xffff0000, v49
	v_lshlrev_b32_e32 v156, 16, v50
	v_and_b32_e32 v157, 0xffff0000, v50
	v_lshlrev_b32_e32 v246, 16, v51
	v_and_b32_e32 v247, 0xffff0000, v51
	v_pk_fma_f32 v[198:199], v[20:21], v[238:239], v[132:133] op_sel_hi:[1,0,1]
	v_pk_fma_f32 v[200:201], v[22:23], v[238:239], v[134:135] op_sel_hi:[1,0,1]
	v_pk_fma_f32 v[202:203], v[16:17], v[238:239], v[128:129] op_sel_hi:[1,0,1]
	v_pk_fma_f32 v[244:245], v[18:19], v[238:239], v[130:131] op_sel_hi:[1,0,1]
	v_exp_f32_e32 v198, v198
	v_exp_f32_e32 v199, v199
	v_exp_f32_e32 v200, v200
	v_exp_f32_e32 v201, v201
	v_exp_f32_e32 v202, v202
	v_exp_f32_e32 v203, v203
	v_exp_f32_e32 v244, v244
	v_exp_f32_e32 v245, v245
	v_pk_add_f32 v[198:199], v[198:199], v[254:255] op_sel_hi:[1,0]
	v_pk_add_f32 v[200:201], v[200:201], v[254:255] op_sel_hi:[1,0]
	v_pk_add_f32 v[202:203], v[202:203], v[254:255] op_sel_hi:[1,0]
	v_pk_add_f32 v[244:245], v[244:245], v[254:255] op_sel_hi:[1,0]
	v_rcp_f32_e32 v198, v198
	v_rcp_f32_e32 v199, v199
	v_rcp_f32_e32 v200, v200
	v_rcp_f32_e32 v201, v201
	v_rcp_f32_e32 v202, v202
	v_rcp_f32_e32 v203, v203
	v_rcp_f32_e32 v244, v244
	v_rcp_f32_e32 v245, v245
	v_pk_fma_f32 v[198:199], v[198:199], v[164:165], v[172:173]
	v_pk_fma_f32 v[200:201], v[200:201], v[166:167], v[174:175]
	v_pk_fma_f32 v[202:203], v[202:203], v[168:169], v[156:157]
	v_pk_fma_f32 v[244:245], v[244:245], v[170:171], v[246:247]
	v_cvt_pk_bf16_f32 v164, v198, v199
	v_cvt_pk_bf16_f32 v165, v200, v201
	v_cvt_pk_bf16_f32 v166, v202, v203
	v_cvt_pk_bf16_f32 v167, v244, v245
	v_add_u32_e32 v253, 0x48100, v255
	global_store_dwordx2 v253, v[164:165], s[36:37]
	global_store_dwordx2 v253, v[166:167], s[36:37] offset:32
	s_waitcnt vmcnt(10)
	v_fmamk_f32 v239, v196, 0x3a800000, v228
	v_rsq_f32_e32 v238, v239
	v_lshlrev_b32_e32 v164, 16, v44
	v_and_b32_e32 v165, 0xffff0000, v44
	v_lshlrev_b32_e32 v166, 16, v45
	v_and_b32_e32 v167, 0xffff0000, v45
	v_lshlrev_b32_e32 v168, 16, v46
	v_and_b32_e32 v169, 0xffff0000, v46
	v_lshlrev_b32_e32 v170, 16, v47
	v_and_b32_e32 v171, 0xffff0000, v47
	v_mul_f32_e32 v238, s45, v238
	v_lshlrev_b32_e32 v172, 16, v40
	v_and_b32_e32 v173, 0xffff0000, v40
	v_lshlrev_b32_e32 v174, 16, v41
	v_and_b32_e32 v175, 0xffff0000, v41
	v_lshlrev_b32_e32 v156, 16, v42
	v_and_b32_e32 v157, 0xffff0000, v42
	v_lshlrev_b32_e32 v246, 16, v43
	v_and_b32_e32 v247, 0xffff0000, v43
	v_pk_fma_f32 v[198:199], v[12:13], v[238:239], v[132:133] op_sel_hi:[1,0,1]
	v_pk_fma_f32 v[200:201], v[14:15], v[238:239], v[134:135] op_sel_hi:[1,0,1]
	v_pk_fma_f32 v[202:203], v[8:9], v[238:239], v[128:129] op_sel_hi:[1,0,1]
	v_pk_fma_f32 v[244:245], v[10:11], v[238:239], v[130:131] op_sel_hi:[1,0,1]
	v_exp_f32_e32 v198, v198
	v_exp_f32_e32 v199, v199
	v_exp_f32_e32 v200, v200
	v_exp_f32_e32 v201, v201
	v_exp_f32_e32 v202, v202
	v_exp_f32_e32 v203, v203
	v_exp_f32_e32 v244, v244
	v_exp_f32_e32 v245, v245
	v_pk_add_f32 v[198:199], v[198:199], v[254:255] op_sel_hi:[1,0]
	v_pk_add_f32 v[200:201], v[200:201], v[254:255] op_sel_hi:[1,0]
	v_pk_add_f32 v[202:203], v[202:203], v[254:255] op_sel_hi:[1,0]
	v_pk_add_f32 v[244:245], v[244:245], v[254:255] op_sel_hi:[1,0]
	v_rcp_f32_e32 v198, v198
	v_rcp_f32_e32 v199, v199
	v_rcp_f32_e32 v200, v200
	v_rcp_f32_e32 v201, v201
	v_rcp_f32_e32 v202, v202
	v_rcp_f32_e32 v203, v203
	v_rcp_f32_e32 v244, v244
	v_rcp_f32_e32 v245, v245
	v_pk_fma_f32 v[198:199], v[198:199], v[164:165], v[172:173]
	v_pk_fma_f32 v[200:201], v[200:201], v[166:167], v[174:175]
	v_pk_fma_f32 v[202:203], v[202:203], v[168:169], v[156:157]
	v_pk_fma_f32 v[244:245], v[244:245], v[170:171], v[246:247]
	v_cvt_pk_bf16_f32 v164, v198, v199
	v_cvt_pk_bf16_f32 v165, v200, v201
	v_cvt_pk_bf16_f32 v166, v202, v203
	v_cvt_pk_bf16_f32 v167, v244, v245
	v_add_u32_e32 v253, 0x50100, v255
	global_store_dwordx2 v253, v[164:165], s[36:37]
	global_store_dwordx2 v253, v[166:167], s[36:37] offset:32
	s_waitcnt vmcnt(8)
	v_fmamk_f32 v239, v197, 0x3a800000, v228
	v_rsq_f32_e32 v238, v239
	v_lshlrev_b32_e32 v164, 16, v36
	v_and_b32_e32 v165, 0xffff0000, v36
	v_lshlrev_b32_e32 v166, 16, v37
	v_and_b32_e32 v167, 0xffff0000, v37
	v_lshlrev_b32_e32 v168, 16, v38
	v_and_b32_e32 v169, 0xffff0000, v38
	v_lshlrev_b32_e32 v170, 16, v39
	v_and_b32_e32 v171, 0xffff0000, v39
	v_mul_f32_e32 v238, s45, v238
	v_lshlrev_b32_e32 v172, 16, v32
	v_and_b32_e32 v173, 0xffff0000, v32
	v_lshlrev_b32_e32 v174, 16, v33
	v_and_b32_e32 v175, 0xffff0000, v33
	v_lshlrev_b32_e32 v156, 16, v34
	v_and_b32_e32 v157, 0xffff0000, v34
	v_lshlrev_b32_e32 v246, 16, v35
	v_and_b32_e32 v247, 0xffff0000, v35
	v_pk_fma_f32 v[198:199], v[4:5], v[238:239], v[132:133] op_sel_hi:[1,0,1]
	v_pk_fma_f32 v[200:201], v[6:7], v[238:239], v[134:135] op_sel_hi:[1,0,1]
	v_pk_fma_f32 v[202:203], v[0:1], v[238:239], v[128:129] op_sel_hi:[1,0,1]
	v_pk_fma_f32 v[244:245], v[2:3], v[238:239], v[130:131] op_sel_hi:[1,0,1]
	v_exp_f32_e32 v198, v198
	v_exp_f32_e32 v199, v199
	v_exp_f32_e32 v200, v200
	v_exp_f32_e32 v201, v201
	v_exp_f32_e32 v202, v202
	v_exp_f32_e32 v203, v203
	v_exp_f32_e32 v244, v244
	v_exp_f32_e32 v245, v245
	v_pk_add_f32 v[198:199], v[198:199], v[254:255] op_sel_hi:[1,0]
	v_pk_add_f32 v[200:201], v[200:201], v[254:255] op_sel_hi:[1,0]
	v_pk_add_f32 v[202:203], v[202:203], v[254:255] op_sel_hi:[1,0]
	v_pk_add_f32 v[244:245], v[244:245], v[254:255] op_sel_hi:[1,0]
	v_rcp_f32_e32 v198, v198
	v_rcp_f32_e32 v199, v199
	v_rcp_f32_e32 v200, v200
	v_rcp_f32_e32 v201, v201
	v_rcp_f32_e32 v202, v202
	v_rcp_f32_e32 v203, v203
	v_rcp_f32_e32 v244, v244
	v_rcp_f32_e32 v245, v245
	v_pk_fma_f32 v[198:199], v[198:199], v[164:165], v[172:173]
	v_pk_fma_f32 v[200:201], v[200:201], v[166:167], v[174:175]
	v_pk_fma_f32 v[202:203], v[202:203], v[168:169], v[156:157]
	v_pk_fma_f32 v[244:245], v[244:245], v[170:171], v[246:247]
	v_cvt_pk_bf16_f32 v164, v198, v199
	v_cvt_pk_bf16_f32 v165, v200, v201
	v_cvt_pk_bf16_f32 v166, v202, v203
	v_cvt_pk_bf16_f32 v167, v244, v245
	v_add_u32_e32 v253, 0x58100, v255
	global_store_dwordx2 v253, v[164:165], s[36:37]
	global_store_dwordx2 v253, v[166:167], s[36:37] offset:32
	s_branch .LBB0_1002
